# GEMM phases: per-segment s_setprio toggling in the K-loops replaced by one static priority raise for waves 4-7 per tile, reset at phase end (lever: static priority for the younger half)
# baseline (speedup 1.0000x reference)
; template <class Epi, class Sched, bool ALIGN_EPI = false, bool SP2 = false, bool AROWS128 = false>
; __device__ __forceinline__ void gemm_phase(PG8_LAS unsigned char* lds, const Gemm g, const Sched& S, const Epi& E) {
;     ...
;     for (;;) {
;         const bool has_next = S.next(ui + 1, nxt);
;         const char* nA = has_next ? (const char*)g.A + (size_t)nxt.pm * tstep : cA; const char* nB = has_next ? (const char*)g.Bt + (size_t)nxt.pn * tstep : cB;
.LBB0_116:
	v_readfirstlane_b32 vcc_lo, v210
	s_nop 0
	s_cmpk_lt_u32 vcc_lo, 0x100
	s_cbranch_scc1 .Lgprio_0
	s_setprio 1

; #define PG8_STAGE(bufoff, gbase, voff) do { _Pragma("unroll") for (int _i = 0; _i < 2; ++_i) \
;         __builtin_amdgcn_global_load_lds((const unsigned*)((const char*)(gbase) + (voff)[_i]), (PG8_LAS unsigned*)(lds + (bufoff) + ldsw + _i * 8192), 16, 0, 0); } while (0)
; #define PG8_LDA(dst, b, h) do { _Pragma("unroll") for (int m = 0; m < 4; ++m) _Pragma("unroll") for (int k = 0; k < 2; ++k) dst[m][k] = *(const PG8_LAS bf16x8*)(lds + PG8_SA(b, h) + aoff + m * 2048 + k * 1024); } while (0)
; #define PG8_LDB(dst, b, h) do { _Pragma("unroll") for (int n = 0; n < 2; ++n) _Pragma("unroll") for (int k = 0; k < 2; ++k) dst[n][k] = *(const PG8_LAS bf16x8*)(lds + PG8_SB(b, h) + boff + n * 2048 + k * 1024); } while (0)
; #define PG8_MMA(ai, bj, At, Bt) do { __builtin_amdgcn_s_setprio(1); _Pragma("unroll") for (int m = 0; m < 4; ++m) _Pragma("unroll") for (int n = 0; n < 2; ++n) _Pragma("unroll") for (int k = 0; k < 2; ++k) \
;         acc[ai][bj][m][n] = __builtin_amdgcn_mfma_f32_16x16x32_bf16(Bt[n][k], At[m][k], acc[ai][bj][m][n], 0, 0, 0); __builtin_amdgcn_s_setprio(0); } while (0)
; #define PG8_WAIT_V(n) asm volatile("s_waitcnt vmcnt(" #n ")" ::: "memory")
; #define PG8_WAIT_L(n) asm volatile("s_waitcnt lgkmcnt(" #n ")" ::: "memory")
; template <class Epi, class Sched, bool ALIGN_EPI = false, bool SP2 = false, bool AROWS128 = false>
; __device__ __forceinline__ void gemm_phase(PG8_LAS unsigned char* lds, const Gemm g, const Sched& S, const Epi& E) {
;     ...
;             const bool last = (t == nt - 2);
;             const char* a1 = cA + (size_t)(t + 1) * kstep;
;             const char* a2 = last ? nA : cA + (size_t)(t + 2) * kstep; const char* b2 = last ? nB : cB + (size_t)(t + 2) * kstep;
;             const char* a3 = a2 + kstep; const char* b3 = b2 + kstep;
;             if (last && has_next) S.a_ready(nxt);
;             if constexpr (SP2) {
;             PG8_LDB(B0, 0, 0); PG8_LDB(B1, 0, 1); PG8_SCHED; PG8_LDA(At, 0, 0); PG8_STAGE(PG8_SA(1, 1), a1 + hstepA, voffA);
;             PG8_WAIT_V(8); PG8_WAIT_L(0); PG8_BAR; PG8_MMA(0, 0, At, B0); PG8_MMA(0, 1, At, B1); PG8_BAR; PG8_SCHED;
;             PG8_LDA(At, 0, 1); PG8_STAGE(PG8_SB(0, 0), b2, voffB); PG8_STAGE(PG8_SB(0, 1), b2 + hstep, voffB); PG8_STAGE(PG8_SA(0, 0), a2, voffA);
;             PG8_WAIT_V(8); PG8_WAIT_L(0); PG8_BAR; PG8_MMA(1, 0, At, B0); PG8_MMA(1, 1, At, B1); PG8_BAR; PG8_SCHED;
.LBB0_119:
	ds_read_b128 v[148:151], v155
	ds_read_b128 v[160:163], v155 offset:1024
	ds_read_b128 v[164:167], v155 offset:2048
	ds_read_b128 v[168:171], v155 offset:3072
	ds_read_b128 v[172:175], v156
	ds_read_b128 v[176:179], v156 offset:1024
	ds_read_b128 v[180:183], v156 offset:2048
	ds_read_b128 v[184:187], v156 offset:3072
	s_add_u32 s50, s48, 0xfffc0080
	s_addc_u32 s51, s49, -1
	s_cmp_eq_u32 s93, 12
	s_cselect_b32 s59, s25, s51
	s_cselect_b32 s58, s76, s50
	s_cselect_b32 s51, s15, s92
	s_cselect_b32 s50, s77, s91
	v_lshl_add_u64 v[208:209], s[48:49], 0, v[138:139]
	s_add_i32 m0, s31, 0xc000
	ds_read_b128 v[188:191], v157
	ds_read_b128 v[192:195], v157 offset:1024
	ds_read_b128 v[196:199], v157 offset:2048
	ds_read_b128 v[200:203], v157 offset:3072
	ds_read_b128 v[204:207], v157 offset:4096
	ds_read_b128 v[212:215], v157 offset:5120
	ds_read_b128 v[216:219], v157 offset:6144
	ds_read_b128 v[220:223], v157 offset:7168
	global_load_lds_dwordx4 v[208:209], off
	v_lshl_add_u64 v[208:209], s[48:49], 0, v[140:141]
	s_add_i32 m0, s31, 0xe000
	s_nop 0
	global_load_lds_dwordx4 v[208:209], off
	s_waitcnt vmcnt(8)
	s_waitcnt lgkmcnt(0)
	s_barrier
	s_waitcnt lgkmcnt(0)
	v_mfma_f32_16x16x32_bf16 v[124:127], v[148:151], v[188:191], v[124:127]
	v_mfma_f32_16x16x32_bf16 v[120:123], v[164:167], v[188:191], v[120:123]
	v_mfma_f32_16x16x32_bf16 v[112:115], v[148:151], v[196:199], v[112:115]
	v_mfma_f32_16x16x32_bf16 v[104:107], v[164:167], v[196:199], v[104:107]
	v_mfma_f32_16x16x32_bf16 v[96:99], v[148:151], v[204:207], v[96:99]
	v_mfma_f32_16x16x32_bf16 v[88:91], v[164:167], v[204:207], v[88:91]
	v_mfma_f32_16x16x32_bf16 v[80:83], v[148:151], v[216:219], v[80:83]
	v_mfma_f32_16x16x32_bf16 v[72:75], v[164:167], v[216:219], v[72:75]
	v_mfma_f32_16x16x32_bf16 v[124:127], v[160:163], v[192:195], v[124:127]
	v_mfma_f32_16x16x32_bf16 v[120:123], v[168:171], v[192:195], v[120:123]
	v_mfma_f32_16x16x32_bf16 v[112:115], v[160:163], v[200:203], v[112:115]
	v_mfma_f32_16x16x32_bf16 v[104:107], v[168:171], v[200:203], v[104:107]
	v_mfma_f32_16x16x32_bf16 v[96:99], v[160:163], v[212:215], v[96:99]
	v_mfma_f32_16x16x32_bf16 v[88:91], v[168:171], v[212:215], v[88:91]
	v_mfma_f32_16x16x32_bf16 v[80:83], v[160:163], v[220:223], v[80:83]
	v_mfma_f32_16x16x32_bf16 v[72:75], v[168:171], v[220:223], v[72:75]
	v_mfma_f32_16x16x32_bf16 v[116:119], v[172:175], v[188:191], v[116:119]
	v_mfma_f32_16x16x32_bf16 v[108:111], v[180:183], v[188:191], v[108:111]
	v_mfma_f32_16x16x32_bf16 v[100:103], v[172:175], v[196:199], v[100:103]
	v_mfma_f32_16x16x32_bf16 v[92:95], v[180:183], v[196:199], v[92:95]
	v_mfma_f32_16x16x32_bf16 v[84:87], v[172:175], v[204:207], v[84:87]
	v_mfma_f32_16x16x32_bf16 v[76:79], v[180:183], v[204:207], v[76:79]
	v_mfma_f32_16x16x32_bf16 v[68:71], v[172:175], v[216:219], v[68:71]
	v_mfma_f32_16x16x32_bf16 v[64:67], v[180:183], v[216:219], v[64:67]
	v_mfma_f32_16x16x32_bf16 v[116:119], v[176:179], v[192:195], v[116:119]
	v_mfma_f32_16x16x32_bf16 v[108:111], v[184:187], v[192:195], v[108:111]
	v_mfma_f32_16x16x32_bf16 v[100:103], v[176:179], v[200:203], v[100:103]
	v_mfma_f32_16x16x32_bf16 v[92:95], v[184:187], v[200:203], v[92:95]
	v_mfma_f32_16x16x32_bf16 v[84:87], v[176:179], v[212:215], v[84:87]
	v_mfma_f32_16x16x32_bf16 v[76:79], v[184:187], v[212:215], v[76:79]
	v_mfma_f32_16x16x32_bf16 v[68:71], v[176:179], v[220:223], v[68:71]
	v_mfma_f32_16x16x32_bf16 v[64:67], v[184:187], v[220:223], v[64:67]
	s_barrier
	s_add_i32 s94, s87, s3
	v_lshl_add_u64 v[208:209], s[50:51], 0, v[134:135]
	s_mov_b32 m0, s94
	ds_read_b128 v[188:191], v157 offset:16384
	ds_read_b128 v[192:195], v157 offset:17408
	ds_read_b128 v[196:199], v157 offset:18432
	ds_read_b128 v[200:203], v157 offset:19456
	ds_read_b128 v[204:207], v157 offset:20480
	ds_read_b128 v[212:215], v157 offset:21504
	ds_read_b128 v[216:219], v157 offset:22528
	ds_read_b128 v[220:223], v157 offset:23552
	global_load_lds_dwordx4 v[208:209], off
	s_add_i32 m0, s94, 0x2000
	s_add_u32 s94, s50, 0x40000
	v_lshl_add_u64 v[224:225], s[50:51], 0, v[130:131]
	s_addc_u32 s95, s51, 0
	s_add_i32 s96, s88, s3
	global_load_lds_dwordx4 v[224:225], off
	v_lshl_add_u64 v[226:227], s[94:95], 0, v[134:135]
	s_mov_b32 m0, s96
	v_lshl_add_u64 v[228:229], s[58:59], 0, v[132:133]
	global_load_lds_dwordx4 v[226:227], off
	v_lshl_add_u64 v[226:227], s[94:95], 0, v[130:131]
	s_add_i32 m0, s96, 0x2000
	s_nop 0
	global_load_lds_dwordx4 v[226:227], off
	v_lshl_add_u64 v[226:227], s[58:59], 0, v[136:137]
	s_mov_b32 m0, s31
	s_nop 0
	global_load_lds_dwordx4 v[226:227], off
	s_mov_b32 m0, s64
	s_nop 0
	global_load_lds_dwordx4 v[228:229], off
	s_waitcnt vmcnt(8)
	s_waitcnt lgkmcnt(0)
	s_barrier
; #define PG8_STAGE(bufoff, gbase, voff) do { _Pragma("unroll") for (int _i = 0; _i < 2; ++_i) \
;         __builtin_amdgcn_global_load_lds((const unsigned*)((const char*)(gbase) + (voff)[_i]), (PG8_LAS unsigned*)(lds + (bufoff) + ldsw + _i * 8192), 16, 0, 0); } while (0)
; #define PG8_LDA(dst, b, h) do { _Pragma("unroll") for (int m = 0; m < 4; ++m) _Pragma("unroll") for (int k = 0; k < 2; ++k) dst[m][k] = *(const PG8_LAS bf16x8*)(lds + PG8_SA(b, h) + aoff + m * 2048 + k * 1024); } while (0)
; #define PG8_LDB(dst, b, h) do { _Pragma("unroll") for (int n = 0; n < 2; ++n) _Pragma("unroll") for (int k = 0; k < 2; ++k) dst[n][k] = *(const PG8_LAS bf16x8*)(lds + PG8_SB(b, h) + boff + n * 2048 + k * 1024); } while (0)
; #define PG8_MMA(ai, bj, At, Bt) do { __builtin_amdgcn_s_setprio(1); _Pragma("unroll") for (int m = 0; m < 4; ++m) _Pragma("unroll") for (int n = 0; n < 2; ++n) _Pragma("unroll") for (int k = 0; k < 2; ++k) \
;         acc[ai][bj][m][n] = __builtin_amdgcn_mfma_f32_16x16x32_bf16(Bt[n][k], At[m][k], acc[ai][bj][m][n], 0, 0, 0); __builtin_amdgcn_s_setprio(0); } while (0)
; #define PG8_WAIT_V(n) asm volatile("s_waitcnt vmcnt(" #n ")" ::: "memory")
; #define PG8_WAIT_L(n) asm volatile("s_waitcnt lgkmcnt(" #n ")" ::: "memory")
; #define PG8_BAR __builtin_amdgcn_s_barrier()
; #define PG8_SCHED __builtin_amdgcn_sched_barrier(0)
; template <class Epi, class Sched, bool ALIGN_EPI = false, bool SP2 = false, bool AROWS128 = false>
; __device__ __forceinline__ void gemm_phase(PG8_LAS unsigned char* lds, const Gemm g, const Sched& S, const Epi& E) {
;     ...
;             PG8_WAIT_V(8); PG8_WAIT_L(0); PG8_BAR; PG8_MMA(1, 0, At, B0); PG8_MMA(1, 1, At, B1); PG8_BAR; PG8_SCHED;
;             PG8_LDB(B0, 1, 0); PG8_LDB(B1, 1, 1); PG8_SCHED; PG8_LDA(At, 1, 0); PG8_STAGE(PG8_SA(0, 1), a2 + hstepA, voffA);
;             PG8_WAIT_V(8); PG8_WAIT_L(0); PG8_BAR; PG8_MMA(0, 0, At, B0); PG8_MMA(0, 1, At, B1); PG8_BAR; PG8_SCHED;
	s_waitcnt lgkmcnt(0)
	v_mfma_f32_16x16x32_bf16 v[60:63], v[148:151], v[188:191], v[60:63]
	v_mfma_f32_16x16x32_bf16 v[56:59], v[164:167], v[188:191], v[56:59]
	v_mfma_f32_16x16x32_bf16 v[48:51], v[148:151], v[196:199], v[48:51]
	v_mfma_f32_16x16x32_bf16 v[40:43], v[164:167], v[196:199], v[40:43]
	v_mfma_f32_16x16x32_bf16 v[32:35], v[148:151], v[204:207], v[32:35]
	v_mfma_f32_16x16x32_bf16 v[24:27], v[164:167], v[204:207], v[24:27]
	v_mfma_f32_16x16x32_bf16 v[16:19], v[148:151], v[216:219], v[16:19]
	v_mfma_f32_16x16x32_bf16 v[8:11], v[164:167], v[216:219], v[8:11]
	v_mfma_f32_16x16x32_bf16 v[60:63], v[160:163], v[192:195], v[60:63]
	v_mfma_f32_16x16x32_bf16 v[56:59], v[168:171], v[192:195], v[56:59]
	v_mfma_f32_16x16x32_bf16 v[48:51], v[160:163], v[200:203], v[48:51]
	v_mfma_f32_16x16x32_bf16 v[40:43], v[168:171], v[200:203], v[40:43]
	v_mfma_f32_16x16x32_bf16 v[32:35], v[160:163], v[212:215], v[32:35]
	v_mfma_f32_16x16x32_bf16 v[24:27], v[168:171], v[212:215], v[24:27]
	v_mfma_f32_16x16x32_bf16 v[16:19], v[160:163], v[220:223], v[16:19]
	v_mfma_f32_16x16x32_bf16 v[8:11], v[168:171], v[220:223], v[8:11]
	v_mfma_f32_16x16x32_bf16 v[52:55], v[172:175], v[188:191], v[52:55]
	v_mfma_f32_16x16x32_bf16 v[44:47], v[180:183], v[188:191], v[44:47]
	v_mfma_f32_16x16x32_bf16 v[36:39], v[172:175], v[196:199], v[36:39]
	v_mfma_f32_16x16x32_bf16 v[28:31], v[180:183], v[196:199], v[28:31]
	v_mfma_f32_16x16x32_bf16 v[20:23], v[172:175], v[204:207], v[20:23]
	v_mfma_f32_16x16x32_bf16 v[12:15], v[180:183], v[204:207], v[12:15]
	v_mfma_f32_16x16x32_bf16 v[4:7], v[172:175], v[216:219], v[4:7]
	v_mfma_f32_16x16x32_bf16 v[0:3], v[180:183], v[216:219], v[0:3]
	v_mfma_f32_16x16x32_bf16 v[52:55], v[176:179], v[192:195], v[52:55]
	v_mfma_f32_16x16x32_bf16 v[44:47], v[184:187], v[192:195], v[44:47]
	v_mfma_f32_16x16x32_bf16 v[36:39], v[176:179], v[200:203], v[36:39]
	v_mfma_f32_16x16x32_bf16 v[28:31], v[184:187], v[200:203], v[28:31]
	v_mfma_f32_16x16x32_bf16 v[20:23], v[176:179], v[212:215], v[20:23]
	v_mfma_f32_16x16x32_bf16 v[12:15], v[184:187], v[212:215], v[12:15]
	v_mfma_f32_16x16x32_bf16 v[4:7], v[176:179], v[220:223], v[4:7]
	v_mfma_f32_16x16x32_bf16 v[0:3], v[184:187], v[220:223], v[0:3]
	s_barrier
	s_add_i32 s94, 0, 0x18000
	v_add_u32_e32 v146, s94, v153
	s_add_i32 s95, 0, 0x1c000
	ds_read_b128 v[148:151], v146
	ds_read_b128 v[160:163], v146 offset:1024
	ds_read_b128 v[164:167], v146 offset:2048
	ds_read_b128 v[168:171], v146 offset:3072
	v_add_u32_e32 v146, s95, v153
	ds_read_b128 v[172:175], v146
	ds_read_b128 v[176:179], v146 offset:1024
	ds_read_b128 v[180:183], v146 offset:2048
	ds_read_b128 v[184:187], v146 offset:3072
	s_add_u32 s58, s58, 0x40000
	s_addc_u32 s59, s59, 0
	s_mov_b32 m0, s65
	v_lshl_add_u64 v[230:231], s[58:59], 0, v[136:137]
	ds_read_b128 v[188:191], v157 offset:32768
	ds_read_b128 v[192:195], v157 offset:33792
	ds_read_b128 v[196:199], v157 offset:34816
	ds_read_b128 v[200:203], v157 offset:35840
	ds_read_b128 v[204:207], v157 offset:36864
	ds_read_b128 v[212:215], v157 offset:37888
	ds_read_b128 v[216:219], v157 offset:38912
	ds_read_b128 v[220:223], v157 offset:39936
	global_load_lds_dwordx4 v[230:231], off
	v_lshl_add_u64 v[230:231], s[58:59], 0, v[132:133]
	s_mov_b32 m0, s72
	s_nop 0
	global_load_lds_dwordx4 v[230:231], off
	s_waitcnt vmcnt(8)
	s_waitcnt lgkmcnt(0)
	s_barrier
	s_waitcnt lgkmcnt(0)
	v_mfma_f32_16x16x32_bf16 v[124:127], v[148:151], v[188:191], v[124:127]
	v_mfma_f32_16x16x32_bf16 v[120:123], v[164:167], v[188:191], v[120:123]
	v_mfma_f32_16x16x32_bf16 v[112:115], v[148:151], v[196:199], v[112:115]
	v_mfma_f32_16x16x32_bf16 v[104:107], v[164:167], v[196:199], v[104:107]
	v_mfma_f32_16x16x32_bf16 v[96:99], v[148:151], v[204:207], v[96:99]
	v_mfma_f32_16x16x32_bf16 v[88:91], v[164:167], v[204:207], v[88:91]
	v_mfma_f32_16x16x32_bf16 v[80:83], v[148:151], v[216:219], v[80:83]
	v_mfma_f32_16x16x32_bf16 v[72:75], v[164:167], v[216:219], v[72:75]
	v_mfma_f32_16x16x32_bf16 v[124:127], v[160:163], v[192:195], v[124:127]
	v_mfma_f32_16x16x32_bf16 v[120:123], v[168:171], v[192:195], v[120:123]
	v_mfma_f32_16x16x32_bf16 v[112:115], v[160:163], v[200:203], v[112:115]
	v_mfma_f32_16x16x32_bf16 v[104:107], v[168:171], v[200:203], v[104:107]
	v_mfma_f32_16x16x32_bf16 v[96:99], v[160:163], v[212:215], v[96:99]
	v_mfma_f32_16x16x32_bf16 v[88:91], v[168:171], v[212:215], v[88:91]
	v_mfma_f32_16x16x32_bf16 v[80:83], v[160:163], v[220:223], v[80:83]
	v_mfma_f32_16x16x32_bf16 v[72:75], v[168:171], v[220:223], v[72:75]
	v_mfma_f32_16x16x32_bf16 v[116:119], v[172:175], v[188:191], v[116:119]
	v_mfma_f32_16x16x32_bf16 v[108:111], v[180:183], v[188:191], v[108:111]
	v_mfma_f32_16x16x32_bf16 v[100:103], v[172:175], v[196:199], v[100:103]
	v_mfma_f32_16x16x32_bf16 v[92:95], v[180:183], v[196:199], v[92:95]
	v_mfma_f32_16x16x32_bf16 v[84:87], v[172:175], v[204:207], v[84:87]
	v_mfma_f32_16x16x32_bf16 v[76:79], v[180:183], v[204:207], v[76:79]
	v_mfma_f32_16x16x32_bf16 v[68:71], v[172:175], v[216:219], v[68:71]
	v_mfma_f32_16x16x32_bf16 v[64:67], v[180:183], v[216:219], v[64:67]
	v_mfma_f32_16x16x32_bf16 v[116:119], v[176:179], v[192:195], v[116:119]
	v_mfma_f32_16x16x32_bf16 v[108:111], v[184:187], v[192:195], v[108:111]
	v_mfma_f32_16x16x32_bf16 v[100:103], v[176:179], v[200:203], v[100:103]
	v_mfma_f32_16x16x32_bf16 v[92:95], v[184:187], v[200:203], v[92:95]
	v_mfma_f32_16x16x32_bf16 v[84:87], v[176:179], v[212:215], v[84:87]
	v_mfma_f32_16x16x32_bf16 v[76:79], v[184:187], v[212:215], v[76:79]
	v_mfma_f32_16x16x32_bf16 v[68:71], v[176:179], v[220:223], v[68:71]
	v_mfma_f32_16x16x32_bf16 v[64:67], v[184:187], v[220:223], v[64:67]
	s_barrier
; __device__ __forceinline__ unsigned cvt_pk_bf16(float lo, float hi) { unsigned r; asm volatile("v_cvt_pk_bf16_f32 %0, %1, %2" : "=v"(r) : "v"(lo), "v"(hi)); return r; }
; #define PG8_STAGE(bufoff, gbase, voff) do { _Pragma("unroll") for (int _i = 0; _i < 2; ++_i) \
;         __builtin_amdgcn_global_load_lds((const unsigned*)((const char*)(gbase) + (voff)[_i]), (PG8_LAS unsigned*)(lds + (bufoff) + ldsw + _i * 8192), 16, 0, 0); } while (0)
; #define PG8_LDA(dst, b, h) do { _Pragma("unroll") for (int m = 0; m < 4; ++m) _Pragma("unroll") for (int k = 0; k < 2; ++k) dst[m][k] = *(const PG8_LAS bf16x8*)(lds + PG8_SA(b, h) + aoff + m * 2048 + k * 1024); } while (0)
; #define PG8_MMA(ai, bj, At, Bt) do { __builtin_amdgcn_s_setprio(1); _Pragma("unroll") for (int m = 0; m < 4; ++m) _Pragma("unroll") for (int n = 0; n < 2; ++n) _Pragma("unroll") for (int k = 0; k < 2; ++k) \
;         acc[ai][bj][m][n] = __builtin_amdgcn_mfma_f32_16x16x32_bf16(Bt[n][k], At[m][k], acc[ai][bj][m][n], 0, 0, 0); __builtin_amdgcn_s_setprio(0); } while (0)
;     __device__ __forceinline__ void operator()(const f32x4 (&acc)[2][2][4][2], const Unit& u, int wr, int wc, int fr, int fq) const {
;         const int row0 = u.pm * BM + wr * 64 + fr; const int col0 = u.pn * BM + wc * 32 + 8 * fq; const float sc = (u.pn < scale_tiles) ? scale0 : 1.f;
; #pragma unroll
;         for (int ai = 0; ai < 2; ++ai)
; #pragma unroll
;             for (int m = 0; m < 4; ++m) { bf16_t* rowp = O + (size_t)(row0 + ai * HALF + m * 16) * ldc + col0;
; #pragma unroll
;                 for (int bj = 0; bj < 2; ++bj) { const f32x4 v0 = acc[ai][bj][m][0] * sc, v1 = acc[ai][bj][m][1] * sc;
;                     u32x4 w; w.x = cvt_pk_bf16(v0[0], v0[1]); w.y = cvt_pk_bf16(v0[2], v0[3]); w.z = cvt_pk_bf16(v1[0], v1[1]); w.w = cvt_pk_bf16(v1[2], v1[3]);
;                     __builtin_nontemporal_store(w, (u32x4*)(rowp + bj * HALF)); } }
; template <class Epi, class Sched, bool ALIGN_EPI = false, bool SP2 = false, bool AROWS128 = false>
; __device__ __forceinline__ void gemm_phase(PG8_LAS unsigned char* lds, const Gemm g, const Sched& S, const Epi& E) {
;     ...
;             PG8_LDA(At, 1, 1); PG8_STAGE(PG8_SB(1, 0), b3, voffB); PG8_STAGE(PG8_SB(1, 1), b3 + hstep, voffB); PG8_STAGE(PG8_SA(1, 0), a3, voffA);
;             PG8_WAIT_V(8); PG8_WAIT_L(0); PG8_BAR; PG8_MMA(1, 0, At, B0); PG8_MMA(1, 1, At, B1); PG8_BAR; PG8_SCHED;
	s_add_i32 s58, s94, s3
	v_lshl_add_u64 v[208:209], v[208:209], 0, s[6:7]
	s_mov_b32 m0, s58
	ds_read_b128 v[188:191], v157 offset:49152
	ds_read_b128 v[192:195], v157 offset:50176
	ds_read_b128 v[196:199], v157 offset:51200
	ds_read_b128 v[200:203], v157 offset:52224
	ds_read_b128 v[204:207], v157 offset:53248
	ds_read_b128 v[212:215], v157 offset:54272
	ds_read_b128 v[216:219], v157 offset:55296
	ds_read_b128 v[220:223], v157 offset:56320
	global_load_lds_dwordx4 v[208:209], off
	s_add_i32 m0, s58, 0x2000
	s_add_u32 s50, s50, 0x40080
	v_lshl_add_u64 v[208:209], v[224:225], 0, s[6:7]
	s_addc_u32 s51, s51, 0
	s_add_i32 s58, s95, s3
	global_load_lds_dwordx4 v[208:209], off
	v_lshl_add_u64 v[208:209], s[50:51], 0, v[134:135]
	s_mov_b32 m0, s58
	s_nop 0
	global_load_lds_dwordx4 v[208:209], off
	v_lshl_add_u64 v[208:209], s[50:51], 0, v[130:131]
	s_add_i32 m0, s58, 0x2000
	s_nop 0
	global_load_lds_dwordx4 v[208:209], off
	v_lshl_add_u64 v[208:209], v[226:227], 0, s[6:7]
	s_mov_b32 m0, s81
	s_nop 0
	global_load_lds_dwordx4 v[208:209], off
	v_lshl_add_u64 v[208:209], v[228:229], 0, s[6:7]
	s_mov_b32 m0, s84
	s_nop 0
	global_load_lds_dwordx4 v[208:209], off
	s_waitcnt vmcnt(8)
	s_waitcnt lgkmcnt(0)
	s_barrier
	s_waitcnt lgkmcnt(0)
	v_mfma_f32_16x16x32_bf16 v[60:63], v[148:151], v[188:191], v[60:63]
	v_mfma_f32_16x16x32_bf16 v[56:59], v[164:167], v[188:191], v[56:59]
	v_mfma_f32_16x16x32_bf16 v[48:51], v[148:151], v[196:199], v[48:51]
	v_mfma_f32_16x16x32_bf16 v[40:43], v[164:167], v[196:199], v[40:43]
	v_mfma_f32_16x16x32_bf16 v[32:35], v[148:151], v[204:207], v[32:35]
	v_mfma_f32_16x16x32_bf16 v[24:27], v[164:167], v[204:207], v[24:27]
	v_mfma_f32_16x16x32_bf16 v[16:19], v[148:151], v[216:219], v[16:19]
	v_mfma_f32_16x16x32_bf16 v[8:11], v[164:167], v[216:219], v[8:11]
	v_mfma_f32_16x16x32_bf16 v[60:63], v[160:163], v[192:195], v[60:63]
	v_mfma_f32_16x16x32_bf16 v[56:59], v[168:171], v[192:195], v[56:59]
	v_mfma_f32_16x16x32_bf16 v[48:51], v[160:163], v[200:203], v[48:51]
	v_mfma_f32_16x16x32_bf16 v[40:43], v[168:171], v[200:203], v[40:43]
	v_mfma_f32_16x16x32_bf16 v[32:35], v[160:163], v[212:215], v[32:35]
	v_mfma_f32_16x16x32_bf16 v[24:27], v[168:171], v[212:215], v[24:27]
	v_mfma_f32_16x16x32_bf16 v[16:19], v[160:163], v[220:223], v[16:19]
	v_mfma_f32_16x16x32_bf16 v[8:11], v[168:171], v[220:223], v[8:11]
	v_mfma_f32_16x16x32_bf16 v[52:55], v[172:175], v[188:191], v[52:55]
	v_mfma_f32_16x16x32_bf16 v[44:47], v[180:183], v[188:191], v[44:47]
	v_mfma_f32_16x16x32_bf16 v[36:39], v[172:175], v[196:199], v[36:39]
	v_mfma_f32_16x16x32_bf16 v[28:31], v[180:183], v[196:199], v[28:31]
	v_mfma_f32_16x16x32_bf16 v[20:23], v[172:175], v[204:207], v[20:23]
	v_mfma_f32_16x16x32_bf16 v[12:15], v[180:183], v[204:207], v[12:15]
	v_mfma_f32_16x16x32_bf16 v[4:7], v[172:175], v[216:219], v[4:7]
	v_mfma_f32_16x16x32_bf16 v[0:3], v[180:183], v[216:219], v[0:3]
	v_mfma_f32_16x16x32_bf16 v[52:55], v[176:179], v[192:195], v[52:55]
	v_mfma_f32_16x16x32_bf16 v[44:47], v[184:187], v[192:195], v[44:47]
	v_mfma_f32_16x16x32_bf16 v[36:39], v[176:179], v[200:203], v[36:39]
	v_mfma_f32_16x16x32_bf16 v[28:31], v[184:187], v[200:203], v[28:31]
	v_mfma_f32_16x16x32_bf16 v[20:23], v[176:179], v[212:215], v[20:23]
	v_mfma_f32_16x16x32_bf16 v[12:15], v[184:187], v[212:215], v[12:15]
	v_mfma_f32_16x16x32_bf16 v[4:7], v[176:179], v[220:223], v[4:7]
	v_mfma_f32_16x16x32_bf16 v[0:3], v[184:187], v[220:223], v[0:3]
	s_barrier
	s_add_i32 s93, s93, 2
	s_add_u32 s48, s48, 0x100
	s_addc_u32 s49, s49, 0
	s_add_u32 s91, s91, 0x100
	s_addc_u32 s92, s92, 0
	s_cmp_gt_u32 s93, 13
	s_cbranch_scc0 .LBB0_119
	s_and_b64 vcc, exec, s[10:11]
	s_cbranch_vccz .LBB0_122
	s_barrier
.LBB0_122:
	v_lshl_or_b32 v150, s90, 8, v154
	s_cmp_lt_i32 s90, 2
	v_lshl_add_u32 v159, s30, 8, v152
	s_cselect_b64 vcc, -1, 0
	v_ashrrev_i32_e32 v151, 31, v150
	v_mov_b64_e32 v[148:149], s[44:45]
	v_cndmask_b32_e32 v146, 1.0, v158, vcc
	v_mad_i64_i32 v[160:161], s[48:49], v159, s89, v[148:149]
	v_lshlrev_b64 v[150:151], 1, v[150:151]
	v_lshl_add_u64 v[160:161], v[160:161], 0, v[150:151]
	v_pk_mul_f32 v[126:127], v[146:147], v[126:127] op_sel_hi:[0,1]
	v_pk_mul_f32 v[124:125], v[146:147], v[124:125] op_sel_hi:[0,1]
	v_pk_mul_f32 v[162:163], v[146:147], v[122:123] op_sel_hi:[0,1]
	v_pk_mul_f32 v[122:123], v[146:147], v[120:121] op_sel_hi:[0,1]
	v_cvt_pk_bf16_f32 v120, v124, v125
	v_cvt_pk_bf16_f32 v121, v126, v127
	v_cvt_pk_bf16_f32 v122, v122, v123
	v_cvt_pk_bf16_f32 v123, v162, v163
	global_store_dwordx4 v[160:161], v[120:123], off nt
	v_pk_mul_f32 v[116:117], v[146:147], v[116:117] op_sel_hi:[0,1]
	v_pk_mul_f32 v[118:119], v[146:147], v[118:119] op_sel_hi:[0,1]
	v_pk_mul_f32 v[120:121], v[146:147], v[110:111] op_sel_hi:[0,1]
	v_pk_mul_f32 v[110:111], v[146:147], v[108:109] op_sel_hi:[0,1]
	v_cvt_pk_bf16_f32 v108, v116, v117
	v_cvt_pk_bf16_f32 v109, v118, v119
	v_cvt_pk_bf16_f32 v110, v110, v111
	v_cvt_pk_bf16_f32 v111, v120, v121
	global_store_dwordx4 v[160:161], v[108:111], off offset:256 nt
	v_pk_mul_f32 v[112:113], v[146:147], v[112:113] op_sel_hi:[0,1]
	v_pk_mul_f32 v[100:101], v[146:147], v[100:101] op_sel_hi:[0,1]
	v_or_b32_e32 v108, 16, v159
	v_mad_i64_i32 v[108:109], s[48:49], v108, s89, v[148:149]
	v_lshl_add_u64 v[108:109], v[108:109], 0, v[150:151]
	v_pk_mul_f32 v[110:111], v[146:147], v[114:115] op_sel_hi:[0,1]
	v_pk_mul_f32 v[114:115], v[146:147], v[106:107] op_sel_hi:[0,1]
	v_pk_mul_f32 v[106:107], v[146:147], v[104:105] op_sel_hi:[0,1]
	v_cvt_pk_bf16_f32 v104, v112, v113
	v_cvt_pk_bf16_f32 v105, v110, v111
	v_cvt_pk_bf16_f32 v106, v106, v107
	v_cvt_pk_bf16_f32 v107, v114, v115
	global_store_dwordx4 v[108:109], v[104:107], off nt
; __device__ __forceinline__ unsigned cvt_pk_bf16(float lo, float hi) { unsigned r; asm volatile("v_cvt_pk_bf16_f32 %0, %1, %2" : "=v"(r) : "v"(lo), "v"(hi)); return r; }
; #define PG8_BAR __builtin_amdgcn_s_barrier()
;     __device__ __forceinline__ void operator()(const f32x4 (&acc)[2][2][4][2], const Unit& u, int wr, int wc, int fr, int fq) const {
;     ...
;             for (int m = 0; m < 4; ++m) { bf16_t* rowp = O + (size_t)(row0 + ai * HALF + m * 16) * ldc + col0;
; #pragma unroll
;                 for (int bj = 0; bj < 2; ++bj) { const f32x4 v0 = acc[ai][bj][m][0] * sc, v1 = acc[ai][bj][m][1] * sc;
;                     u32x4 w; w.x = cvt_pk_bf16(v0[0], v0[1]); w.y = cvt_pk_bf16(v0[2], v0[3]); w.z = cvt_pk_bf16(v1[0], v1[1]); w.w = cvt_pk_bf16(v1[2], v1[3]);
;                     __builtin_nontemporal_store(w, (u32x4*)(rowp + bj * HALF)); } }
; template <class Epi, class Sched, bool ALIGN_EPI = false, bool SP2 = false, bool AROWS128 = false>
; __device__ __forceinline__ void gemm_phase(PG8_LAS unsigned char* lds, const Gemm g, const Sched& S, const Epi& E) {
;     ...
;         if constexpr (!Epi::AFTER_DRAIN) { E(acc, cur, wr, wc, fr, fq); S.done(cur); }
;         if (!has_next) break;
; #pragma unroll
;         for (int a = 0; a < 2; ++a)
; #pragma unroll
;             for (int b = 0; b < 2; ++b)
; #pragma unroll
;                 for (int m = 0; m < 4; ++m)
; #pragma unroll
;                     for (int n = 0; n < 2; ++n) acc[a][b][m][n] = (f32x4){0.f, 0.f, 0.f, 0.f};
;         cur = nxt; cA = nA; cB = nB; ++ui;
;         if constexpr (ALIGN_EPI) { if (wr == 1) PG8_BAR; }
	v_pk_mul_f32 v[102:103], v[146:147], v[102:103] op_sel_hi:[0,1]
	v_pk_mul_f32 v[96:97], v[146:147], v[96:97] op_sel_hi:[0,1]
	v_pk_mul_f32 v[104:105], v[146:147], v[94:95] op_sel_hi:[0,1]
	v_pk_mul_f32 v[94:95], v[146:147], v[92:93] op_sel_hi:[0,1]
	v_cvt_pk_bf16_f32 v92, v100, v101
	v_cvt_pk_bf16_f32 v93, v102, v103
	v_cvt_pk_bf16_f32 v94, v94, v95
	v_cvt_pk_bf16_f32 v95, v104, v105
	global_store_dwordx4 v[108:109], v[92:95], off offset:256 nt
	v_pk_mul_f32 v[84:85], v[146:147], v[84:85] op_sel_hi:[0,1]
	v_pk_mul_f32 v[86:87], v[146:147], v[86:87] op_sel_hi:[0,1]
	v_or_b32_e32 v92, 32, v159
	v_mad_i64_i32 v[92:93], s[48:49], v92, s89, v[148:149]
	v_lshl_add_u64 v[92:93], v[92:93], 0, v[150:151]
	v_pk_mul_f32 v[94:95], v[146:147], v[98:99] op_sel_hi:[0,1]
	v_pk_mul_f32 v[98:99], v[146:147], v[90:91] op_sel_hi:[0,1]
	v_pk_mul_f32 v[90:91], v[146:147], v[88:89] op_sel_hi:[0,1]
	v_cvt_pk_bf16_f32 v88, v96, v97
	v_cvt_pk_bf16_f32 v89, v94, v95
	v_cvt_pk_bf16_f32 v90, v90, v91
	v_cvt_pk_bf16_f32 v91, v98, v99
	global_store_dwordx4 v[92:93], v[88:91], off nt
	v_pk_mul_f32 v[80:81], v[146:147], v[80:81] op_sel_hi:[0,1]
	v_pk_mul_f32 v[68:69], v[146:147], v[68:69] op_sel_hi:[0,1]
	v_pk_mul_f32 v[88:89], v[146:147], v[78:79] op_sel_hi:[0,1]
	v_pk_mul_f32 v[78:79], v[146:147], v[76:77] op_sel_hi:[0,1]
	v_cvt_pk_bf16_f32 v76, v84, v85
	v_cvt_pk_bf16_f32 v77, v86, v87
	v_cvt_pk_bf16_f32 v78, v78, v79
	v_cvt_pk_bf16_f32 v79, v88, v89
	global_store_dwordx4 v[92:93], v[76:79], off offset:256 nt
	v_pk_mul_f32 v[70:71], v[146:147], v[70:71] op_sel_hi:[0,1]
	v_pk_mul_f32 v[62:63], v[146:147], v[62:63] op_sel_hi:[0,1]
	v_or_b32_e32 v76, 48, v159
	v_mad_i64_i32 v[76:77], s[48:49], v76, s89, v[148:149]
	v_lshl_add_u64 v[76:77], v[76:77], 0, v[150:151]
	v_pk_mul_f32 v[78:79], v[146:147], v[82:83] op_sel_hi:[0,1]
	v_pk_mul_f32 v[82:83], v[146:147], v[74:75] op_sel_hi:[0,1]
	v_pk_mul_f32 v[74:75], v[146:147], v[72:73] op_sel_hi:[0,1]
	v_cvt_pk_bf16_f32 v72, v80, v81
	v_cvt_pk_bf16_f32 v73, v78, v79
	v_cvt_pk_bf16_f32 v74, v74, v75
	v_cvt_pk_bf16_f32 v75, v82, v83
	global_store_dwordx4 v[76:77], v[72:75], off nt
	v_pk_mul_f32 v[60:61], v[146:147], v[60:61] op_sel_hi:[0,1]
	v_pk_mul_f32 v[52:53], v[146:147], v[52:53] op_sel_hi:[0,1]
	v_pk_mul_f32 v[72:73], v[146:147], v[66:67] op_sel_hi:[0,1]
	v_pk_mul_f32 v[66:67], v[146:147], v[64:65] op_sel_hi:[0,1]
	v_cvt_pk_bf16_f32 v64, v68, v69
	v_cvt_pk_bf16_f32 v65, v70, v71
	v_cvt_pk_bf16_f32 v66, v66, v67
	v_cvt_pk_bf16_f32 v67, v72, v73
	global_store_dwordx4 v[76:77], v[64:67], off offset:256 nt
	v_pk_mul_f32 v[54:55], v[146:147], v[54:55] op_sel_hi:[0,1]
	v_pk_mul_f32 v[48:49], v[146:147], v[48:49] op_sel_hi:[0,1]
	v_add_u32_e32 v64, 0x80, v159
	v_mad_i64_i32 v[64:65], s[48:49], v64, s89, v[148:149]
	v_lshl_add_u64 v[64:65], v[64:65], 0, v[150:151]
	v_pk_mul_f32 v[66:67], v[146:147], v[58:59] op_sel_hi:[0,1]
	v_pk_mul_f32 v[58:59], v[146:147], v[56:57] op_sel_hi:[0,1]
	v_cvt_pk_bf16_f32 v56, v60, v61
	v_cvt_pk_bf16_f32 v57, v62, v63
	v_cvt_pk_bf16_f32 v58, v58, v59
	v_cvt_pk_bf16_f32 v59, v66, v67
	global_store_dwordx4 v[64:65], v[56:59], off nt
	v_pk_mul_f32 v[36:37], v[146:147], v[36:37] op_sel_hi:[0,1]
	v_pk_mul_f32 v[38:39], v[146:147], v[38:39] op_sel_hi:[0,1]
	v_pk_mul_f32 v[56:57], v[146:147], v[46:47] op_sel_hi:[0,1]
	v_pk_mul_f32 v[46:47], v[146:147], v[44:45] op_sel_hi:[0,1]
	v_cvt_pk_bf16_f32 v44, v52, v53
	v_cvt_pk_bf16_f32 v45, v54, v55
	v_cvt_pk_bf16_f32 v46, v46, v47
	v_cvt_pk_bf16_f32 v47, v56, v57
	global_store_dwordx4 v[64:65], v[44:47], off offset:256 nt
	v_pk_mul_f32 v[32:33], v[146:147], v[32:33] op_sel_hi:[0,1]
	v_pk_mul_f32 v[20:21], v[146:147], v[20:21] op_sel_hi:[0,1]
	v_add_u32_e32 v44, 0x90, v159
	v_mad_i64_i32 v[44:45], s[48:49], v44, s89, v[148:149]
	v_lshl_add_u64 v[44:45], v[44:45], 0, v[150:151]
	v_pk_mul_f32 v[46:47], v[146:147], v[50:51] op_sel_hi:[0,1]
	v_pk_mul_f32 v[50:51], v[146:147], v[42:43] op_sel_hi:[0,1]
	v_pk_mul_f32 v[42:43], v[146:147], v[40:41] op_sel_hi:[0,1]
	v_cvt_pk_bf16_f32 v40, v48, v49
	v_cvt_pk_bf16_f32 v41, v46, v47
	v_cvt_pk_bf16_f32 v42, v42, v43
	v_cvt_pk_bf16_f32 v43, v50, v51
	global_store_dwordx4 v[44:45], v[40:43], off nt
	v_pk_mul_f32 v[22:23], v[146:147], v[22:23] op_sel_hi:[0,1]
	v_pk_mul_f32 v[16:17], v[146:147], v[16:17] op_sel_hi:[0,1]
	v_pk_mul_f32 v[40:41], v[146:147], v[30:31] op_sel_hi:[0,1]
	v_pk_mul_f32 v[30:31], v[146:147], v[28:29] op_sel_hi:[0,1]
	v_cvt_pk_bf16_f32 v28, v36, v37
	v_cvt_pk_bf16_f32 v29, v38, v39
	v_cvt_pk_bf16_f32 v30, v30, v31
	v_cvt_pk_bf16_f32 v31, v40, v41
	global_store_dwordx4 v[44:45], v[28:31], off offset:256 nt
	s_andn2_b64 vcc, exec, s[0:1]
	s_mov_b64 s[0:1], -1
	v_add_u32_e32 v28, 0xa0, v159
	v_mad_i64_i32 v[28:29], s[48:49], v28, s89, v[148:149]
	v_lshl_add_u64 v[28:29], v[28:29], 0, v[150:151]
	v_pk_mul_f32 v[30:31], v[146:147], v[34:35] op_sel_hi:[0,1]
	v_pk_mul_f32 v[34:35], v[146:147], v[26:27] op_sel_hi:[0,1]
	v_pk_mul_f32 v[26:27], v[146:147], v[24:25] op_sel_hi:[0,1]
	v_cvt_pk_bf16_f32 v24, v32, v33
	v_cvt_pk_bf16_f32 v25, v30, v31
	v_cvt_pk_bf16_f32 v26, v26, v27
	v_cvt_pk_bf16_f32 v27, v34, v35
	global_store_dwordx4 v[28:29], v[24:27], off nt
	v_pk_mul_f32 v[6:7], v[146:147], v[6:7] op_sel_hi:[0,1]
	v_pk_mul_f32 v[4:5], v[146:147], v[4:5] op_sel_hi:[0,1]
	v_pk_mul_f32 v[24:25], v[146:147], v[14:15] op_sel_hi:[0,1]
	v_pk_mul_f32 v[14:15], v[146:147], v[12:13] op_sel_hi:[0,1]
	v_cvt_pk_bf16_f32 v12, v20, v21
	v_cvt_pk_bf16_f32 v13, v22, v23
	v_cvt_pk_bf16_f32 v14, v14, v15
	v_cvt_pk_bf16_f32 v15, v24, v25
	global_store_dwordx4 v[28:29], v[12:15], off offset:256 nt
	s_nop 1
	v_add_u32_e32 v12, 0xb0, v159
	v_mad_i64_i32 v[12:13], s[48:49], v12, s89, v[148:149]
	v_lshl_add_u64 v[12:13], v[12:13], 0, v[150:151]
	v_pk_mul_f32 v[14:15], v[146:147], v[18:19] op_sel_hi:[0,1]
	v_pk_mul_f32 v[18:19], v[146:147], v[10:11] op_sel_hi:[0,1]
	v_pk_mul_f32 v[10:11], v[146:147], v[8:9] op_sel_hi:[0,1]
	v_cvt_pk_bf16_f32 v8, v16, v17
	v_cvt_pk_bf16_f32 v9, v14, v15
	v_cvt_pk_bf16_f32 v10, v10, v11
	v_cvt_pk_bf16_f32 v11, v18, v19
	global_store_dwordx4 v[12:13], v[8:11], off nt
	s_nop 1
	v_pk_mul_f32 v[8:9], v[146:147], v[2:3] op_sel_hi:[0,1]
	v_pk_mul_f32 v[2:3], v[146:147], v[0:1] op_sel_hi:[0,1]
	v_cvt_pk_bf16_f32 v0, v4, v5
	v_cvt_pk_bf16_f32 v1, v6, v7
	v_cvt_pk_bf16_f32 v2, v2, v3
	v_cvt_pk_bf16_f32 v3, v8, v9
	global_store_dwordx4 v[12:13], v[0:3], off offset:256 nt
	s_cbranch_vccnz .LBB0_115
	s_andn2_b64 vcc, exec, s[4:5]
	s_cbranch_vccnz .LBB0_114
	s_barrier
	s_branch .LBB0_114
; #define PG8_WAIT_V(n) asm volatile("s_waitcnt vmcnt(" #n ")" ::: "memory")
; #define PG8_BAR __builtin_amdgcn_s_barrier()
; template <class Epi, class Sched, bool ALIGN_EPI = false, bool SP2 = false, bool AROWS128 = false>
; __device__ __forceinline__ void gemm_phase(PG8_LAS unsigned char* lds, const Gemm g, const Sched& S, const Epi& E) {
;     ...
;     PG8_WAIT_V(0);
;     if constexpr (!ALIGN_EPI) { if (wr == 0) PG8_BAR; }
;     PG8_BAR;
; __device__ __forceinline__ void xcd_barrier(const XcdBarrier& b) {
;     asm volatile("s_waitcnt vmcnt(0)" ::: "memory");
;     __syncthreads();
;     if (threadIdx.x == 0) {
;         unsigned* bar = b.bar;
;         __builtin_amdgcn_s_waitcnt(0);
;         unsigned nloc = b.st[0], nx = b.st[1];
;         if (nloc == 0u) { xcd_barrier_complete(bar, b.x, nloc, nx); b.st[0] = nloc; b.st[1] = nx; }
.LBB0_125:
	s_setprio 0
	s_waitcnt vmcnt(0)
	s_barrier
.LBB0_126:
	s_waitcnt vmcnt(0)
	s_waitcnt vmcnt(0)
	s_barrier
	s_and_saveexec_b64 s[0:1], s[22:23]
	s_cbranch_execz .LBB0_178
	s_add_i32 s3, 0, 0x20020
	v_mov_b32_e32 v0, s3
	s_waitcnt vmcnt(0) expcnt(0) lgkmcnt(0)
	ds_read_b32 v2, v0
	s_add_i32 s3, 0, 0x20024
	v_mov_b32_e32 v0, s3
	ds_read_b32 v0, v0
	s_waitcnt lgkmcnt(1)
	v_cmp_ne_u32_e32 vcc, 0, v2
	s_cbranch_vccnz .LBB0_142
	s_add_u32 s4, s70, 0x1200
	s_addc_u32 s5, s71, 0
	s_add_u32 s6, s70, 0x1400
	s_addc_u32 s7, s71, 0
	s_add_u32 s10, s70, 0x1500
	s_addc_u32 s11, s71, 0
	s_add_u32 s14, s70, 0x1600
	s_addc_u32 s15, s71, 0
	s_add_u32 s24, s70, 0x1700
	s_addc_u32 s25, s71, 0
	s_add_u32 s26, s70, 0x1800
	s_addc_u32 s27, s71, 0
	s_add_u32 s28, s70, 0x1900
	s_addc_u32 s29, s71, 0
	s_add_u32 s30, s70, 0x1a00
	s_addc_u32 s31, s71, 0
	s_add_u32 s48, s70, 0x1b00
	s_addc_u32 s49, s71, 0
	s_add_u32 s50, s70, 0x1c00
	s_addc_u32 s51, s71, 0
	s_add_u32 s58, s70, 0x1d00
	s_addc_u32 s59, s71, 0
	s_add_u32 s64, s70, 0x1e00
	s_addc_u32 s65, s71, 0
	s_add_u32 s82, s70, 0x1f00
	s_addc_u32 s83, s71, 0
	s_add_u32 s84, s70, 0x2000
	s_addc_u32 s85, s71, 0
	s_add_u32 s86, s70, 0x2100
	s_addc_u32 s87, s71, 0
	s_add_u32 s88, s70, 0x2200
	v_readlane_b32 s3, v255, 8
	s_addc_u32 s89, s71, 0
	s_mul_i32 s3, s75, s3
	s_add_u32 s90, s70, 0x2300
	s_mul_i32 s3, s3, s74
	s_addc_u32 s91, s71, 0
	s_mov_b32 s33, 1
	v_mov_b32_e32 v16, 0
	s_branch .LBB0_130

; #define PG8_STAGE(bufoff, gbase, voff) do { _Pragma("unroll") for (int _i = 0; _i < 2; ++_i) \
;         __builtin_amdgcn_global_load_lds((const unsigned*)((const char*)(gbase) + (voff)[_i]), (PG8_LAS unsigned*)(lds + (bufoff) + ldsw + _i * 8192), 16, 0, 0); } while (0)
; #define PG8_LDA(dst, b, h) do { _Pragma("unroll") for (int m = 0; m < 4; ++m) _Pragma("unroll") for (int k = 0; k < 2; ++k) dst[m][k] = *(const PG8_LAS bf16x8*)(lds + PG8_SA(b, h) + aoff + m * 2048 + k * 1024); } while (0)
; #define PG8_LDB(dst, b, h) do { _Pragma("unroll") for (int n = 0; n < 2; ++n) _Pragma("unroll") for (int k = 0; k < 2; ++k) dst[n][k] = *(const PG8_LAS bf16x8*)(lds + PG8_SB(b, h) + boff + n * 2048 + k * 1024); } while (0)
; #define PG8_MMA(ai, bj, At, Bt) do { __builtin_amdgcn_s_setprio(1); _Pragma("unroll") for (int m = 0; m < 4; ++m) _Pragma("unroll") for (int n = 0; n < 2; ++n) _Pragma("unroll") for (int k = 0; k < 2; ++k) \
;         acc[ai][bj][m][n] = __builtin_amdgcn_mfma_f32_16x16x32_bf16(Bt[n][k], At[m][k], acc[ai][bj][m][n], 0, 0, 0); __builtin_amdgcn_s_setprio(0); } while (0)
; #define PG8_WAIT_V(n) asm volatile("s_waitcnt vmcnt(" #n ")" ::: "memory")
; #define PG8_WAIT_L(n) asm volatile("s_waitcnt lgkmcnt(" #n ")" ::: "memory")
; template <class Epi, class Sched, bool ALIGN_EPI = false, bool SP2 = false, bool AROWS128 = false>
; __device__ __forceinline__ void gemm_phase(PG8_LAS unsigned char* lds, const Gemm g, const Sched& S, const Epi& E) {
;     ...
;             const bool last = (t == nt - 2);
;             const char* a1 = cA + (size_t)(t + 1) * kstep;
;             const char* a2 = last ? nA : cA + (size_t)(t + 2) * kstep; const char* b2 = last ? nB : cB + (size_t)(t + 2) * kstep;
;             const char* a3 = a2 + kstep; const char* b3 = b2 + kstep;
;             if (last && has_next) S.a_ready(nxt);
;             if constexpr (SP2) {
;             PG8_LDB(B0, 0, 0); PG8_LDB(B1, 0, 1); PG8_SCHED; PG8_LDA(At, 0, 0); PG8_STAGE(PG8_SA(1, 1), a1 + hstepA, voffA);
;             PG8_WAIT_V(8); PG8_WAIT_L(0); PG8_BAR; PG8_MMA(0, 0, At, B0); PG8_MMA(0, 1, At, B1); PG8_BAR; PG8_SCHED;
;             PG8_LDA(At, 0, 1); PG8_STAGE(PG8_SB(0, 0), b2, voffB); PG8_STAGE(PG8_SB(0, 1), b2 + hstep, voffB); PG8_STAGE(PG8_SA(0, 0), a2, voffA);
;             PG8_WAIT_V(8); PG8_WAIT_L(0); PG8_BAR; PG8_MMA(1, 0, At, B0); PG8_MMA(1, 1, At, B1); PG8_BAR; PG8_SCHED;
.LBB0_489:
	ds_read_b128 v[152:155], v149
	ds_read_b128 v[156:159], v149 offset:1024
	ds_read_b128 v[160:163], v149 offset:2048
	ds_read_b128 v[164:167], v149 offset:3072
	ds_read_b128 v[168:171], v150
	ds_read_b128 v[172:175], v150 offset:1024
	ds_read_b128 v[176:179], v150 offset:2048
	ds_read_b128 v[180:183], v150 offset:3072
	s_add_u32 s28, s26, 0xfffc0080
	s_addc_u32 s29, s27, -1
	s_cmp_eq_u32 s84, 12
	s_cselect_b32 s31, s15, s29
	s_cselect_b32 s30, s76, s28
	s_cselect_b32 s29, s13, s83
	s_cselect_b32 s28, s77, s82
	v_lshl_add_u64 v[144:145], s[26:27], 0, v[136:137]
	s_add_i32 m0, s25, 0xc000
	ds_read_b128 v[184:187], v151
	ds_read_b128 v[188:191], v151 offset:1024
	ds_read_b128 v[192:195], v151 offset:2048
	ds_read_b128 v[196:199], v151 offset:3072
	ds_read_b128 v[200:203], v151 offset:4096
	ds_read_b128 v[204:207], v151 offset:5120
	ds_read_b128 v[212:215], v151 offset:6144
	ds_read_b128 v[216:219], v151 offset:7168
	global_load_lds_dwordx4 v[144:145], off
	v_lshl_add_u64 v[144:145], s[26:27], 0, v[138:139]
	s_add_i32 m0, s25, 0xe000
	s_nop 0
	global_load_lds_dwordx4 v[144:145], off
	s_waitcnt vmcnt(8)
	s_waitcnt lgkmcnt(0)
	s_barrier
	s_waitcnt lgkmcnt(0)
	v_mfma_f32_16x16x32_bf16 v[124:127], v[152:155], v[184:187], v[124:127]
	v_mfma_f32_16x16x32_bf16 v[120:123], v[160:163], v[184:187], v[120:123]
	v_mfma_f32_16x16x32_bf16 v[116:119], v[152:155], v[192:195], v[116:119]
	v_mfma_f32_16x16x32_bf16 v[108:111], v[160:163], v[192:195], v[108:111]
	v_mfma_f32_16x16x32_bf16 v[100:103], v[152:155], v[200:203], v[100:103]
	v_mfma_f32_16x16x32_bf16 v[92:95], v[160:163], v[200:203], v[92:95]
	v_mfma_f32_16x16x32_bf16 v[84:87], v[152:155], v[212:215], v[84:87]
	v_mfma_f32_16x16x32_bf16 v[76:79], v[160:163], v[212:215], v[76:79]
	v_mfma_f32_16x16x32_bf16 v[124:127], v[156:159], v[188:191], v[124:127]
	v_mfma_f32_16x16x32_bf16 v[120:123], v[164:167], v[188:191], v[120:123]
	v_mfma_f32_16x16x32_bf16 v[116:119], v[156:159], v[196:199], v[116:119]
	v_mfma_f32_16x16x32_bf16 v[108:111], v[164:167], v[196:199], v[108:111]
	v_mfma_f32_16x16x32_bf16 v[100:103], v[156:159], v[204:207], v[100:103]
	v_mfma_f32_16x16x32_bf16 v[92:95], v[164:167], v[204:207], v[92:95]
	v_mfma_f32_16x16x32_bf16 v[84:87], v[156:159], v[216:219], v[84:87]
	v_mfma_f32_16x16x32_bf16 v[76:79], v[164:167], v[216:219], v[76:79]
	v_mfma_f32_16x16x32_bf16 v[112:115], v[168:171], v[184:187], v[112:115]
	v_mfma_f32_16x16x32_bf16 v[104:107], v[176:179], v[184:187], v[104:107]
	v_mfma_f32_16x16x32_bf16 v[96:99], v[168:171], v[192:195], v[96:99]
	v_mfma_f32_16x16x32_bf16 v[88:91], v[176:179], v[192:195], v[88:91]
	v_mfma_f32_16x16x32_bf16 v[80:83], v[168:171], v[200:203], v[80:83]
	v_mfma_f32_16x16x32_bf16 v[72:75], v[176:179], v[200:203], v[72:75]
	v_mfma_f32_16x16x32_bf16 v[68:71], v[168:171], v[212:215], v[68:71]
	v_mfma_f32_16x16x32_bf16 v[64:67], v[176:179], v[212:215], v[64:67]
	v_mfma_f32_16x16x32_bf16 v[112:115], v[172:175], v[188:191], v[112:115]
	v_mfma_f32_16x16x32_bf16 v[104:107], v[180:183], v[188:191], v[104:107]
	v_mfma_f32_16x16x32_bf16 v[96:99], v[172:175], v[196:199], v[96:99]
	v_mfma_f32_16x16x32_bf16 v[88:91], v[180:183], v[196:199], v[88:91]
	v_mfma_f32_16x16x32_bf16 v[80:83], v[172:175], v[204:207], v[80:83]
	v_mfma_f32_16x16x32_bf16 v[72:75], v[180:183], v[204:207], v[72:75]
	v_mfma_f32_16x16x32_bf16 v[68:71], v[172:175], v[216:219], v[68:71]
	v_mfma_f32_16x16x32_bf16 v[64:67], v[180:183], v[216:219], v[64:67]
	s_barrier
	s_add_i32 s85, s72, s3
	v_lshl_add_u64 v[144:145], s[28:29], 0, v[132:133]
	s_mov_b32 m0, s85
	ds_read_b128 v[184:187], v151 offset:16384
	ds_read_b128 v[188:191], v151 offset:17408
	ds_read_b128 v[192:195], v151 offset:18432
	ds_read_b128 v[196:199], v151 offset:19456
	ds_read_b128 v[200:203], v151 offset:20480
	ds_read_b128 v[204:207], v151 offset:21504
	ds_read_b128 v[212:215], v151 offset:22528
	ds_read_b128 v[216:219], v151 offset:23552
	global_load_lds_dwordx4 v[144:145], off
	s_add_i32 m0, s85, 0x2000
	s_add_u32 s86, s28, 0x40000
	v_lshl_add_u64 v[208:209], s[28:29], 0, v[128:129]
	s_addc_u32 s87, s29, 0
	s_add_i32 s85, s73, s3
	global_load_lds_dwordx4 v[208:209], off
	v_lshl_add_u64 v[220:221], s[86:87], 0, v[132:133]
	s_mov_b32 m0, s85
	v_lshl_add_u64 v[222:223], s[30:31], 0, v[130:131]
	global_load_lds_dwordx4 v[220:221], off
	v_lshl_add_u64 v[220:221], s[86:87], 0, v[128:129]
	s_add_i32 m0, s85, 0x2000
	s_nop 0
	global_load_lds_dwordx4 v[220:221], off
	v_lshl_add_u64 v[220:221], s[30:31], 0, v[134:135]
	s_mov_b32 m0, s25
	s_nop 0
	global_load_lds_dwordx4 v[220:221], off
	s_mov_b32 m0, s50
	s_nop 0
	global_load_lds_dwordx4 v[222:223], off
	s_waitcnt vmcnt(8)
	s_waitcnt lgkmcnt(0)
	s_barrier
; #define PG8_STAGE(bufoff, gbase, voff) do { _Pragma("unroll") for (int _i = 0; _i < 2; ++_i) \
;         __builtin_amdgcn_global_load_lds((const unsigned*)((const char*)(gbase) + (voff)[_i]), (PG8_LAS unsigned*)(lds + (bufoff) + ldsw + _i * 8192), 16, 0, 0); } while (0)
; #define PG8_LDA(dst, b, h) do { _Pragma("unroll") for (int m = 0; m < 4; ++m) _Pragma("unroll") for (int k = 0; k < 2; ++k) dst[m][k] = *(const PG8_LAS bf16x8*)(lds + PG8_SA(b, h) + aoff + m * 2048 + k * 1024); } while (0)
; #define PG8_LDB(dst, b, h) do { _Pragma("unroll") for (int n = 0; n < 2; ++n) _Pragma("unroll") for (int k = 0; k < 2; ++k) dst[n][k] = *(const PG8_LAS bf16x8*)(lds + PG8_SB(b, h) + boff + n * 2048 + k * 1024); } while (0)
; #define PG8_MMA(ai, bj, At, Bt) do { __builtin_amdgcn_s_setprio(1); _Pragma("unroll") for (int m = 0; m < 4; ++m) _Pragma("unroll") for (int n = 0; n < 2; ++n) _Pragma("unroll") for (int k = 0; k < 2; ++k) \
;         acc[ai][bj][m][n] = __builtin_amdgcn_mfma_f32_16x16x32_bf16(Bt[n][k], At[m][k], acc[ai][bj][m][n], 0, 0, 0); __builtin_amdgcn_s_setprio(0); } while (0)
; #define PG8_WAIT_V(n) asm volatile("s_waitcnt vmcnt(" #n ")" ::: "memory")
; #define PG8_WAIT_L(n) asm volatile("s_waitcnt lgkmcnt(" #n ")" ::: "memory")
; #define PG8_BAR __builtin_amdgcn_s_barrier()
; #define PG8_SCHED __builtin_amdgcn_sched_barrier(0)
; template <class Epi, class Sched, bool ALIGN_EPI = false, bool SP2 = false, bool AROWS128 = false>
; __device__ __forceinline__ void gemm_phase(PG8_LAS unsigned char* lds, const Gemm g, const Sched& S, const Epi& E) {
;     ...
;             PG8_WAIT_V(8); PG8_WAIT_L(0); PG8_BAR; PG8_MMA(1, 0, At, B0); PG8_MMA(1, 1, At, B1); PG8_BAR; PG8_SCHED;
;             PG8_LDB(B0, 1, 0); PG8_LDB(B1, 1, 1); PG8_SCHED; PG8_LDA(At, 1, 0); PG8_STAGE(PG8_SA(0, 1), a2 + hstepA, voffA);
;             PG8_WAIT_V(8); PG8_WAIT_L(0); PG8_BAR; PG8_MMA(0, 0, At, B0); PG8_MMA(0, 1, At, B1); PG8_BAR; PG8_SCHED;
	s_waitcnt lgkmcnt(0)
	v_mfma_f32_16x16x32_bf16 v[60:63], v[152:155], v[184:187], v[60:63]
	v_mfma_f32_16x16x32_bf16 v[56:59], v[160:163], v[184:187], v[56:59]
	v_mfma_f32_16x16x32_bf16 v[52:55], v[152:155], v[192:195], v[52:55]
	v_mfma_f32_16x16x32_bf16 v[44:47], v[160:163], v[192:195], v[44:47]
	v_mfma_f32_16x16x32_bf16 v[36:39], v[152:155], v[200:203], v[36:39]
	v_mfma_f32_16x16x32_bf16 v[28:31], v[160:163], v[200:203], v[28:31]
	v_mfma_f32_16x16x32_bf16 v[20:23], v[152:155], v[212:215], v[20:23]
	v_mfma_f32_16x16x32_bf16 v[12:15], v[160:163], v[212:215], v[12:15]
	v_mfma_f32_16x16x32_bf16 v[60:63], v[156:159], v[188:191], v[60:63]
	v_mfma_f32_16x16x32_bf16 v[56:59], v[164:167], v[188:191], v[56:59]
	v_mfma_f32_16x16x32_bf16 v[52:55], v[156:159], v[196:199], v[52:55]
	v_mfma_f32_16x16x32_bf16 v[44:47], v[164:167], v[196:199], v[44:47]
	v_mfma_f32_16x16x32_bf16 v[36:39], v[156:159], v[204:207], v[36:39]
	v_mfma_f32_16x16x32_bf16 v[28:31], v[164:167], v[204:207], v[28:31]
	v_mfma_f32_16x16x32_bf16 v[20:23], v[156:159], v[216:219], v[20:23]
	v_mfma_f32_16x16x32_bf16 v[12:15], v[164:167], v[216:219], v[12:15]
	v_mfma_f32_16x16x32_bf16 v[48:51], v[168:171], v[184:187], v[48:51]
	v_mfma_f32_16x16x32_bf16 v[40:43], v[176:179], v[184:187], v[40:43]
	v_mfma_f32_16x16x32_bf16 v[32:35], v[168:171], v[192:195], v[32:35]
	v_mfma_f32_16x16x32_bf16 v[24:27], v[176:179], v[192:195], v[24:27]
	v_mfma_f32_16x16x32_bf16 v[16:19], v[168:171], v[200:203], v[16:19]
	v_mfma_f32_16x16x32_bf16 v[8:11], v[176:179], v[200:203], v[8:11]
	v_mfma_f32_16x16x32_bf16 v[4:7], v[168:171], v[212:215], v[4:7]
	v_mfma_f32_16x16x32_bf16 v[0:3], v[176:179], v[212:215], v[0:3]
	v_mfma_f32_16x16x32_bf16 v[48:51], v[172:175], v[188:191], v[48:51]
	v_mfma_f32_16x16x32_bf16 v[40:43], v[180:183], v[188:191], v[40:43]
	v_mfma_f32_16x16x32_bf16 v[32:35], v[172:175], v[196:199], v[32:35]
	v_mfma_f32_16x16x32_bf16 v[24:27], v[180:183], v[196:199], v[24:27]
	v_mfma_f32_16x16x32_bf16 v[16:19], v[172:175], v[204:207], v[16:19]
	v_mfma_f32_16x16x32_bf16 v[8:11], v[180:183], v[204:207], v[8:11]
	v_mfma_f32_16x16x32_bf16 v[4:7], v[172:175], v[216:219], v[4:7]
	v_mfma_f32_16x16x32_bf16 v[0:3], v[180:183], v[216:219], v[0:3]
	s_barrier
	s_add_i32 s85, 0, 0x18000
	s_add_i32 s86, 0, 0x1c000
	v_add_u32_e32 v164, s85, v147
	v_add_u32_e32 v180, s86, v147
	ds_read_b128 v[152:155], v164
	ds_read_b128 v[156:159], v164 offset:1024
	ds_read_b128 v[160:163], v164 offset:2048
	ds_read_b128 v[164:167], v164 offset:3072
	ds_read_b128 v[168:171], v180
	ds_read_b128 v[172:175], v180 offset:1024
	ds_read_b128 v[176:179], v180 offset:2048
	ds_read_b128 v[180:183], v180 offset:3072
	s_add_u32 s30, s30, 0x40000
	s_addc_u32 s31, s31, 0
	s_mov_b32 m0, s51
	v_lshl_add_u64 v[224:225], s[30:31], 0, v[134:135]
	ds_read_b128 v[184:187], v151 offset:32768
	ds_read_b128 v[188:191], v151 offset:33792
	ds_read_b128 v[192:195], v151 offset:34816
	ds_read_b128 v[196:199], v151 offset:35840
	ds_read_b128 v[200:203], v151 offset:36864
	ds_read_b128 v[204:207], v151 offset:37888
	ds_read_b128 v[212:215], v151 offset:38912
	ds_read_b128 v[216:219], v151 offset:39936
	global_load_lds_dwordx4 v[224:225], off
	v_lshl_add_u64 v[224:225], s[30:31], 0, v[130:131]
	s_mov_b32 m0, s52
	s_nop 0
	global_load_lds_dwordx4 v[224:225], off
	s_waitcnt vmcnt(8)
	s_waitcnt lgkmcnt(0)
	s_barrier
	s_waitcnt lgkmcnt(0)
	v_mfma_f32_16x16x32_bf16 v[124:127], v[152:155], v[184:187], v[124:127]
	v_mfma_f32_16x16x32_bf16 v[120:123], v[160:163], v[184:187], v[120:123]
	v_mfma_f32_16x16x32_bf16 v[116:119], v[152:155], v[192:195], v[116:119]
	v_mfma_f32_16x16x32_bf16 v[108:111], v[160:163], v[192:195], v[108:111]
	v_mfma_f32_16x16x32_bf16 v[100:103], v[152:155], v[200:203], v[100:103]
	v_mfma_f32_16x16x32_bf16 v[92:95], v[160:163], v[200:203], v[92:95]
	v_mfma_f32_16x16x32_bf16 v[84:87], v[152:155], v[212:215], v[84:87]
	v_mfma_f32_16x16x32_bf16 v[76:79], v[160:163], v[212:215], v[76:79]
	v_mfma_f32_16x16x32_bf16 v[124:127], v[156:159], v[188:191], v[124:127]
	v_mfma_f32_16x16x32_bf16 v[120:123], v[164:167], v[188:191], v[120:123]
	v_mfma_f32_16x16x32_bf16 v[116:119], v[156:159], v[196:199], v[116:119]
	v_mfma_f32_16x16x32_bf16 v[108:111], v[164:167], v[196:199], v[108:111]
	v_mfma_f32_16x16x32_bf16 v[100:103], v[156:159], v[204:207], v[100:103]
	v_mfma_f32_16x16x32_bf16 v[92:95], v[164:167], v[204:207], v[92:95]
	v_mfma_f32_16x16x32_bf16 v[84:87], v[156:159], v[216:219], v[84:87]
	v_mfma_f32_16x16x32_bf16 v[76:79], v[164:167], v[216:219], v[76:79]
	v_mfma_f32_16x16x32_bf16 v[112:115], v[168:171], v[184:187], v[112:115]
	v_mfma_f32_16x16x32_bf16 v[104:107], v[176:179], v[184:187], v[104:107]
	v_mfma_f32_16x16x32_bf16 v[96:99], v[168:171], v[192:195], v[96:99]
	v_mfma_f32_16x16x32_bf16 v[88:91], v[176:179], v[192:195], v[88:91]
	v_mfma_f32_16x16x32_bf16 v[80:83], v[168:171], v[200:203], v[80:83]
	v_mfma_f32_16x16x32_bf16 v[72:75], v[176:179], v[200:203], v[72:75]
	v_mfma_f32_16x16x32_bf16 v[68:71], v[168:171], v[212:215], v[68:71]
	v_mfma_f32_16x16x32_bf16 v[64:67], v[176:179], v[212:215], v[64:67]
	v_mfma_f32_16x16x32_bf16 v[112:115], v[172:175], v[188:191], v[112:115]
	v_mfma_f32_16x16x32_bf16 v[104:107], v[180:183], v[188:191], v[104:107]
	v_mfma_f32_16x16x32_bf16 v[96:99], v[172:175], v[196:199], v[96:99]
	v_mfma_f32_16x16x32_bf16 v[88:91], v[180:183], v[196:199], v[88:91]
	v_mfma_f32_16x16x32_bf16 v[80:83], v[172:175], v[204:207], v[80:83]
	v_mfma_f32_16x16x32_bf16 v[72:75], v[180:183], v[204:207], v[72:75]
	v_mfma_f32_16x16x32_bf16 v[68:71], v[172:175], v[216:219], v[68:71]
	v_mfma_f32_16x16x32_bf16 v[64:67], v[180:183], v[216:219], v[64:67]
	s_barrier
; #define PG8_STAGE(bufoff, gbase, voff) do { _Pragma("unroll") for (int _i = 0; _i < 2; ++_i) \
;         __builtin_amdgcn_global_load_lds((const unsigned*)((const char*)(gbase) + (voff)[_i]), (PG8_LAS unsigned*)(lds + (bufoff) + ldsw + _i * 8192), 16, 0, 0); } while (0)
; #define PG8_LDA(dst, b, h) do { _Pragma("unroll") for (int m = 0; m < 4; ++m) _Pragma("unroll") for (int k = 0; k < 2; ++k) dst[m][k] = *(const PG8_LAS bf16x8*)(lds + PG8_SA(b, h) + aoff + m * 2048 + k * 1024); } while (0)
; #define PG8_MMA(ai, bj, At, Bt) do { __builtin_amdgcn_s_setprio(1); _Pragma("unroll") for (int m = 0; m < 4; ++m) _Pragma("unroll") for (int n = 0; n < 2; ++n) _Pragma("unroll") for (int k = 0; k < 2; ++k) \
;         acc[ai][bj][m][n] = __builtin_amdgcn_mfma_f32_16x16x32_bf16(Bt[n][k], At[m][k], acc[ai][bj][m][n], 0, 0, 0); __builtin_amdgcn_s_setprio(0); } while (0)
; #define PG8_WAIT_V(n) asm volatile("s_waitcnt vmcnt(" #n ")" ::: "memory")
; #define PG8_WAIT_L(n) asm volatile("s_waitcnt lgkmcnt(" #n ")" ::: "memory")
; #define PG8_BAR __builtin_amdgcn_s_barrier()
; #define PG8_SCHED __builtin_amdgcn_sched_barrier(0)
; template <class Epi, class Sched, bool ALIGN_EPI = false, bool SP2 = false, bool AROWS128 = false>
; __device__ __forceinline__ void gemm_phase(PG8_LAS unsigned char* lds, const Gemm g, const Sched& S, const Epi& E) {
;     ...
;         for (int t = 0; t < nt; t += 2) {
;             const bool last = (t == nt - 2);
;             const char* a1 = cA + (size_t)(t + 1) * kstep;
;             const char* a2 = last ? nA : cA + (size_t)(t + 2) * kstep; const char* b2 = last ? nB : cB + (size_t)(t + 2) * kstep;
;     ...
;             PG8_LDA(At, 1, 1); PG8_STAGE(PG8_SB(1, 0), b3, voffB); PG8_STAGE(PG8_SB(1, 1), b3 + hstep, voffB); PG8_STAGE(PG8_SA(1, 0), a3, voffA);
;             PG8_WAIT_V(8); PG8_WAIT_L(0); PG8_BAR; PG8_MMA(1, 0, At, B0); PG8_MMA(1, 1, At, B1); PG8_BAR; PG8_SCHED;
	s_add_i32 s30, s85, s3
	v_lshl_add_u64 v[144:145], v[144:145], 0, s[6:7]
	s_mov_b32 m0, s30
	ds_read_b128 v[184:187], v151 offset:49152
	ds_read_b128 v[188:191], v151 offset:50176
	ds_read_b128 v[192:195], v151 offset:51200
	ds_read_b128 v[196:199], v151 offset:52224
	ds_read_b128 v[200:203], v151 offset:53248
	ds_read_b128 v[204:207], v151 offset:54272
	ds_read_b128 v[212:215], v151 offset:55296
	ds_read_b128 v[216:219], v151 offset:56320
	global_load_lds_dwordx4 v[144:145], off
	s_add_i32 m0, s30, 0x2000
	s_add_u32 s28, s28, 0x40080
	v_lshl_add_u64 v[144:145], v[208:209], 0, s[6:7]
	s_addc_u32 s29, s29, 0
	s_add_i32 s30, s86, s3
	global_load_lds_dwordx4 v[144:145], off
	v_lshl_add_u64 v[144:145], s[28:29], 0, v[132:133]
	s_mov_b32 m0, s30
	s_nop 0
	global_load_lds_dwordx4 v[144:145], off
	v_lshl_add_u64 v[144:145], s[28:29], 0, v[128:129]
	s_add_i32 m0, s30, 0x2000
	s_nop 0
	global_load_lds_dwordx4 v[144:145], off
	v_lshl_add_u64 v[144:145], v[220:221], 0, s[6:7]
	s_mov_b32 m0, s58
	s_nop 0
	global_load_lds_dwordx4 v[144:145], off
	v_lshl_add_u64 v[144:145], v[222:223], 0, s[6:7]
	s_mov_b32 m0, s59
	s_nop 0
	global_load_lds_dwordx4 v[144:145], off
	s_waitcnt vmcnt(8)
	s_waitcnt lgkmcnt(0)
	s_barrier
	s_waitcnt lgkmcnt(0)
	v_mfma_f32_16x16x32_bf16 v[60:63], v[152:155], v[184:187], v[60:63]
	v_mfma_f32_16x16x32_bf16 v[56:59], v[160:163], v[184:187], v[56:59]
	v_mfma_f32_16x16x32_bf16 v[52:55], v[152:155], v[192:195], v[52:55]
	v_mfma_f32_16x16x32_bf16 v[44:47], v[160:163], v[192:195], v[44:47]
	v_mfma_f32_16x16x32_bf16 v[36:39], v[152:155], v[200:203], v[36:39]
	v_mfma_f32_16x16x32_bf16 v[28:31], v[160:163], v[200:203], v[28:31]
	v_mfma_f32_16x16x32_bf16 v[20:23], v[152:155], v[212:215], v[20:23]
	v_mfma_f32_16x16x32_bf16 v[12:15], v[160:163], v[212:215], v[12:15]
	v_mfma_f32_16x16x32_bf16 v[60:63], v[156:159], v[188:191], v[60:63]
	v_mfma_f32_16x16x32_bf16 v[56:59], v[164:167], v[188:191], v[56:59]
	v_mfma_f32_16x16x32_bf16 v[52:55], v[156:159], v[196:199], v[52:55]
	v_mfma_f32_16x16x32_bf16 v[44:47], v[164:167], v[196:199], v[44:47]
	v_mfma_f32_16x16x32_bf16 v[36:39], v[156:159], v[204:207], v[36:39]
	v_mfma_f32_16x16x32_bf16 v[28:31], v[164:167], v[204:207], v[28:31]
	v_mfma_f32_16x16x32_bf16 v[20:23], v[156:159], v[216:219], v[20:23]
	v_mfma_f32_16x16x32_bf16 v[12:15], v[164:167], v[216:219], v[12:15]
	v_mfma_f32_16x16x32_bf16 v[48:51], v[168:171], v[184:187], v[48:51]
	v_mfma_f32_16x16x32_bf16 v[40:43], v[176:179], v[184:187], v[40:43]
	v_mfma_f32_16x16x32_bf16 v[32:35], v[168:171], v[192:195], v[32:35]
	v_mfma_f32_16x16x32_bf16 v[24:27], v[176:179], v[192:195], v[24:27]
	v_mfma_f32_16x16x32_bf16 v[16:19], v[168:171], v[200:203], v[16:19]
	v_mfma_f32_16x16x32_bf16 v[8:11], v[176:179], v[200:203], v[8:11]
	v_mfma_f32_16x16x32_bf16 v[4:7], v[168:171], v[212:215], v[4:7]
	v_mfma_f32_16x16x32_bf16 v[0:3], v[176:179], v[212:215], v[0:3]
	v_mfma_f32_16x16x32_bf16 v[48:51], v[172:175], v[188:191], v[48:51]
	v_mfma_f32_16x16x32_bf16 v[40:43], v[180:183], v[188:191], v[40:43]
	v_mfma_f32_16x16x32_bf16 v[32:35], v[172:175], v[196:199], v[32:35]
	v_mfma_f32_16x16x32_bf16 v[24:27], v[180:183], v[196:199], v[24:27]
	v_mfma_f32_16x16x32_bf16 v[16:19], v[172:175], v[204:207], v[16:19]
	v_mfma_f32_16x16x32_bf16 v[8:11], v[180:183], v[204:207], v[8:11]
	v_mfma_f32_16x16x32_bf16 v[4:7], v[172:175], v[216:219], v[4:7]
	v_mfma_f32_16x16x32_bf16 v[0:3], v[180:183], v[216:219], v[0:3]
	s_barrier
	s_add_i32 s84, s84, 2
	s_add_u32 s26, s26, 0x100
	s_addc_u32 s27, s27, 0
	s_add_u32 s82, s82, 0x100
	s_addc_u32 s83, s83, 0
	s_cmp_gt_u32 s84, 13
	s_cbranch_scc0 .LBB0_489
	s_and_b64 vcc, exec, s[8:9]
	s_cbranch_vccz .LBB0_492
	s_barrier
; __device__ __forceinline__ unsigned cvt_pk_bf16(float lo, float hi) { unsigned r; asm volatile("v_cvt_pk_bf16_f32 %0, %1, %2" : "=v"(r) : "v"(lo), "v"(hi)); return r; }
; #define PG8_WAIT_V(n) asm volatile("s_waitcnt vmcnt(" #n ")" ::: "memory")
; #define PG8_BAR __builtin_amdgcn_s_barrier()
;     __device__ __forceinline__ void operator()(const f32x4 (&acc)[2][2][4][2], const Unit& u, int wr, int wc, int fr, int fq) const {
;         const int row0 = u.pm * BM + wr * 64 + fr; const int col0 = u.pn * BM + wc * 32 + 8 * fq; const float sc = (u.pn < scale_tiles) ? scale0 : 1.f;
; #pragma unroll
;         for (int ai = 0; ai < 2; ++ai)
; #pragma unroll
;             for (int m = 0; m < 4; ++m) { bf16_t* rowp = O + (size_t)(row0 + ai * HALF + m * 16) * ldc + col0;
; #pragma unroll
;                 for (int bj = 0; bj < 2; ++bj) { const f32x4 v0 = acc[ai][bj][m][0] * sc, v1 = acc[ai][bj][m][1] * sc;
;                     u32x4 w; w.x = cvt_pk_bf16(v0[0], v0[1]); w.y = cvt_pk_bf16(v0[2], v0[3]); w.z = cvt_pk_bf16(v1[0], v1[1]); w.w = cvt_pk_bf16(v1[2], v1[3]);
;                     __builtin_nontemporal_store(w, (u32x4*)(rowp + bj * HALF)); } }
; template <class Epi, class Sched, bool ALIGN_EPI = false, bool SP2 = false, bool AROWS128 = false>
; __device__ __forceinline__ void gemm_phase(PG8_LAS unsigned char* lds, const Gemm g, const Sched& S, const Epi& E) {
;     ...
;     PG8_WAIT_V(0);
;     if constexpr (!ALIGN_EPI) { if (wr == 0) PG8_BAR; }
;     PG8_BAR;
.LBB0_492:
	v_lshl_add_u32 v152, s24, 8, v146
	v_lshl_or_b32 v144, s81, 8, v148
	v_ashrrev_i32_e32 v153, 31, v152
	v_ashrrev_i32_e32 v145, 31, v144
	v_lshlrev_b64 v[154:155], 11, v[152:153]
	v_lshl_add_u64 v[154:155], s[44:45], 0, v[154:155]
	v_lshlrev_b64 v[156:157], 1, v[144:145]
	v_lshl_add_u64 v[144:145], v[154:155], 0, v[156:157]
	v_cvt_pk_bf16_f32 v124, v124, v125
	v_cvt_pk_bf16_f32 v125, v126, v127
	v_cvt_pk_bf16_f32 v126, v120, v121
	v_cvt_pk_bf16_f32 v127, v122, v123
	global_store_dwordx4 v[144:145], v[124:127], off nt
	v_cvt_pk_bf16_f32 v112, v112, v113
	v_cvt_pk_bf16_f32 v113, v114, v115
	v_cvt_pk_bf16_f32 v114, v104, v105
	v_or_b32_e32 v104, 16, v152
	v_ashrrev_i32_e32 v105, 31, v104
	v_lshlrev_b64 v[104:105], 11, v[104:105]
	v_lshl_add_u64 v[104:105], s[44:45], 0, v[104:105]
	v_cvt_pk_bf16_f32 v115, v106, v107
	global_store_dwordx4 v[144:145], v[112:115], off offset:256 nt
	s_mov_b32 s13, 0x40000
	s_mov_b64 s[26:27], 0x40000
	v_lshl_add_u64 v[112:113], v[104:105], 0, v[156:157]
	v_cvt_pk_bf16_f32 v104, v116, v117
	v_cvt_pk_bf16_f32 v105, v118, v119
	v_cvt_pk_bf16_f32 v106, v108, v109
	v_cvt_pk_bf16_f32 v107, v110, v111
	global_store_dwordx4 v[112:113], v[104:107], off nt
	v_cvt_pk_bf16_f32 v96, v96, v97
	v_cvt_pk_bf16_f32 v97, v98, v99
	v_cvt_pk_bf16_f32 v98, v88, v89
	v_or_b32_e32 v88, 32, v152
	v_ashrrev_i32_e32 v89, 31, v88
	v_lshlrev_b64 v[88:89], 11, v[88:89]
	v_lshl_add_u64 v[88:89], s[44:45], 0, v[88:89]
	v_cvt_pk_bf16_f32 v99, v90, v91
	global_store_dwordx4 v[112:113], v[96:99], off offset:256 nt
	s_nop 1
	v_lshl_add_u64 v[96:97], v[88:89], 0, v[156:157]
	v_cvt_pk_bf16_f32 v88, v100, v101
	v_cvt_pk_bf16_f32 v89, v102, v103
	v_cvt_pk_bf16_f32 v90, v92, v93
	v_cvt_pk_bf16_f32 v91, v94, v95
	global_store_dwordx4 v[96:97], v[88:91], off nt
	v_cvt_pk_bf16_f32 v80, v80, v81
	v_cvt_pk_bf16_f32 v81, v82, v83
	v_cvt_pk_bf16_f32 v82, v72, v73
	v_or_b32_e32 v72, 48, v152
	v_ashrrev_i32_e32 v73, 31, v72
	v_lshlrev_b64 v[72:73], 11, v[72:73]
	v_lshl_add_u64 v[72:73], s[44:45], 0, v[72:73]
	v_cvt_pk_bf16_f32 v83, v74, v75
	global_store_dwordx4 v[96:97], v[80:83], off offset:256 nt
	s_nop 1
	v_lshl_add_u64 v[80:81], v[72:73], 0, v[156:157]
	v_cvt_pk_bf16_f32 v72, v84, v85
	v_cvt_pk_bf16_f32 v73, v86, v87
	v_cvt_pk_bf16_f32 v74, v76, v77
	v_cvt_pk_bf16_f32 v75, v78, v79
	global_store_dwordx4 v[80:81], v[72:75], off nt
	v_cvt_pk_bf16_f32 v68, v68, v69
	v_cvt_pk_bf16_f32 v69, v70, v71
	v_cvt_pk_bf16_f32 v70, v64, v65
	v_cvt_pk_bf16_f32 v71, v66, v67
	global_store_dwordx4 v[80:81], v[68:71], off offset:256 nt
	v_cvt_pk_bf16_f32 v60, v60, v61
	v_cvt_pk_bf16_f32 v61, v62, v63
	v_cvt_pk_bf16_f32 v62, v56, v57
	v_add_co_u32_e32 v56, vcc, s13, v144
	v_lshl_add_u64 v[64:65], v[144:145], 0, s[26:27]
	s_nop 0
	v_addc_co_u32_e32 v57, vcc, 0, v145, vcc
	s_mov_b32 s13, 0x48000
	v_cvt_pk_bf16_f32 v63, v58, v59
	global_store_dwordx4 v[56:57], v[60:63], off nt
	v_cvt_pk_bf16_f32 v48, v48, v49
	v_cvt_pk_bf16_f32 v49, v50, v51
	v_cvt_pk_bf16_f32 v50, v40, v41
	v_cvt_pk_bf16_f32 v51, v42, v43
	global_store_dwordx4 v[64:65], v[48:51], off offset:256 nt
	s_mov_b64 s[26:27], 0x48000
	v_cvt_pk_bf16_f32 v40, v52, v53
	v_cvt_pk_bf16_f32 v41, v54, v55
	v_cvt_pk_bf16_f32 v42, v44, v45
	v_add_co_u32_e32 v44, vcc, s13, v144
	v_lshl_add_u64 v[48:49], v[144:145], 0, s[26:27]
	s_nop 0
	v_addc_co_u32_e32 v45, vcc, 0, v145, vcc
	s_mov_b32 s13, 0x50000
	v_cvt_pk_bf16_f32 v43, v46, v47
	global_store_dwordx4 v[44:45], v[40:43], off nt
	v_cvt_pk_bf16_f32 v32, v32, v33
	v_cvt_pk_bf16_f32 v33, v34, v35
	v_cvt_pk_bf16_f32 v34, v24, v25
	v_cvt_pk_bf16_f32 v35, v26, v27
	global_store_dwordx4 v[48:49], v[32:35], off offset:256 nt
	s_mov_b64 s[26:27], 0x50000
	v_cvt_pk_bf16_f32 v24, v36, v37
	v_cvt_pk_bf16_f32 v25, v38, v39
	v_cvt_pk_bf16_f32 v26, v28, v29
	v_add_co_u32_e32 v28, vcc, s13, v144
	v_lshl_add_u64 v[32:33], v[144:145], 0, s[26:27]
	s_nop 0
	v_addc_co_u32_e32 v29, vcc, 0, v145, vcc
	v_cvt_pk_bf16_f32 v27, v30, v31
	global_store_dwordx4 v[28:29], v[24:27], off nt
	v_cvt_pk_bf16_f32 v16, v16, v17
	v_cvt_pk_bf16_f32 v17, v18, v19
	v_cvt_pk_bf16_f32 v18, v8, v9
	v_cvt_pk_bf16_f32 v19, v10, v11
	global_store_dwordx4 v[32:33], v[16:19], off offset:256 nt
	v_cvt_pk_bf16_f32 v8, v20, v21
	v_cvt_pk_bf16_f32 v9, v22, v23
	v_cvt_pk_bf16_f32 v10, v12, v13
	v_add_co_u32_e32 v12, vcc, s80, v144
	s_nop 0
	v_lshl_add_u64 v[16:17], v[144:145], 0, s[10:11]
	v_addc_co_u32_e32 v13, vcc, 0, v145, vcc
	s_andn2_b64 vcc, exec, s[0:1]
	s_mov_b64 s[0:1], -1
	v_cvt_pk_bf16_f32 v11, v14, v15
	global_store_dwordx4 v[12:13], v[8:11], off nt
	v_cvt_pk_bf16_f32 v4, v4, v5
	v_cvt_pk_bf16_f32 v5, v6, v7
	v_cvt_pk_bf16_f32 v6, v0, v1
	v_cvt_pk_bf16_f32 v7, v2, v3
	global_store_dwordx4 v[16:17], v[4:7], off offset:256 nt
	s_cbranch_vccnz .LBB0_485
	s_andn2_b64 vcc, exec, s[4:5]
	s_cbranch_vccnz .LBB0_484
	s_barrier
	s_branch .LBB0_484
.LBB0_495:
	s_setprio 0
	s_waitcnt vmcnt(0)
	s_barrier
.LBB0_496:
	s_waitcnt vmcnt(0)
	s_waitcnt vmcnt(0)
	s_barrier
	s_and_saveexec_b64 s[0:1], s[22:23]
	s_cbranch_execz .LBB0_548
	s_add_i32 s3, 0, 0x20020
	v_mov_b32_e32 v0, s3
	s_waitcnt vmcnt(0) expcnt(0) lgkmcnt(0)
	ds_read_b32 v2, v0
	s_add_i32 s3, 0, 0x20024
	v_mov_b32_e32 v0, s3
	ds_read_b32 v0, v0
	s_waitcnt lgkmcnt(1)
	v_cmp_ne_u32_e32 vcc, 0, v2
	s_cbranch_vccnz .LBB0_512
	s_add_u32 s4, s70, 0x1200
	s_addc_u32 s5, s71, 0
	s_add_u32 s6, s70, 0x1400
	s_addc_u32 s7, s71, 0
	s_add_u32 s8, s70, 0x1500
	s_addc_u32 s9, s71, 0
	s_add_u32 s10, s70, 0x1600
	s_addc_u32 s11, s71, 0
	s_add_u32 s12, s70, 0x1700
	s_addc_u32 s13, s71, 0
	s_add_u32 s14, s70, 0x1800
	s_addc_u32 s15, s71, 0
	s_add_u32 s16, s70, 0x1900
	s_addc_u32 s17, s71, 0
	s_add_u32 s18, s70, 0x1a00
	s_addc_u32 s19, s71, 0
	s_add_u32 s20, s70, 0x1b00
	s_addc_u32 s21, s71, 0
	s_add_u32 s24, s70, 0x1c00
	s_addc_u32 s25, s71, 0
	s_add_u32 s26, s70, 0x1d00
	s_addc_u32 s27, s71, 0
	s_add_u32 s28, s70, 0x1e00
	s_addc_u32 s29, s71, 0
	s_add_u32 s30, s70, 0x1f00
	s_addc_u32 s31, s71, 0
	s_add_u32 s50, s70, 0x2000
	s_addc_u32 s51, s71, 0
	s_add_u32 s52, s70, 0x2100
	s_addc_u32 s53, s71, 0
	s_add_u32 s58, s70, 0x2200
	v_readlane_b32 s3, v255, 8
	s_addc_u32 s59, s71, 0
	s_mul_i32 s3, s75, s3
	s_add_u32 s64, s70, 0x2300
	s_mul_i32 s3, s3, s74
	s_addc_u32 s65, s71, 0
	s_mov_b32 s33, 1
	v_mov_b32_e32 v16, 0
	s_branch .LBB0_500

; #define PG8_STAGE(bufoff, gbase, voff) do { _Pragma("unroll") for (int _i = 0; _i < 2; ++_i) \
;         __builtin_amdgcn_global_load_lds((const unsigned*)((const char*)(gbase) + (voff)[_i]), (PG8_LAS unsigned*)(lds + (bufoff) + ldsw + _i * 8192), 16, 0, 0); } while (0)
; #define PG8_LDA(dst, b, h) do { _Pragma("unroll") for (int m = 0; m < 4; ++m) _Pragma("unroll") for (int k = 0; k < 2; ++k) dst[m][k] = *(const PG8_LAS bf16x8*)(lds + PG8_SA(b, h) + aoff + m * 2048 + k * 1024); } while (0)
; #define PG8_LDB(dst, b, h) do { _Pragma("unroll") for (int n = 0; n < 2; ++n) _Pragma("unroll") for (int k = 0; k < 2; ++k) dst[n][k] = *(const PG8_LAS bf16x8*)(lds + PG8_SB(b, h) + boff + n * 2048 + k * 1024); } while (0)
; #define PG8_MMA(ai, bj, At, Bt) do { __builtin_amdgcn_s_setprio(1); _Pragma("unroll") for (int m = 0; m < 4; ++m) _Pragma("unroll") for (int n = 0; n < 2; ++n) _Pragma("unroll") for (int k = 0; k < 2; ++k) \
;         acc[ai][bj][m][n] = __builtin_amdgcn_mfma_f32_16x16x32_bf16(Bt[n][k], At[m][k], acc[ai][bj][m][n], 0, 0, 0); __builtin_amdgcn_s_setprio(0); } while (0)
; #define PG8_WAIT_V(n) asm volatile("s_waitcnt vmcnt(" #n ")" ::: "memory")
; #define PG8_WAIT_L(n) asm volatile("s_waitcnt lgkmcnt(" #n ")" ::: "memory")
; template <class Epi, class Sched, bool ALIGN_EPI = false, bool SP2 = false, bool AROWS128 = false>
; __device__ __forceinline__ void gemm_phase(PG8_LAS unsigned char* lds, const Gemm g, const Sched& S, const Epi& E) {
;     ...
;             const bool last = (t == nt - 2);
;             const char* a1 = cA + (size_t)(t + 1) * kstep;
;             const char* a2 = last ? nA : cA + (size_t)(t + 2) * kstep; const char* b2 = last ? nB : cB + (size_t)(t + 2) * kstep;
;             const char* a3 = a2 + kstep; const char* b3 = b2 + kstep;
;             if (last && has_next) S.a_ready(nxt);
;             if constexpr (SP2) {
;             PG8_LDB(B0, 0, 0); PG8_LDB(B1, 0, 1); PG8_SCHED; PG8_LDA(At, 0, 0); PG8_STAGE(PG8_SA(1, 1), a1 + hstepA, voffA);
;             PG8_WAIT_V(8); PG8_WAIT_L(0); PG8_BAR; PG8_MMA(0, 0, At, B0); PG8_MMA(0, 1, At, B1); PG8_BAR; PG8_SCHED;
;             PG8_LDA(At, 0, 1); PG8_STAGE(PG8_SB(0, 0), b2, voffB); PG8_STAGE(PG8_SB(0, 1), b2 + hstep, voffB); PG8_STAGE(PG8_SA(0, 0), a2, voffA);
;             PG8_WAIT_V(8); PG8_WAIT_L(0); PG8_BAR; PG8_MMA(1, 0, At, B0); PG8_MMA(1, 1, At, B1); PG8_BAR; PG8_SCHED;
.LBB0_626:
	ds_read_b128 v[72:75], v207
	ds_read_b128 v[76:79], v207 offset:1024
	ds_read_b128 v[80:83], v207 offset:2048
	ds_read_b128 v[84:87], v207 offset:3072
	ds_read_b128 v[88:91], v208
	ds_read_b128 v[92:95], v208 offset:1024
	ds_read_b128 v[96:99], v208 offset:2048
	ds_read_b128 v[100:103], v208 offset:3072
	s_add_u32 s20, s18, 0xfffe0080
	s_addc_u32 s21, s19, -1
	s_cmp_eq_u32 s73, 12
	s_cselect_b32 s81, s17, s21
	s_cselect_b32 s80, s33, s20
	s_cselect_b32 s21, s53, s72
	s_cselect_b32 s20, s55, s65
	v_lshl_add_u64 v[220:221], s[18:19], 0, v[168:169]
	s_add_i32 m0, s84, 0xc000
	ds_read_b128 v[176:179], v209
	ds_read_b128 v[180:183], v209 offset:1024
	ds_read_b128 v[184:187], v209 offset:2048
	ds_read_b128 v[188:191], v209 offset:3072
	ds_read_b128 v[192:195], v209 offset:4096
	ds_read_b128 v[196:199], v209 offset:5120
	ds_read_b128 v[212:215], v209 offset:6144
	ds_read_b128 v[216:219], v209 offset:7168
	global_load_lds_dwordx4 v[220:221], off
	v_lshl_add_u64 v[220:221], s[18:19], 0, v[170:171]
	s_add_i32 m0, s84, 0xe000
	s_nop 0
	global_load_lds_dwordx4 v[220:221], off
	s_waitcnt vmcnt(8)
	s_waitcnt lgkmcnt(0)
	s_barrier
	s_waitcnt lgkmcnt(0)
	v_mfma_f32_16x16x32_bf16 v[36:39], v[72:75], v[176:179], v[36:39]
	v_mfma_f32_16x16x32_bf16 v[28:31], v[80:83], v[176:179], v[28:31]
	v_mfma_f32_16x16x32_bf16 v[140:143], v[72:75], v[184:187], v[140:143]
	v_mfma_f32_16x16x32_bf16 v[136:139], v[80:83], v[184:187], v[136:139]
	v_mfma_f32_16x16x32_bf16 v[124:127], v[72:75], v[192:195], v[124:127]
	v_mfma_f32_16x16x32_bf16 v[120:123], v[80:83], v[192:195], v[120:123]
	v_mfma_f32_16x16x32_bf16 v[108:111], v[72:75], v[212:215], v[108:111]
	v_mfma_f32_16x16x32_bf16 v[104:107], v[80:83], v[212:215], v[104:107]
	v_mfma_f32_16x16x32_bf16 v[36:39], v[76:79], v[180:183], v[36:39]
	v_mfma_f32_16x16x32_bf16 v[28:31], v[84:87], v[180:183], v[28:31]
	v_mfma_f32_16x16x32_bf16 v[140:143], v[76:79], v[188:191], v[140:143]
	v_mfma_f32_16x16x32_bf16 v[136:139], v[84:87], v[188:191], v[136:139]
	v_mfma_f32_16x16x32_bf16 v[124:127], v[76:79], v[196:199], v[124:127]
	v_mfma_f32_16x16x32_bf16 v[120:123], v[84:87], v[196:199], v[120:123]
	v_mfma_f32_16x16x32_bf16 v[108:111], v[76:79], v[216:219], v[108:111]
	v_mfma_f32_16x16x32_bf16 v[104:107], v[84:87], v[216:219], v[104:107]
	v_mfma_f32_16x16x32_bf16 v[156:159], v[88:91], v[176:179], v[156:159]
	v_mfma_f32_16x16x32_bf16 v[152:155], v[96:99], v[176:179], v[152:155]
	v_mfma_f32_16x16x32_bf16 v[148:151], v[88:91], v[184:187], v[148:151]
	v_mfma_f32_16x16x32_bf16 v[144:147], v[96:99], v[184:187], v[144:147]
	v_mfma_f32_16x16x32_bf16 v[132:135], v[88:91], v[192:195], v[132:135]
	v_mfma_f32_16x16x32_bf16 v[128:131], v[96:99], v[192:195], v[128:131]
	v_mfma_f32_16x16x32_bf16 v[116:119], v[88:91], v[212:215], v[116:119]
	v_mfma_f32_16x16x32_bf16 v[112:115], v[96:99], v[212:215], v[112:115]
	v_mfma_f32_16x16x32_bf16 v[156:159], v[92:95], v[180:183], v[156:159]
	v_mfma_f32_16x16x32_bf16 v[152:155], v[100:103], v[180:183], v[152:155]
	v_mfma_f32_16x16x32_bf16 v[148:151], v[92:95], v[188:191], v[148:151]
	v_mfma_f32_16x16x32_bf16 v[144:147], v[100:103], v[188:191], v[144:147]
	v_mfma_f32_16x16x32_bf16 v[132:135], v[92:95], v[196:199], v[132:135]
	v_mfma_f32_16x16x32_bf16 v[128:131], v[100:103], v[196:199], v[128:131]
	v_mfma_f32_16x16x32_bf16 v[116:119], v[92:95], v[216:219], v[116:119]
	v_mfma_f32_16x16x32_bf16 v[112:115], v[100:103], v[216:219], v[112:115]
	s_barrier
	s_add_i32 s76, s3, s35
	v_lshl_add_u64 v[220:221], s[20:21], 0, v[162:163]
	s_mov_b32 m0, s76
	ds_read_b128 v[176:179], v209 offset:16384
	ds_read_b128 v[180:183], v209 offset:17408
	ds_read_b128 v[184:187], v209 offset:18432
	ds_read_b128 v[188:191], v209 offset:19456
	ds_read_b128 v[192:195], v209 offset:20480
	ds_read_b128 v[196:199], v209 offset:21504
	ds_read_b128 v[212:215], v209 offset:22528
	ds_read_b128 v[216:219], v209 offset:23552
	global_load_lds_dwordx4 v[220:221], off
	s_add_i32 m0, s76, 0x2000
	s_add_u32 s76, s20, 0x40000
	v_lshl_add_u64 v[222:223], s[20:21], 0, v[166:167]
	s_addc_u32 s77, s21, 0
	s_add_i32 s82, s95, s35
	global_load_lds_dwordx4 v[222:223], off
	v_lshl_add_u64 v[224:225], s[76:77], 0, v[162:163]
	s_mov_b32 m0, s82
	v_lshl_add_u64 v[226:227], s[80:81], 0, v[164:165]
	global_load_lds_dwordx4 v[224:225], off
	v_lshl_add_u64 v[224:225], s[76:77], 0, v[166:167]
	s_add_i32 m0, s82, 0x2000
	s_nop 0
	global_load_lds_dwordx4 v[224:225], off
	v_lshl_add_u64 v[224:225], s[80:81], 0, v[160:161]
	s_mov_b32 m0, s84
	s_nop 0
	global_load_lds_dwordx4 v[224:225], off
	s_mov_b32 m0, s85
	s_nop 0
	global_load_lds_dwordx4 v[226:227], off
	s_waitcnt vmcnt(8)
	s_waitcnt lgkmcnt(0)
	s_barrier
; #define PG8_STAGE(bufoff, gbase, voff) do { _Pragma("unroll") for (int _i = 0; _i < 2; ++_i) \
;         __builtin_amdgcn_global_load_lds((const unsigned*)((const char*)(gbase) + (voff)[_i]), (PG8_LAS unsigned*)(lds + (bufoff) + ldsw + _i * 8192), 16, 0, 0); } while (0)
; #define PG8_LDA(dst, b, h) do { _Pragma("unroll") for (int m = 0; m < 4; ++m) _Pragma("unroll") for (int k = 0; k < 2; ++k) dst[m][k] = *(const PG8_LAS bf16x8*)(lds + PG8_SA(b, h) + aoff + m * 2048 + k * 1024); } while (0)
; #define PG8_LDB(dst, b, h) do { _Pragma("unroll") for (int n = 0; n < 2; ++n) _Pragma("unroll") for (int k = 0; k < 2; ++k) dst[n][k] = *(const PG8_LAS bf16x8*)(lds + PG8_SB(b, h) + boff + n * 2048 + k * 1024); } while (0)
; #define PG8_MMA(ai, bj, At, Bt) do { __builtin_amdgcn_s_setprio(1); _Pragma("unroll") for (int m = 0; m < 4; ++m) _Pragma("unroll") for (int n = 0; n < 2; ++n) _Pragma("unroll") for (int k = 0; k < 2; ++k) \
;         acc[ai][bj][m][n] = __builtin_amdgcn_mfma_f32_16x16x32_bf16(Bt[n][k], At[m][k], acc[ai][bj][m][n], 0, 0, 0); __builtin_amdgcn_s_setprio(0); } while (0)
; #define PG8_WAIT_V(n) asm volatile("s_waitcnt vmcnt(" #n ")" ::: "memory")
; #define PG8_WAIT_L(n) asm volatile("s_waitcnt lgkmcnt(" #n ")" ::: "memory")
; #define PG8_BAR __builtin_amdgcn_s_barrier()
; #define PG8_SCHED __builtin_amdgcn_sched_barrier(0)
; template <class Epi, class Sched, bool ALIGN_EPI = false, bool SP2 = false, bool AROWS128 = false>
; __device__ __forceinline__ void gemm_phase(PG8_LAS unsigned char* lds, const Gemm g, const Sched& S, const Epi& E) {
;     ...
;             PG8_WAIT_V(8); PG8_WAIT_L(0); PG8_BAR; PG8_MMA(1, 0, At, B0); PG8_MMA(1, 1, At, B1); PG8_BAR; PG8_SCHED;
;             PG8_LDB(B0, 1, 0); PG8_LDB(B1, 1, 1); PG8_SCHED; PG8_LDA(At, 1, 0); PG8_STAGE(PG8_SA(0, 1), a2 + hstepA, voffA);
;             PG8_WAIT_V(8); PG8_WAIT_L(0); PG8_BAR; PG8_MMA(0, 0, At, B0); PG8_MMA(0, 1, At, B1); PG8_BAR; PG8_SCHED;
	s_waitcnt lgkmcnt(0)
	v_mfma_f32_16x16x32_bf16 v[60:63], v[72:75], v[176:179], v[60:63]
	v_mfma_f32_16x16x32_bf16 v[56:59], v[80:83], v[176:179], v[56:59]
	v_mfma_f32_16x16x32_bf16 v[44:47], v[72:75], v[184:187], v[44:47]
	v_mfma_f32_16x16x32_bf16 v[40:43], v[80:83], v[184:187], v[40:43]
	v_mfma_f32_16x16x32_bf16 v[20:23], v[72:75], v[192:195], v[20:23]
	v_mfma_f32_16x16x32_bf16 v[16:19], v[80:83], v[192:195], v[16:19]
	v_mfma_f32_16x16x32_bf16 v[12:15], v[72:75], v[212:215], v[12:15]
	v_mfma_f32_16x16x32_bf16 v[8:11], v[80:83], v[212:215], v[8:11]
	v_mfma_f32_16x16x32_bf16 v[60:63], v[76:79], v[180:183], v[60:63]
	v_mfma_f32_16x16x32_bf16 v[56:59], v[84:87], v[180:183], v[56:59]
	v_mfma_f32_16x16x32_bf16 v[44:47], v[76:79], v[188:191], v[44:47]
	v_mfma_f32_16x16x32_bf16 v[40:43], v[84:87], v[188:191], v[40:43]
	v_mfma_f32_16x16x32_bf16 v[20:23], v[76:79], v[196:199], v[20:23]
	v_mfma_f32_16x16x32_bf16 v[16:19], v[84:87], v[196:199], v[16:19]
	v_mfma_f32_16x16x32_bf16 v[12:15], v[76:79], v[216:219], v[12:15]
	v_mfma_f32_16x16x32_bf16 v[8:11], v[84:87], v[216:219], v[8:11]
	v_mfma_f32_16x16x32_bf16 v[68:71], v[88:91], v[176:179], v[68:71]
	v_mfma_f32_16x16x32_bf16 v[64:67], v[96:99], v[176:179], v[64:67]
	v_mfma_f32_16x16x32_bf16 v[52:55], v[88:91], v[184:187], v[52:55]
	v_mfma_f32_16x16x32_bf16 v[48:51], v[96:99], v[184:187], v[48:51]
	v_mfma_f32_16x16x32_bf16 v[32:35], v[88:91], v[192:195], v[32:35]
	v_mfma_f32_16x16x32_bf16 v[24:27], v[96:99], v[192:195], v[24:27]
	v_mfma_f32_16x16x32_bf16 v[4:7], v[88:91], v[212:215], v[4:7]
	v_mfma_f32_16x16x32_bf16 v[0:3], v[96:99], v[212:215], v[0:3]
	v_mfma_f32_16x16x32_bf16 v[68:71], v[92:95], v[180:183], v[68:71]
	v_mfma_f32_16x16x32_bf16 v[64:67], v[100:103], v[180:183], v[64:67]
	v_mfma_f32_16x16x32_bf16 v[52:55], v[92:95], v[188:191], v[52:55]
	v_mfma_f32_16x16x32_bf16 v[48:51], v[100:103], v[188:191], v[48:51]
	v_mfma_f32_16x16x32_bf16 v[32:35], v[92:95], v[196:199], v[32:35]
	v_mfma_f32_16x16x32_bf16 v[24:27], v[100:103], v[196:199], v[24:27]
	v_mfma_f32_16x16x32_bf16 v[4:7], v[92:95], v[216:219], v[4:7]
	v_mfma_f32_16x16x32_bf16 v[0:3], v[100:103], v[216:219], v[0:3]
	s_barrier
	s_add_i32 s82, 0, 0x18000
	s_add_i32 s83, 0, 0x1c000
	v_add_u32_e32 v84, s82, v200
	v_add_u32_e32 v100, s83, v200
	ds_read_b128 v[72:75], v84
	ds_read_b128 v[76:79], v84 offset:1024
	ds_read_b128 v[80:83], v84 offset:2048
	ds_read_b128 v[84:87], v84 offset:3072
	ds_read_b128 v[88:91], v100
	ds_read_b128 v[92:95], v100 offset:1024
	ds_read_b128 v[96:99], v100 offset:2048
	ds_read_b128 v[100:103], v100 offset:3072
	s_add_u32 s76, s80, 0x20000
	s_addc_u32 s77, s81, 0
	s_mov_b32 m0, s86
	v_lshl_add_u64 v[228:229], s[76:77], 0, v[160:161]
	ds_read_b128 v[176:179], v209 offset:32768
	ds_read_b128 v[180:183], v209 offset:33792
	ds_read_b128 v[184:187], v209 offset:34816
	ds_read_b128 v[188:191], v209 offset:35840
	ds_read_b128 v[192:195], v209 offset:36864
	ds_read_b128 v[196:199], v209 offset:37888
	ds_read_b128 v[212:215], v209 offset:38912
	ds_read_b128 v[216:219], v209 offset:39936
	global_load_lds_dwordx4 v[228:229], off
	v_lshl_add_u64 v[228:229], s[76:77], 0, v[164:165]
	s_mov_b32 m0, s87
	s_nop 0
	global_load_lds_dwordx4 v[228:229], off
	s_waitcnt vmcnt(8)
	s_waitcnt lgkmcnt(0)
	s_barrier
	s_waitcnt lgkmcnt(0)
	v_mfma_f32_16x16x32_bf16 v[36:39], v[72:75], v[176:179], v[36:39]
	v_mfma_f32_16x16x32_bf16 v[28:31], v[80:83], v[176:179], v[28:31]
	v_mfma_f32_16x16x32_bf16 v[140:143], v[72:75], v[184:187], v[140:143]
	v_mfma_f32_16x16x32_bf16 v[136:139], v[80:83], v[184:187], v[136:139]
	v_mfma_f32_16x16x32_bf16 v[124:127], v[72:75], v[192:195], v[124:127]
	v_mfma_f32_16x16x32_bf16 v[120:123], v[80:83], v[192:195], v[120:123]
	v_mfma_f32_16x16x32_bf16 v[108:111], v[72:75], v[212:215], v[108:111]
	v_mfma_f32_16x16x32_bf16 v[104:107], v[80:83], v[212:215], v[104:107]
	v_mfma_f32_16x16x32_bf16 v[36:39], v[76:79], v[180:183], v[36:39]
	v_mfma_f32_16x16x32_bf16 v[28:31], v[84:87], v[180:183], v[28:31]
	v_mfma_f32_16x16x32_bf16 v[140:143], v[76:79], v[188:191], v[140:143]
	v_mfma_f32_16x16x32_bf16 v[136:139], v[84:87], v[188:191], v[136:139]
	v_mfma_f32_16x16x32_bf16 v[124:127], v[76:79], v[196:199], v[124:127]
	v_mfma_f32_16x16x32_bf16 v[120:123], v[84:87], v[196:199], v[120:123]
	v_mfma_f32_16x16x32_bf16 v[108:111], v[76:79], v[216:219], v[108:111]
	v_mfma_f32_16x16x32_bf16 v[104:107], v[84:87], v[216:219], v[104:107]
	v_mfma_f32_16x16x32_bf16 v[156:159], v[88:91], v[176:179], v[156:159]
	v_mfma_f32_16x16x32_bf16 v[152:155], v[96:99], v[176:179], v[152:155]
	v_mfma_f32_16x16x32_bf16 v[148:151], v[88:91], v[184:187], v[148:151]
	v_mfma_f32_16x16x32_bf16 v[144:147], v[96:99], v[184:187], v[144:147]
	v_mfma_f32_16x16x32_bf16 v[132:135], v[88:91], v[192:195], v[132:135]
	v_mfma_f32_16x16x32_bf16 v[128:131], v[96:99], v[192:195], v[128:131]
	v_mfma_f32_16x16x32_bf16 v[116:119], v[88:91], v[212:215], v[116:119]
	v_mfma_f32_16x16x32_bf16 v[112:115], v[96:99], v[212:215], v[112:115]
	v_mfma_f32_16x16x32_bf16 v[156:159], v[92:95], v[180:183], v[156:159]
	v_mfma_f32_16x16x32_bf16 v[152:155], v[100:103], v[180:183], v[152:155]
	v_mfma_f32_16x16x32_bf16 v[148:151], v[92:95], v[188:191], v[148:151]
	v_mfma_f32_16x16x32_bf16 v[144:147], v[100:103], v[188:191], v[144:147]
	v_mfma_f32_16x16x32_bf16 v[132:135], v[92:95], v[196:199], v[132:135]
	v_mfma_f32_16x16x32_bf16 v[128:131], v[100:103], v[196:199], v[128:131]
	v_mfma_f32_16x16x32_bf16 v[116:119], v[92:95], v[216:219], v[116:119]
	v_mfma_f32_16x16x32_bf16 v[112:115], v[100:103], v[216:219], v[112:115]
	s_barrier
; #define PG8_STAGE(bufoff, gbase, voff) do { _Pragma("unroll") for (int _i = 0; _i < 2; ++_i) \
;         __builtin_amdgcn_global_load_lds((const unsigned*)((const char*)(gbase) + (voff)[_i]), (PG8_LAS unsigned*)(lds + (bufoff) + ldsw + _i * 8192), 16, 0, 0); } while (0)
; #define PG8_LDA(dst, b, h) do { _Pragma("unroll") for (int m = 0; m < 4; ++m) _Pragma("unroll") for (int k = 0; k < 2; ++k) dst[m][k] = *(const PG8_LAS bf16x8*)(lds + PG8_SA(b, h) + aoff + m * 2048 + k * 1024); } while (0)
; #define PG8_MMA(ai, bj, At, Bt) do { __builtin_amdgcn_s_setprio(1); _Pragma("unroll") for (int m = 0; m < 4; ++m) _Pragma("unroll") for (int n = 0; n < 2; ++n) _Pragma("unroll") for (int k = 0; k < 2; ++k) \
;         acc[ai][bj][m][n] = __builtin_amdgcn_mfma_f32_16x16x32_bf16(Bt[n][k], At[m][k], acc[ai][bj][m][n], 0, 0, 0); __builtin_amdgcn_s_setprio(0); } while (0)
; #define PG8_WAIT_V(n) asm volatile("s_waitcnt vmcnt(" #n ")" ::: "memory")
; #define PG8_WAIT_L(n) asm volatile("s_waitcnt lgkmcnt(" #n ")" ::: "memory")
; #define PG8_BAR __builtin_amdgcn_s_barrier()
; #define PG8_SCHED __builtin_amdgcn_sched_barrier(0)
; template <class Epi, class Sched, bool ALIGN_EPI = false, bool SP2 = false, bool AROWS128 = false>
; __device__ __forceinline__ void gemm_phase(PG8_LAS unsigned char* lds, const Gemm g, const Sched& S, const Epi& E) {
;     ...
;         for (int t = 0; t < nt; t += 2) {
;             const bool last = (t == nt - 2);
;             const char* a1 = cA + (size_t)(t + 1) * kstep;
;             const char* a2 = last ? nA : cA + (size_t)(t + 2) * kstep; const char* b2 = last ? nB : cB + (size_t)(t + 2) * kstep;
;     ...
;             PG8_LDA(At, 1, 1); PG8_STAGE(PG8_SB(1, 0), b3, voffB); PG8_STAGE(PG8_SB(1, 1), b3 + hstep, voffB); PG8_STAGE(PG8_SA(1, 0), a3, voffA);
;             PG8_WAIT_V(8); PG8_WAIT_L(0); PG8_BAR; PG8_MMA(1, 0, At, B0); PG8_MMA(1, 1, At, B1); PG8_BAR; PG8_SCHED;
	s_add_i32 s76, s82, s35
	v_lshl_add_u64 v[220:221], v[220:221], 0, s[26:27]
	s_mov_b32 m0, s76
	ds_read_b128 v[176:179], v209 offset:49152
	ds_read_b128 v[180:183], v209 offset:50176
	ds_read_b128 v[184:187], v209 offset:51200
	ds_read_b128 v[188:191], v209 offset:52224
	ds_read_b128 v[192:195], v209 offset:53248
	ds_read_b128 v[196:199], v209 offset:54272
	ds_read_b128 v[212:215], v209 offset:55296
	ds_read_b128 v[216:219], v209 offset:56320
	global_load_lds_dwordx4 v[220:221], off
	s_add_i32 m0, s76, 0x2000
	s_add_u32 s20, s20, 0x40080
	v_lshl_add_u64 v[220:221], v[222:223], 0, s[26:27]
	s_addc_u32 s21, s21, 0
	s_add_i32 s76, s83, s35
	global_load_lds_dwordx4 v[220:221], off
	v_lshl_add_u64 v[220:221], s[20:21], 0, v[162:163]
	s_mov_b32 m0, s76
	s_nop 0
	global_load_lds_dwordx4 v[220:221], off
	v_lshl_add_u64 v[220:221], s[20:21], 0, v[166:167]
	s_add_i32 m0, s76, 0x2000
	s_nop 0
	global_load_lds_dwordx4 v[220:221], off
	v_lshl_add_u64 v[220:221], v[224:225], 0, s[26:27]
	s_mov_b32 m0, s89
	s_nop 0
	global_load_lds_dwordx4 v[220:221], off
	v_lshl_add_u64 v[220:221], v[226:227], 0, s[26:27]
	s_mov_b32 m0, s90
	s_nop 0
	global_load_lds_dwordx4 v[220:221], off
	s_waitcnt vmcnt(8)
	s_waitcnt lgkmcnt(0)
	s_barrier
	s_waitcnt lgkmcnt(0)
	v_mfma_f32_16x16x32_bf16 v[60:63], v[72:75], v[176:179], v[60:63]
	v_mfma_f32_16x16x32_bf16 v[56:59], v[80:83], v[176:179], v[56:59]
	v_mfma_f32_16x16x32_bf16 v[44:47], v[72:75], v[184:187], v[44:47]
	v_mfma_f32_16x16x32_bf16 v[40:43], v[80:83], v[184:187], v[40:43]
	v_mfma_f32_16x16x32_bf16 v[20:23], v[72:75], v[192:195], v[20:23]
	v_mfma_f32_16x16x32_bf16 v[16:19], v[80:83], v[192:195], v[16:19]
	v_mfma_f32_16x16x32_bf16 v[12:15], v[72:75], v[212:215], v[12:15]
	v_mfma_f32_16x16x32_bf16 v[8:11], v[80:83], v[212:215], v[8:11]
	v_mfma_f32_16x16x32_bf16 v[60:63], v[76:79], v[180:183], v[60:63]
	v_mfma_f32_16x16x32_bf16 v[56:59], v[84:87], v[180:183], v[56:59]
	v_mfma_f32_16x16x32_bf16 v[44:47], v[76:79], v[188:191], v[44:47]
	v_mfma_f32_16x16x32_bf16 v[40:43], v[84:87], v[188:191], v[40:43]
	v_mfma_f32_16x16x32_bf16 v[20:23], v[76:79], v[196:199], v[20:23]
	v_mfma_f32_16x16x32_bf16 v[16:19], v[84:87], v[196:199], v[16:19]
	v_mfma_f32_16x16x32_bf16 v[12:15], v[76:79], v[216:219], v[12:15]
	v_mfma_f32_16x16x32_bf16 v[8:11], v[84:87], v[216:219], v[8:11]
	v_mfma_f32_16x16x32_bf16 v[68:71], v[88:91], v[176:179], v[68:71]
	v_mfma_f32_16x16x32_bf16 v[64:67], v[96:99], v[176:179], v[64:67]
	v_mfma_f32_16x16x32_bf16 v[52:55], v[88:91], v[184:187], v[52:55]
	v_mfma_f32_16x16x32_bf16 v[48:51], v[96:99], v[184:187], v[48:51]
	v_mfma_f32_16x16x32_bf16 v[32:35], v[88:91], v[192:195], v[32:35]
	v_mfma_f32_16x16x32_bf16 v[24:27], v[96:99], v[192:195], v[24:27]
	v_mfma_f32_16x16x32_bf16 v[4:7], v[88:91], v[212:215], v[4:7]
	v_mfma_f32_16x16x32_bf16 v[0:3], v[96:99], v[212:215], v[0:3]
	v_mfma_f32_16x16x32_bf16 v[68:71], v[92:95], v[180:183], v[68:71]
	v_mfma_f32_16x16x32_bf16 v[64:67], v[100:103], v[180:183], v[64:67]
	v_mfma_f32_16x16x32_bf16 v[52:55], v[92:95], v[188:191], v[52:55]
	v_mfma_f32_16x16x32_bf16 v[48:51], v[100:103], v[188:191], v[48:51]
	v_mfma_f32_16x16x32_bf16 v[32:35], v[92:95], v[196:199], v[32:35]
	v_mfma_f32_16x16x32_bf16 v[24:27], v[100:103], v[196:199], v[24:27]
	v_mfma_f32_16x16x32_bf16 v[4:7], v[92:95], v[216:219], v[4:7]
	v_mfma_f32_16x16x32_bf16 v[0:3], v[100:103], v[216:219], v[0:3]
	s_barrier
	s_add_i32 s73, s73, 2
	s_add_u32 s18, s18, 0x100
	s_addc_u32 s19, s19, 0
	s_add_u32 s65, s65, 0x100
	s_addc_u32 s72, s72, 0
	s_cmp_gt_u32 s73, 13
	s_cbranch_scc0 .LBB0_626
	s_and_b64 vcc, exec, s[28:29]
	s_cbranch_vccz .LBB0_629
	s_barrier

; #define PG8_WAIT_V(n) asm volatile("s_waitcnt vmcnt(" #n ")" ::: "memory")
; #define PG8_BAR __builtin_amdgcn_s_barrier()
; template <class Epi, class Sched, bool ALIGN_EPI = false, bool SP2 = false, bool AROWS128 = false>
; __device__ __forceinline__ void gemm_phase(PG8_LAS unsigned char* lds, const Gemm g, const Sched& S, const Epi& E) {
;     ...
;         if constexpr (!Epi::AFTER_DRAIN) { E(acc, cur, wr, wc, fr, fq); S.done(cur); }
;         if (!has_next) break;
; #pragma unroll
;         for (int a = 0; a < 2; ++a)
; #pragma unroll
;             for (int b = 0; b < 2; ++b)
; #pragma unroll
;                 for (int m = 0; m < 4; ++m)
; #pragma unroll
;                     for (int n = 0; n < 2; ++n) acc[a][b][m][n] = (f32x4){0.f, 0.f, 0.f, 0.f};
;         cur = nxt; cA = nA; cB = nB; ++ui;
;         if constexpr (ALIGN_EPI) { if (wr == 1) PG8_BAR; }
;     }
;     PG8_WAIT_V(0);
;     if constexpr (!ALIGN_EPI) { if (wr == 0) PG8_BAR; }
;     PG8_BAR;
.LBB0_687:
	s_or_b64 exec, exec, s[16:17]
	s_andn2_b64 vcc, exec, s[14:15]
	s_mov_b64 s[14:15], -1
	s_cbranch_vccnz .LBB0_622
	s_andn2_b64 vcc, exec, s[24:25]
	s_cbranch_vccnz .LBB0_621
	s_barrier
	s_branch .LBB0_621
.LBB0_690:
	s_setprio 0
	s_waitcnt vmcnt(0)
	s_barrier
.LBB0_691:
	s_waitcnt vmcnt(0)
	s_waitcnt vmcnt(0)
	s_barrier
	s_and_saveexec_b64 s[0:1], s[22:23]
	v_readlane_b32 s60, v255, 12
	s_cbranch_execz .LBB0_743
	s_add_i32 s3, 0, 0x20020
	v_mov_b32_e32 v0, s3
	s_waitcnt vmcnt(0) expcnt(0) lgkmcnt(0)
	ds_read_b32 v2, v0
	s_add_i32 s3, 0, 0x20024
	v_mov_b32_e32 v0, s3
	ds_read_b32 v0, v0
	s_waitcnt lgkmcnt(1)
	v_cmp_ne_u32_e32 vcc, 0, v2
	s_cbranch_vccnz .LBB0_707
	s_add_u32 s4, s70, 0x1200
	s_addc_u32 s5, s71, 0
	s_add_u32 s6, s70, 0x1400
	s_addc_u32 s7, s71, 0
	s_add_u32 s8, s70, 0x1500
	s_addc_u32 s9, s71, 0
	s_add_u32 s10, s70, 0x1600
	s_addc_u32 s11, s71, 0
	s_add_u32 s12, s70, 0x1700
	s_addc_u32 s13, s71, 0
	s_add_u32 s14, s70, 0x1800
	s_addc_u32 s15, s71, 0
	s_add_u32 s16, s70, 0x1900
	s_addc_u32 s17, s71, 0
	s_add_u32 s18, s70, 0x1a00
	s_addc_u32 s19, s71, 0
	s_add_u32 s20, s70, 0x1b00
	s_addc_u32 s21, s71, 0
	s_add_u32 s24, s70, 0x1c00
	s_addc_u32 s25, s71, 0
	s_add_u32 s26, s70, 0x1d00
	s_addc_u32 s27, s71, 0
	s_add_u32 s28, s70, 0x1e00
	s_addc_u32 s29, s71, 0
	s_add_u32 s30, s70, 0x1f00
	s_addc_u32 s31, s71, 0
	s_add_u32 s36, s70, 0x2000
	s_addc_u32 s37, s71, 0
	s_add_u32 s38, s70, 0x2100
	s_addc_u32 s39, s71, 0
	s_add_u32 s50, s70, 0x2200
	v_readlane_b32 s3, v255, 8
	s_addc_u32 s51, s71, 0
	s_mul_i32 s3, s75, s3
	s_add_u32 s52, s70, 0x2300
	s_mul_i32 s3, s3, s74
	s_addc_u32 s53, s71, 0
	s_mov_b32 s33, 1
	v_mov_b32_e32 v16, 0
	s_branch .LBB0_695

; #define PG8_STAGE(bufoff, gbase, voff) do { _Pragma("unroll") for (int _i = 0; _i < 2; ++_i) \
;         __builtin_amdgcn_global_load_lds((const unsigned*)((const char*)(gbase) + (voff)[_i]), (PG8_LAS unsigned*)(lds + (bufoff) + ldsw + _i * 8192), 16, 0, 0); } while (0)
; #define PG8_LDA(dst, b, h) do { _Pragma("unroll") for (int m = 0; m < 4; ++m) _Pragma("unroll") for (int k = 0; k < 2; ++k) dst[m][k] = *(const PG8_LAS bf16x8*)(lds + PG8_SA(b, h) + aoff + m * 2048 + k * 1024); } while (0)
; #define PG8_LDB(dst, b, h) do { _Pragma("unroll") for (int n = 0; n < 2; ++n) _Pragma("unroll") for (int k = 0; k < 2; ++k) dst[n][k] = *(const PG8_LAS bf16x8*)(lds + PG8_SB(b, h) + boff + n * 2048 + k * 1024); } while (0)
; #define PG8_MMA(ai, bj, At, Bt) do { __builtin_amdgcn_s_setprio(1); _Pragma("unroll") for (int m = 0; m < 4; ++m) _Pragma("unroll") for (int n = 0; n < 2; ++n) _Pragma("unroll") for (int k = 0; k < 2; ++k) \
;         acc[ai][bj][m][n] = __builtin_amdgcn_mfma_f32_16x16x32_bf16(Bt[n][k], At[m][k], acc[ai][bj][m][n], 0, 0, 0); __builtin_amdgcn_s_setprio(0); } while (0)
; #define PG8_WAIT_V(n) asm volatile("s_waitcnt vmcnt(" #n ")" ::: "memory")
; #define PG8_WAIT_L(n) asm volatile("s_waitcnt lgkmcnt(" #n ")" ::: "memory")
; template <class Epi, class Sched, bool ALIGN_EPI = false, bool SP2 = false, bool AROWS128 = false>
; __device__ __forceinline__ void gemm_phase(PG8_LAS unsigned char* lds, const Gemm g, const Sched& S, const Epi& E) {
;     ...
;             const bool last = (t == nt - 2);
;             const char* a1 = cA + (size_t)(t + 1) * kstep;
;             const char* a2 = last ? nA : cA + (size_t)(t + 2) * kstep; const char* b2 = last ? nB : cB + (size_t)(t + 2) * kstep;
;             const char* a3 = a2 + kstep; const char* b3 = b2 + kstep;
;             if (last && has_next) S.a_ready(nxt);
;             if constexpr (SP2) {
;             PG8_LDB(B0, 0, 0); PG8_LDB(B1, 0, 1); PG8_SCHED; PG8_LDA(At, 0, 0); PG8_STAGE(PG8_SA(1, 1), a1 + hstepA, voffA);
;             PG8_WAIT_V(8); PG8_WAIT_L(0); PG8_BAR; PG8_MMA(0, 0, At, B0); PG8_MMA(0, 1, At, B1); PG8_BAR; PG8_SCHED;
;             PG8_LDA(At, 0, 1); PG8_STAGE(PG8_SB(0, 0), b2, voffB); PG8_STAGE(PG8_SB(0, 1), b2 + hstep, voffB); PG8_STAGE(PG8_SA(0, 0), a2, voffA);
;             PG8_WAIT_V(8); PG8_WAIT_L(0); PG8_BAR; PG8_MMA(1, 0, At, B0); PG8_MMA(1, 1, At, B1); PG8_BAR; PG8_SCHED;
.LBB0_752:
	ds_read_b128 v[152:155], v149
	ds_read_b128 v[156:159], v149 offset:1024
	ds_read_b128 v[160:163], v149 offset:2048
	ds_read_b128 v[164:167], v149 offset:3072
	ds_read_b128 v[168:171], v150
	ds_read_b128 v[172:175], v150 offset:1024
	ds_read_b128 v[176:179], v150 offset:2048
	ds_read_b128 v[180:183], v150 offset:3072
	s_add_u32 s38, s36, 0xfff00080
	s_addc_u32 s39, s37, -1
	s_cmp_eq_u32 s77, 60
	s_cselect_b32 s49, s25, s39
	s_cselect_b32 s48, s65, s38
	s_cselect_b32 s39, s21, s76
	s_cselect_b32 s38, s72, s73
	v_lshl_add_u64 v[144:145], s[36:37], 0, v[136:137]
	s_add_i32 m0, s31, 0xc000
	ds_read_b128 v[184:187], v151
	ds_read_b128 v[188:191], v151 offset:1024
	ds_read_b128 v[192:195], v151 offset:2048
	ds_read_b128 v[196:199], v151 offset:3072
	ds_read_b128 v[200:203], v151 offset:4096
	ds_read_b128 v[204:207], v151 offset:5120
	ds_read_b128 v[212:215], v151 offset:6144
	ds_read_b128 v[216:219], v151 offset:7168
	global_load_lds_dwordx4 v[144:145], off
	v_lshl_add_u64 v[144:145], s[36:37], 0, v[138:139]
	s_add_i32 m0, s31, 0xe000
	s_nop 0
	global_load_lds_dwordx4 v[144:145], off
	s_waitcnt vmcnt(8)
	s_waitcnt lgkmcnt(0)
	s_barrier
	s_waitcnt lgkmcnt(0)
	v_mfma_f32_16x16x32_bf16 v[124:127], v[152:155], v[184:187], v[124:127]
	v_mfma_f32_16x16x32_bf16 v[120:123], v[160:163], v[184:187], v[120:123]
	v_mfma_f32_16x16x32_bf16 v[116:119], v[152:155], v[192:195], v[116:119]
	v_mfma_f32_16x16x32_bf16 v[108:111], v[160:163], v[192:195], v[108:111]
	v_mfma_f32_16x16x32_bf16 v[100:103], v[152:155], v[200:203], v[100:103]
	v_mfma_f32_16x16x32_bf16 v[92:95], v[160:163], v[200:203], v[92:95]
	v_mfma_f32_16x16x32_bf16 v[84:87], v[152:155], v[212:215], v[84:87]
	v_mfma_f32_16x16x32_bf16 v[76:79], v[160:163], v[212:215], v[76:79]
	v_mfma_f32_16x16x32_bf16 v[124:127], v[156:159], v[188:191], v[124:127]
	v_mfma_f32_16x16x32_bf16 v[120:123], v[164:167], v[188:191], v[120:123]
	v_mfma_f32_16x16x32_bf16 v[116:119], v[156:159], v[196:199], v[116:119]
	v_mfma_f32_16x16x32_bf16 v[108:111], v[164:167], v[196:199], v[108:111]
	v_mfma_f32_16x16x32_bf16 v[100:103], v[156:159], v[204:207], v[100:103]
	v_mfma_f32_16x16x32_bf16 v[92:95], v[164:167], v[204:207], v[92:95]
	v_mfma_f32_16x16x32_bf16 v[84:87], v[156:159], v[216:219], v[84:87]
	v_mfma_f32_16x16x32_bf16 v[76:79], v[164:167], v[216:219], v[76:79]
	v_mfma_f32_16x16x32_bf16 v[112:115], v[168:171], v[184:187], v[112:115]
	v_mfma_f32_16x16x32_bf16 v[104:107], v[176:179], v[184:187], v[104:107]
	v_mfma_f32_16x16x32_bf16 v[96:99], v[168:171], v[192:195], v[96:99]
	v_mfma_f32_16x16x32_bf16 v[88:91], v[176:179], v[192:195], v[88:91]
	v_mfma_f32_16x16x32_bf16 v[80:83], v[168:171], v[200:203], v[80:83]
	v_mfma_f32_16x16x32_bf16 v[72:75], v[176:179], v[200:203], v[72:75]
	v_mfma_f32_16x16x32_bf16 v[68:71], v[168:171], v[212:215], v[68:71]
	v_mfma_f32_16x16x32_bf16 v[64:67], v[176:179], v[212:215], v[64:67]
	v_mfma_f32_16x16x32_bf16 v[112:115], v[172:175], v[188:191], v[112:115]
	v_mfma_f32_16x16x32_bf16 v[104:107], v[180:183], v[188:191], v[104:107]
	v_mfma_f32_16x16x32_bf16 v[96:99], v[172:175], v[196:199], v[96:99]
	v_mfma_f32_16x16x32_bf16 v[88:91], v[180:183], v[196:199], v[88:91]
	v_mfma_f32_16x16x32_bf16 v[80:83], v[172:175], v[204:207], v[80:83]
	v_mfma_f32_16x16x32_bf16 v[72:75], v[180:183], v[204:207], v[72:75]
	v_mfma_f32_16x16x32_bf16 v[68:71], v[172:175], v[216:219], v[68:71]
	v_mfma_f32_16x16x32_bf16 v[64:67], v[180:183], v[216:219], v[64:67]
	s_barrier
	s_add_i32 s78, s58, s3
	v_lshl_add_u64 v[144:145], s[38:39], 0, v[132:133]
	s_mov_b32 m0, s78
	ds_read_b128 v[184:187], v151 offset:16384
	ds_read_b128 v[188:191], v151 offset:17408
	ds_read_b128 v[192:195], v151 offset:18432
	ds_read_b128 v[196:199], v151 offset:19456
	ds_read_b128 v[200:203], v151 offset:20480
	ds_read_b128 v[204:207], v151 offset:21504
	ds_read_b128 v[212:215], v151 offset:22528
	ds_read_b128 v[216:219], v151 offset:23552
	global_load_lds_dwordx4 v[144:145], off
	s_add_i32 m0, s78, 0x2000
	s_add_u32 s78, s38, 0x100000
	v_lshl_add_u64 v[208:209], s[38:39], 0, v[128:129]
	s_addc_u32 s79, s39, 0
	s_add_i32 s80, s59, s3
	global_load_lds_dwordx4 v[208:209], off
	v_lshl_add_u64 v[220:221], s[78:79], 0, v[132:133]
	s_mov_b32 m0, s80
	v_lshl_add_u64 v[222:223], s[48:49], 0, v[130:131]
	global_load_lds_dwordx4 v[220:221], off
	v_lshl_add_u64 v[220:221], s[78:79], 0, v[128:129]
	s_add_i32 m0, s80, 0x2000
	s_nop 0
	global_load_lds_dwordx4 v[220:221], off
	v_lshl_add_u64 v[220:221], s[48:49], 0, v[134:135]
	s_mov_b32 m0, s31
	s_nop 0
	global_load_lds_dwordx4 v[220:221], off
	s_mov_b32 m0, s50
	s_nop 0
	global_load_lds_dwordx4 v[222:223], off
	s_waitcnt vmcnt(8)
	s_waitcnt lgkmcnt(0)
	s_barrier
; #define PG8_STAGE(bufoff, gbase, voff) do { _Pragma("unroll") for (int _i = 0; _i < 2; ++_i) \
;         __builtin_amdgcn_global_load_lds((const unsigned*)((const char*)(gbase) + (voff)[_i]), (PG8_LAS unsigned*)(lds + (bufoff) + ldsw + _i * 8192), 16, 0, 0); } while (0)
; #define PG8_LDA(dst, b, h) do { _Pragma("unroll") for (int m = 0; m < 4; ++m) _Pragma("unroll") for (int k = 0; k < 2; ++k) dst[m][k] = *(const PG8_LAS bf16x8*)(lds + PG8_SA(b, h) + aoff + m * 2048 + k * 1024); } while (0)
; #define PG8_LDB(dst, b, h) do { _Pragma("unroll") for (int n = 0; n < 2; ++n) _Pragma("unroll") for (int k = 0; k < 2; ++k) dst[n][k] = *(const PG8_LAS bf16x8*)(lds + PG8_SB(b, h) + boff + n * 2048 + k * 1024); } while (0)
; #define PG8_MMA(ai, bj, At, Bt) do { __builtin_amdgcn_s_setprio(1); _Pragma("unroll") for (int m = 0; m < 4; ++m) _Pragma("unroll") for (int n = 0; n < 2; ++n) _Pragma("unroll") for (int k = 0; k < 2; ++k) \
;         acc[ai][bj][m][n] = __builtin_amdgcn_mfma_f32_16x16x32_bf16(Bt[n][k], At[m][k], acc[ai][bj][m][n], 0, 0, 0); __builtin_amdgcn_s_setprio(0); } while (0)
; #define PG8_WAIT_V(n) asm volatile("s_waitcnt vmcnt(" #n ")" ::: "memory")
; #define PG8_WAIT_L(n) asm volatile("s_waitcnt lgkmcnt(" #n ")" ::: "memory")
; #define PG8_BAR __builtin_amdgcn_s_barrier()
; #define PG8_SCHED __builtin_amdgcn_sched_barrier(0)
; template <class Epi, class Sched, bool ALIGN_EPI = false, bool SP2 = false, bool AROWS128 = false>
; __device__ __forceinline__ void gemm_phase(PG8_LAS unsigned char* lds, const Gemm g, const Sched& S, const Epi& E) {
;     ...
;             PG8_WAIT_V(8); PG8_WAIT_L(0); PG8_BAR; PG8_MMA(1, 0, At, B0); PG8_MMA(1, 1, At, B1); PG8_BAR; PG8_SCHED;
;             PG8_LDB(B0, 1, 0); PG8_LDB(B1, 1, 1); PG8_SCHED; PG8_LDA(At, 1, 0); PG8_STAGE(PG8_SA(0, 1), a2 + hstepA, voffA);
;             PG8_WAIT_V(8); PG8_WAIT_L(0); PG8_BAR; PG8_MMA(0, 0, At, B0); PG8_MMA(0, 1, At, B1); PG8_BAR; PG8_SCHED;
	s_waitcnt lgkmcnt(0)
	v_mfma_f32_16x16x32_bf16 v[60:63], v[152:155], v[184:187], v[60:63]
	v_mfma_f32_16x16x32_bf16 v[56:59], v[160:163], v[184:187], v[56:59]
	v_mfma_f32_16x16x32_bf16 v[52:55], v[152:155], v[192:195], v[52:55]
	v_mfma_f32_16x16x32_bf16 v[44:47], v[160:163], v[192:195], v[44:47]
	v_mfma_f32_16x16x32_bf16 v[36:39], v[152:155], v[200:203], v[36:39]
	v_mfma_f32_16x16x32_bf16 v[28:31], v[160:163], v[200:203], v[28:31]
	v_mfma_f32_16x16x32_bf16 v[20:23], v[152:155], v[212:215], v[20:23]
	v_mfma_f32_16x16x32_bf16 v[12:15], v[160:163], v[212:215], v[12:15]
	v_mfma_f32_16x16x32_bf16 v[60:63], v[156:159], v[188:191], v[60:63]
	v_mfma_f32_16x16x32_bf16 v[56:59], v[164:167], v[188:191], v[56:59]
	v_mfma_f32_16x16x32_bf16 v[52:55], v[156:159], v[196:199], v[52:55]
	v_mfma_f32_16x16x32_bf16 v[44:47], v[164:167], v[196:199], v[44:47]
	v_mfma_f32_16x16x32_bf16 v[36:39], v[156:159], v[204:207], v[36:39]
	v_mfma_f32_16x16x32_bf16 v[28:31], v[164:167], v[204:207], v[28:31]
	v_mfma_f32_16x16x32_bf16 v[20:23], v[156:159], v[216:219], v[20:23]
	v_mfma_f32_16x16x32_bf16 v[12:15], v[164:167], v[216:219], v[12:15]
	v_mfma_f32_16x16x32_bf16 v[48:51], v[168:171], v[184:187], v[48:51]
	v_mfma_f32_16x16x32_bf16 v[40:43], v[176:179], v[184:187], v[40:43]
	v_mfma_f32_16x16x32_bf16 v[32:35], v[168:171], v[192:195], v[32:35]
	v_mfma_f32_16x16x32_bf16 v[24:27], v[176:179], v[192:195], v[24:27]
	v_mfma_f32_16x16x32_bf16 v[16:19], v[168:171], v[200:203], v[16:19]
	v_mfma_f32_16x16x32_bf16 v[8:11], v[176:179], v[200:203], v[8:11]
	v_mfma_f32_16x16x32_bf16 v[4:7], v[168:171], v[212:215], v[4:7]
	v_mfma_f32_16x16x32_bf16 v[0:3], v[176:179], v[212:215], v[0:3]
	v_mfma_f32_16x16x32_bf16 v[48:51], v[172:175], v[188:191], v[48:51]
	v_mfma_f32_16x16x32_bf16 v[40:43], v[180:183], v[188:191], v[40:43]
	v_mfma_f32_16x16x32_bf16 v[32:35], v[172:175], v[196:199], v[32:35]
	v_mfma_f32_16x16x32_bf16 v[24:27], v[180:183], v[196:199], v[24:27]
	v_mfma_f32_16x16x32_bf16 v[16:19], v[172:175], v[204:207], v[16:19]
	v_mfma_f32_16x16x32_bf16 v[8:11], v[180:183], v[204:207], v[8:11]
	v_mfma_f32_16x16x32_bf16 v[4:7], v[172:175], v[216:219], v[4:7]
	v_mfma_f32_16x16x32_bf16 v[0:3], v[180:183], v[216:219], v[0:3]
	s_barrier
	s_add_i32 s78, 0, 0x18000
	s_add_i32 s79, 0, 0x1c000
	v_add_u32_e32 v164, s78, v147
	v_add_u32_e32 v180, s79, v147
	ds_read_b128 v[152:155], v164
	ds_read_b128 v[156:159], v164 offset:1024
	ds_read_b128 v[160:163], v164 offset:2048
	ds_read_b128 v[164:167], v164 offset:3072
	ds_read_b128 v[168:171], v180
	ds_read_b128 v[172:175], v180 offset:1024
	ds_read_b128 v[176:179], v180 offset:2048
	ds_read_b128 v[180:183], v180 offset:3072
	s_add_u32 s48, s48, 0x100000
	s_addc_u32 s49, s49, 0
	s_mov_b32 m0, s51
	v_lshl_add_u64 v[224:225], s[48:49], 0, v[134:135]
	ds_read_b128 v[184:187], v151 offset:32768
	ds_read_b128 v[188:191], v151 offset:33792
	ds_read_b128 v[192:195], v151 offset:34816
	ds_read_b128 v[196:199], v151 offset:35840
	ds_read_b128 v[200:203], v151 offset:36864
	ds_read_b128 v[204:207], v151 offset:37888
	ds_read_b128 v[212:215], v151 offset:38912
	ds_read_b128 v[216:219], v151 offset:39936
	global_load_lds_dwordx4 v[224:225], off
	v_lshl_add_u64 v[224:225], s[48:49], 0, v[130:131]
	s_mov_b32 m0, s52
	s_nop 0
	global_load_lds_dwordx4 v[224:225], off
	s_waitcnt vmcnt(8)
	s_waitcnt lgkmcnt(0)
	s_barrier
	s_waitcnt lgkmcnt(0)
	v_mfma_f32_16x16x32_bf16 v[124:127], v[152:155], v[184:187], v[124:127]
	v_mfma_f32_16x16x32_bf16 v[120:123], v[160:163], v[184:187], v[120:123]
	v_mfma_f32_16x16x32_bf16 v[116:119], v[152:155], v[192:195], v[116:119]
	v_mfma_f32_16x16x32_bf16 v[108:111], v[160:163], v[192:195], v[108:111]
	v_mfma_f32_16x16x32_bf16 v[100:103], v[152:155], v[200:203], v[100:103]
	v_mfma_f32_16x16x32_bf16 v[92:95], v[160:163], v[200:203], v[92:95]
	v_mfma_f32_16x16x32_bf16 v[84:87], v[152:155], v[212:215], v[84:87]
	v_mfma_f32_16x16x32_bf16 v[76:79], v[160:163], v[212:215], v[76:79]
	v_mfma_f32_16x16x32_bf16 v[124:127], v[156:159], v[188:191], v[124:127]
	v_mfma_f32_16x16x32_bf16 v[120:123], v[164:167], v[188:191], v[120:123]
	v_mfma_f32_16x16x32_bf16 v[116:119], v[156:159], v[196:199], v[116:119]
	v_mfma_f32_16x16x32_bf16 v[108:111], v[164:167], v[196:199], v[108:111]
	v_mfma_f32_16x16x32_bf16 v[100:103], v[156:159], v[204:207], v[100:103]
	v_mfma_f32_16x16x32_bf16 v[92:95], v[164:167], v[204:207], v[92:95]
	v_mfma_f32_16x16x32_bf16 v[84:87], v[156:159], v[216:219], v[84:87]
	v_mfma_f32_16x16x32_bf16 v[76:79], v[164:167], v[216:219], v[76:79]
	v_mfma_f32_16x16x32_bf16 v[112:115], v[168:171], v[184:187], v[112:115]
	v_mfma_f32_16x16x32_bf16 v[104:107], v[176:179], v[184:187], v[104:107]
	v_mfma_f32_16x16x32_bf16 v[96:99], v[168:171], v[192:195], v[96:99]
	v_mfma_f32_16x16x32_bf16 v[88:91], v[176:179], v[192:195], v[88:91]
	v_mfma_f32_16x16x32_bf16 v[80:83], v[168:171], v[200:203], v[80:83]
	v_mfma_f32_16x16x32_bf16 v[72:75], v[176:179], v[200:203], v[72:75]
	v_mfma_f32_16x16x32_bf16 v[68:71], v[168:171], v[212:215], v[68:71]
	v_mfma_f32_16x16x32_bf16 v[64:67], v[176:179], v[212:215], v[64:67]
	v_mfma_f32_16x16x32_bf16 v[112:115], v[172:175], v[188:191], v[112:115]
	v_mfma_f32_16x16x32_bf16 v[104:107], v[180:183], v[188:191], v[104:107]
	v_mfma_f32_16x16x32_bf16 v[96:99], v[172:175], v[196:199], v[96:99]
	v_mfma_f32_16x16x32_bf16 v[88:91], v[180:183], v[196:199], v[88:91]
	v_mfma_f32_16x16x32_bf16 v[80:83], v[172:175], v[204:207], v[80:83]
	v_mfma_f32_16x16x32_bf16 v[72:75], v[180:183], v[204:207], v[72:75]
	v_mfma_f32_16x16x32_bf16 v[68:71], v[172:175], v[216:219], v[68:71]
	v_mfma_f32_16x16x32_bf16 v[64:67], v[180:183], v[216:219], v[64:67]
	s_barrier
; #define PG8_STAGE(bufoff, gbase, voff) do { _Pragma("unroll") for (int _i = 0; _i < 2; ++_i) \
;         __builtin_amdgcn_global_load_lds((const unsigned*)((const char*)(gbase) + (voff)[_i]), (PG8_LAS unsigned*)(lds + (bufoff) + ldsw + _i * 8192), 16, 0, 0); } while (0)
; #define PG8_LDA(dst, b, h) do { _Pragma("unroll") for (int m = 0; m < 4; ++m) _Pragma("unroll") for (int k = 0; k < 2; ++k) dst[m][k] = *(const PG8_LAS bf16x8*)(lds + PG8_SA(b, h) + aoff + m * 2048 + k * 1024); } while (0)
; #define PG8_MMA(ai, bj, At, Bt) do { __builtin_amdgcn_s_setprio(1); _Pragma("unroll") for (int m = 0; m < 4; ++m) _Pragma("unroll") for (int n = 0; n < 2; ++n) _Pragma("unroll") for (int k = 0; k < 2; ++k) \
;         acc[ai][bj][m][n] = __builtin_amdgcn_mfma_f32_16x16x32_bf16(Bt[n][k], At[m][k], acc[ai][bj][m][n], 0, 0, 0); __builtin_amdgcn_s_setprio(0); } while (0)
; #define PG8_WAIT_V(n) asm volatile("s_waitcnt vmcnt(" #n ")" ::: "memory")
; #define PG8_WAIT_L(n) asm volatile("s_waitcnt lgkmcnt(" #n ")" ::: "memory")
; #define PG8_BAR __builtin_amdgcn_s_barrier()
; #define PG8_SCHED __builtin_amdgcn_sched_barrier(0)
; template <class Epi, class Sched, bool ALIGN_EPI = false, bool SP2 = false, bool AROWS128 = false>
; __device__ __forceinline__ void gemm_phase(PG8_LAS unsigned char* lds, const Gemm g, const Sched& S, const Epi& E) {
;     ...
;         for (int t = 0; t < nt; t += 2) {
;             const bool last = (t == nt - 2);
;             const char* a1 = cA + (size_t)(t + 1) * kstep;
;             const char* a2 = last ? nA : cA + (size_t)(t + 2) * kstep; const char* b2 = last ? nB : cB + (size_t)(t + 2) * kstep;
;     ...
;             PG8_LDA(At, 1, 1); PG8_STAGE(PG8_SB(1, 0), b3, voffB); PG8_STAGE(PG8_SB(1, 1), b3 + hstep, voffB); PG8_STAGE(PG8_SA(1, 0), a3, voffA);
;             PG8_WAIT_V(8); PG8_WAIT_L(0); PG8_BAR; PG8_MMA(1, 0, At, B0); PG8_MMA(1, 1, At, B1); PG8_BAR; PG8_SCHED;
	s_add_i32 s48, s78, s3
	v_lshl_add_u64 v[144:145], v[144:145], 0, s[8:9]
	s_mov_b32 m0, s48
	ds_read_b128 v[184:187], v151 offset:49152
	ds_read_b128 v[188:191], v151 offset:50176
	ds_read_b128 v[192:195], v151 offset:51200
	ds_read_b128 v[196:199], v151 offset:52224
	ds_read_b128 v[200:203], v151 offset:53248
	ds_read_b128 v[204:207], v151 offset:54272
	ds_read_b128 v[212:215], v151 offset:55296
	ds_read_b128 v[216:219], v151 offset:56320
	global_load_lds_dwordx4 v[144:145], off
	s_add_i32 m0, s48, 0x2000
	s_add_u32 s38, s38, 0x100080
	v_lshl_add_u64 v[144:145], v[208:209], 0, s[8:9]
	s_addc_u32 s39, s39, 0
	s_add_i32 s48, s79, s3
	global_load_lds_dwordx4 v[144:145], off
	v_lshl_add_u64 v[144:145], s[38:39], 0, v[132:133]
	s_mov_b32 m0, s48
	s_nop 0
	global_load_lds_dwordx4 v[144:145], off
	v_lshl_add_u64 v[144:145], s[38:39], 0, v[128:129]
	s_add_i32 m0, s48, 0x2000
	s_nop 0
	global_load_lds_dwordx4 v[144:145], off
	v_lshl_add_u64 v[144:145], v[220:221], 0, s[8:9]
	s_mov_b32 m0, s54
	s_nop 0
	global_load_lds_dwordx4 v[144:145], off
	v_lshl_add_u64 v[144:145], v[222:223], 0, s[8:9]
	s_mov_b32 m0, s55
	s_nop 0
	global_load_lds_dwordx4 v[144:145], off
	s_waitcnt vmcnt(8)
	s_waitcnt lgkmcnt(0)
	s_barrier
	s_waitcnt lgkmcnt(0)
	v_mfma_f32_16x16x32_bf16 v[60:63], v[152:155], v[184:187], v[60:63]
	v_mfma_f32_16x16x32_bf16 v[56:59], v[160:163], v[184:187], v[56:59]
	v_mfma_f32_16x16x32_bf16 v[52:55], v[152:155], v[192:195], v[52:55]
	v_mfma_f32_16x16x32_bf16 v[44:47], v[160:163], v[192:195], v[44:47]
	v_mfma_f32_16x16x32_bf16 v[36:39], v[152:155], v[200:203], v[36:39]
	v_mfma_f32_16x16x32_bf16 v[28:31], v[160:163], v[200:203], v[28:31]
	v_mfma_f32_16x16x32_bf16 v[20:23], v[152:155], v[212:215], v[20:23]
	v_mfma_f32_16x16x32_bf16 v[12:15], v[160:163], v[212:215], v[12:15]
	v_mfma_f32_16x16x32_bf16 v[60:63], v[156:159], v[188:191], v[60:63]
	v_mfma_f32_16x16x32_bf16 v[56:59], v[164:167], v[188:191], v[56:59]
	v_mfma_f32_16x16x32_bf16 v[52:55], v[156:159], v[196:199], v[52:55]
	v_mfma_f32_16x16x32_bf16 v[44:47], v[164:167], v[196:199], v[44:47]
	v_mfma_f32_16x16x32_bf16 v[36:39], v[156:159], v[204:207], v[36:39]
	v_mfma_f32_16x16x32_bf16 v[28:31], v[164:167], v[204:207], v[28:31]
	v_mfma_f32_16x16x32_bf16 v[20:23], v[156:159], v[216:219], v[20:23]
	v_mfma_f32_16x16x32_bf16 v[12:15], v[164:167], v[216:219], v[12:15]
	v_mfma_f32_16x16x32_bf16 v[48:51], v[168:171], v[184:187], v[48:51]
	v_mfma_f32_16x16x32_bf16 v[40:43], v[176:179], v[184:187], v[40:43]
	v_mfma_f32_16x16x32_bf16 v[32:35], v[168:171], v[192:195], v[32:35]
	v_mfma_f32_16x16x32_bf16 v[24:27], v[176:179], v[192:195], v[24:27]
	v_mfma_f32_16x16x32_bf16 v[16:19], v[168:171], v[200:203], v[16:19]
	v_mfma_f32_16x16x32_bf16 v[8:11], v[176:179], v[200:203], v[8:11]
	v_mfma_f32_16x16x32_bf16 v[4:7], v[168:171], v[212:215], v[4:7]
	v_mfma_f32_16x16x32_bf16 v[0:3], v[176:179], v[212:215], v[0:3]
	v_mfma_f32_16x16x32_bf16 v[48:51], v[172:175], v[188:191], v[48:51]
	v_mfma_f32_16x16x32_bf16 v[40:43], v[180:183], v[188:191], v[40:43]
	v_mfma_f32_16x16x32_bf16 v[32:35], v[172:175], v[196:199], v[32:35]
	v_mfma_f32_16x16x32_bf16 v[24:27], v[180:183], v[196:199], v[24:27]
	v_mfma_f32_16x16x32_bf16 v[16:19], v[172:175], v[204:207], v[16:19]
	v_mfma_f32_16x16x32_bf16 v[8:11], v[180:183], v[204:207], v[8:11]
	v_mfma_f32_16x16x32_bf16 v[4:7], v[172:175], v[216:219], v[4:7]
	v_mfma_f32_16x16x32_bf16 v[0:3], v[180:183], v[216:219], v[0:3]
	s_barrier
	s_add_i32 s77, s77, 2
	s_add_u32 s36, s36, 0x100
	s_addc_u32 s37, s37, 0
	s_add_u32 s73, s73, 0x100
	s_addc_u32 s76, s76, 0
	s_cmp_gt_u32 s77, 61
	s_cbranch_scc0 .LBB0_752
	s_and_b64 vcc, exec, s[10:11]
	s_cbranch_vccz .LBB0_755
	s_barrier

; #define PG8_WAIT_V(n) asm volatile("s_waitcnt vmcnt(" #n ")" ::: "memory")
; #define PG8_BAR __builtin_amdgcn_s_barrier()
; template <class Epi, class Sched, bool ALIGN_EPI = false, bool SP2 = false, bool AROWS128 = false>
; __device__ __forceinline__ void gemm_phase(PG8_LAS unsigned char* lds, const Gemm g, const Sched& S, const Epi& E) {
;     ...
;     PG8_WAIT_V(0);
;     if constexpr (!ALIGN_EPI) { if (wr == 0) PG8_BAR; }
;     PG8_BAR;
.LBB0_758:
	s_setprio 0
	s_waitcnt vmcnt(0)
	v_readlane_b32 s60, v255, 12
	s_barrier

; #define PG8_STAGE(bufoff, gbase, voff) do { _Pragma("unroll") for (int _i = 0; _i < 2; ++_i) \
;         __builtin_amdgcn_global_load_lds((const unsigned*)((const char*)(gbase) + (voff)[_i]), (PG8_LAS unsigned*)(lds + (bufoff) + ldsw + _i * 8192), 16, 0, 0); } while (0)
; #define PG8_LDA(dst, b, h) do { _Pragma("unroll") for (int m = 0; m < 4; ++m) _Pragma("unroll") for (int k = 0; k < 2; ++k) dst[m][k] = *(const PG8_LAS bf16x8*)(lds + PG8_SA(b, h) + aoff + m * 2048 + k * 1024); } while (0)
; #define PG8_LDB(dst, b, h) do { _Pragma("unroll") for (int n = 0; n < 2; ++n) _Pragma("unroll") for (int k = 0; k < 2; ++k) dst[n][k] = *(const PG8_LAS bf16x8*)(lds + PG8_SB(b, h) + boff + n * 2048 + k * 1024); } while (0)
; #define PG8_MMA(ai, bj, At, Bt) do { __builtin_amdgcn_s_setprio(1); _Pragma("unroll") for (int m = 0; m < 4; ++m) _Pragma("unroll") for (int n = 0; n < 2; ++n) _Pragma("unroll") for (int k = 0; k < 2; ++k) \
;         acc[ai][bj][m][n] = __builtin_amdgcn_mfma_f32_16x16x32_bf16(Bt[n][k], At[m][k], acc[ai][bj][m][n], 0, 0, 0); __builtin_amdgcn_s_setprio(0); } while (0)
; #define PG8_WAIT_V(n) asm volatile("s_waitcnt vmcnt(" #n ")" ::: "memory")
; #define PG8_WAIT_L(n) asm volatile("s_waitcnt lgkmcnt(" #n ")" ::: "memory")
; template <class Epi, class Sched, bool ALIGN_EPI = false, bool SP2 = false, bool AROWS128 = false>
; __device__ __forceinline__ void gemm_phase(PG8_LAS unsigned char* lds, const Gemm g, const Sched& S, const Epi& E) {
;     ...
;             const bool last = (t == nt - 2);
;             const char* a1 = cA + (size_t)(t + 1) * kstep;
;             const char* a2 = last ? nA : cA + (size_t)(t + 2) * kstep; const char* b2 = last ? nB : cB + (size_t)(t + 2) * kstep;
;             const char* a3 = a2 + kstep; const char* b3 = b2 + kstep;
;             if (last && has_next) S.a_ready(nxt);
;             if constexpr (SP2) {
;             PG8_LDB(B0, 0, 0); PG8_LDB(B1, 0, 1); PG8_SCHED; PG8_LDA(At, 0, 0); PG8_STAGE(PG8_SA(1, 1), a1 + hstepA, voffA);
;             PG8_WAIT_V(8); PG8_WAIT_L(0); PG8_BAR; PG8_MMA(0, 0, At, B0); PG8_MMA(0, 1, At, B1); PG8_BAR; PG8_SCHED;
;             PG8_LDA(At, 0, 1); PG8_STAGE(PG8_SB(0, 0), b2, voffB); PG8_STAGE(PG8_SB(0, 1), b2 + hstep, voffB); PG8_STAGE(PG8_SA(0, 0), a2, voffA);
;             PG8_WAIT_V(8); PG8_WAIT_L(0); PG8_BAR; PG8_MMA(1, 0, At, B0); PG8_MMA(1, 1, At, B1); PG8_BAR; PG8_SCHED;
.LBB0_886:
	ds_read_b128 v[152:155], v149
	ds_read_b128 v[156:159], v149 offset:1024
	ds_read_b128 v[160:163], v149 offset:2048
	ds_read_b128 v[164:167], v149 offset:3072
	ds_read_b128 v[168:171], v150
	ds_read_b128 v[172:175], v150 offset:1024
	ds_read_b128 v[176:179], v150 offset:2048
	ds_read_b128 v[180:183], v150 offset:3072
	s_add_u32 s46, s42, 0xfffc0080
	s_addc_u32 s47, s43, -1
	s_cmp_eq_u32 s73, 12
	s_cselect_b32 s49, s31, s47
	s_cselect_b32 s48, s65, s46
	s_cselect_b32 s47, s29, s72
	s_cselect_b32 s46, s66, s67
	v_lshl_add_u64 v[144:145], s[42:43], 0, v[136:137]
	s_add_i32 m0, s41, 0xc000
	ds_read_b128 v[184:187], v151
	ds_read_b128 v[188:191], v151 offset:1024
	ds_read_b128 v[192:195], v151 offset:2048
	ds_read_b128 v[196:199], v151 offset:3072
	ds_read_b128 v[200:203], v151 offset:4096
	ds_read_b128 v[204:207], v151 offset:5120
	ds_read_b128 v[212:215], v151 offset:6144
	ds_read_b128 v[216:219], v151 offset:7168
	global_load_lds_dwordx4 v[144:145], off
	v_lshl_add_u64 v[144:145], s[42:43], 0, v[138:139]
	s_add_i32 m0, s41, 0xe000
	s_nop 0
	global_load_lds_dwordx4 v[144:145], off
	s_waitcnt vmcnt(8)
	s_waitcnt lgkmcnt(0)
	s_barrier
	s_waitcnt lgkmcnt(0)
	v_mfma_f32_16x16x32_bf16 v[124:127], v[152:155], v[184:187], v[124:127]
	v_mfma_f32_16x16x32_bf16 v[120:123], v[160:163], v[184:187], v[120:123]
	v_mfma_f32_16x16x32_bf16 v[116:119], v[152:155], v[192:195], v[116:119]
	v_mfma_f32_16x16x32_bf16 v[108:111], v[160:163], v[192:195], v[108:111]
	v_mfma_f32_16x16x32_bf16 v[100:103], v[152:155], v[200:203], v[100:103]
	v_mfma_f32_16x16x32_bf16 v[92:95], v[160:163], v[200:203], v[92:95]
	v_mfma_f32_16x16x32_bf16 v[84:87], v[152:155], v[212:215], v[84:87]
	v_mfma_f32_16x16x32_bf16 v[76:79], v[160:163], v[212:215], v[76:79]
	v_mfma_f32_16x16x32_bf16 v[124:127], v[156:159], v[188:191], v[124:127]
	v_mfma_f32_16x16x32_bf16 v[120:123], v[164:167], v[188:191], v[120:123]
	v_mfma_f32_16x16x32_bf16 v[116:119], v[156:159], v[196:199], v[116:119]
	v_mfma_f32_16x16x32_bf16 v[108:111], v[164:167], v[196:199], v[108:111]
	v_mfma_f32_16x16x32_bf16 v[100:103], v[156:159], v[204:207], v[100:103]
	v_mfma_f32_16x16x32_bf16 v[92:95], v[164:167], v[204:207], v[92:95]
	v_mfma_f32_16x16x32_bf16 v[84:87], v[156:159], v[216:219], v[84:87]
	v_mfma_f32_16x16x32_bf16 v[76:79], v[164:167], v[216:219], v[76:79]
	v_mfma_f32_16x16x32_bf16 v[112:115], v[168:171], v[184:187], v[112:115]
	v_mfma_f32_16x16x32_bf16 v[104:107], v[176:179], v[184:187], v[104:107]
	v_mfma_f32_16x16x32_bf16 v[96:99], v[168:171], v[192:195], v[96:99]
	v_mfma_f32_16x16x32_bf16 v[88:91], v[176:179], v[192:195], v[88:91]
	v_mfma_f32_16x16x32_bf16 v[80:83], v[168:171], v[200:203], v[80:83]
	v_mfma_f32_16x16x32_bf16 v[72:75], v[176:179], v[200:203], v[72:75]
	v_mfma_f32_16x16x32_bf16 v[68:71], v[168:171], v[212:215], v[68:71]
	v_mfma_f32_16x16x32_bf16 v[64:67], v[176:179], v[212:215], v[64:67]
	v_mfma_f32_16x16x32_bf16 v[112:115], v[172:175], v[188:191], v[112:115]
	v_mfma_f32_16x16x32_bf16 v[104:107], v[180:183], v[188:191], v[104:107]
	v_mfma_f32_16x16x32_bf16 v[96:99], v[172:175], v[196:199], v[96:99]
	v_mfma_f32_16x16x32_bf16 v[88:91], v[180:183], v[196:199], v[88:91]
	v_mfma_f32_16x16x32_bf16 v[80:83], v[172:175], v[204:207], v[80:83]
	v_mfma_f32_16x16x32_bf16 v[72:75], v[180:183], v[204:207], v[72:75]
	v_mfma_f32_16x16x32_bf16 v[68:71], v[172:175], v[216:219], v[68:71]
	v_mfma_f32_16x16x32_bf16 v[64:67], v[180:183], v[216:219], v[64:67]
	s_barrier
	s_add_i32 s76, s58, s3
	v_lshl_add_u64 v[144:145], s[46:47], 0, v[132:133]
	s_mov_b32 m0, s76
	ds_read_b128 v[184:187], v151 offset:16384
	ds_read_b128 v[188:191], v151 offset:17408
	ds_read_b128 v[192:195], v151 offset:18432
	ds_read_b128 v[196:199], v151 offset:19456
	ds_read_b128 v[200:203], v151 offset:20480
	ds_read_b128 v[204:207], v151 offset:21504
	ds_read_b128 v[212:215], v151 offset:22528
	ds_read_b128 v[216:219], v151 offset:23552
	global_load_lds_dwordx4 v[144:145], off
	s_add_i32 m0, s76, 0x2000
	s_add_u32 s76, s46, 0x40000
	v_lshl_add_u64 v[208:209], s[46:47], 0, v[128:129]
	s_addc_u32 s77, s47, 0
	s_add_i32 s78, s59, s3
	global_load_lds_dwordx4 v[208:209], off
	v_lshl_add_u64 v[220:221], s[76:77], 0, v[132:133]
	s_mov_b32 m0, s78
	v_lshl_add_u64 v[222:223], s[48:49], 0, v[130:131]
	global_load_lds_dwordx4 v[220:221], off
	v_lshl_add_u64 v[220:221], s[76:77], 0, v[128:129]
	s_add_i32 m0, s78, 0x2000
	s_nop 0
	global_load_lds_dwordx4 v[220:221], off
	v_lshl_add_u64 v[220:221], s[48:49], 0, v[134:135]
	s_mov_b32 m0, s41
	s_nop 0
	global_load_lds_dwordx4 v[220:221], off
	s_mov_b32 m0, s50
	s_nop 0
	global_load_lds_dwordx4 v[222:223], off
	s_waitcnt vmcnt(8)
	s_waitcnt lgkmcnt(0)
	s_barrier
; #define PG8_STAGE(bufoff, gbase, voff) do { _Pragma("unroll") for (int _i = 0; _i < 2; ++_i) \
;         __builtin_amdgcn_global_load_lds((const unsigned*)((const char*)(gbase) + (voff)[_i]), (PG8_LAS unsigned*)(lds + (bufoff) + ldsw + _i * 8192), 16, 0, 0); } while (0)
; #define PG8_LDA(dst, b, h) do { _Pragma("unroll") for (int m = 0; m < 4; ++m) _Pragma("unroll") for (int k = 0; k < 2; ++k) dst[m][k] = *(const PG8_LAS bf16x8*)(lds + PG8_SA(b, h) + aoff + m * 2048 + k * 1024); } while (0)
; #define PG8_LDB(dst, b, h) do { _Pragma("unroll") for (int n = 0; n < 2; ++n) _Pragma("unroll") for (int k = 0; k < 2; ++k) dst[n][k] = *(const PG8_LAS bf16x8*)(lds + PG8_SB(b, h) + boff + n * 2048 + k * 1024); } while (0)
; #define PG8_MMA(ai, bj, At, Bt) do { __builtin_amdgcn_s_setprio(1); _Pragma("unroll") for (int m = 0; m < 4; ++m) _Pragma("unroll") for (int n = 0; n < 2; ++n) _Pragma("unroll") for (int k = 0; k < 2; ++k) \
;         acc[ai][bj][m][n] = __builtin_amdgcn_mfma_f32_16x16x32_bf16(Bt[n][k], At[m][k], acc[ai][bj][m][n], 0, 0, 0); __builtin_amdgcn_s_setprio(0); } while (0)
; #define PG8_WAIT_V(n) asm volatile("s_waitcnt vmcnt(" #n ")" ::: "memory")
; #define PG8_WAIT_L(n) asm volatile("s_waitcnt lgkmcnt(" #n ")" ::: "memory")
; #define PG8_BAR __builtin_amdgcn_s_barrier()
; #define PG8_SCHED __builtin_amdgcn_sched_barrier(0)
; template <class Epi, class Sched, bool ALIGN_EPI = false, bool SP2 = false, bool AROWS128 = false>
; __device__ __forceinline__ void gemm_phase(PG8_LAS unsigned char* lds, const Gemm g, const Sched& S, const Epi& E) {
;     ...
;             PG8_WAIT_V(8); PG8_WAIT_L(0); PG8_BAR; PG8_MMA(1, 0, At, B0); PG8_MMA(1, 1, At, B1); PG8_BAR; PG8_SCHED;
;             PG8_LDB(B0, 1, 0); PG8_LDB(B1, 1, 1); PG8_SCHED; PG8_LDA(At, 1, 0); PG8_STAGE(PG8_SA(0, 1), a2 + hstepA, voffA);
;             PG8_WAIT_V(8); PG8_WAIT_L(0); PG8_BAR; PG8_MMA(0, 0, At, B0); PG8_MMA(0, 1, At, B1); PG8_BAR; PG8_SCHED;
	s_waitcnt lgkmcnt(0)
	v_mfma_f32_16x16x32_bf16 v[60:63], v[152:155], v[184:187], v[60:63]
	v_mfma_f32_16x16x32_bf16 v[56:59], v[160:163], v[184:187], v[56:59]
	v_mfma_f32_16x16x32_bf16 v[52:55], v[152:155], v[192:195], v[52:55]
	v_mfma_f32_16x16x32_bf16 v[44:47], v[160:163], v[192:195], v[44:47]
	v_mfma_f32_16x16x32_bf16 v[36:39], v[152:155], v[200:203], v[36:39]
	v_mfma_f32_16x16x32_bf16 v[28:31], v[160:163], v[200:203], v[28:31]
	v_mfma_f32_16x16x32_bf16 v[20:23], v[152:155], v[212:215], v[20:23]
	v_mfma_f32_16x16x32_bf16 v[12:15], v[160:163], v[212:215], v[12:15]
	v_mfma_f32_16x16x32_bf16 v[60:63], v[156:159], v[188:191], v[60:63]
	v_mfma_f32_16x16x32_bf16 v[56:59], v[164:167], v[188:191], v[56:59]
	v_mfma_f32_16x16x32_bf16 v[52:55], v[156:159], v[196:199], v[52:55]
	v_mfma_f32_16x16x32_bf16 v[44:47], v[164:167], v[196:199], v[44:47]
	v_mfma_f32_16x16x32_bf16 v[36:39], v[156:159], v[204:207], v[36:39]
	v_mfma_f32_16x16x32_bf16 v[28:31], v[164:167], v[204:207], v[28:31]
	v_mfma_f32_16x16x32_bf16 v[20:23], v[156:159], v[216:219], v[20:23]
	v_mfma_f32_16x16x32_bf16 v[12:15], v[164:167], v[216:219], v[12:15]
	v_mfma_f32_16x16x32_bf16 v[48:51], v[168:171], v[184:187], v[48:51]
	v_mfma_f32_16x16x32_bf16 v[40:43], v[176:179], v[184:187], v[40:43]
	v_mfma_f32_16x16x32_bf16 v[32:35], v[168:171], v[192:195], v[32:35]
	v_mfma_f32_16x16x32_bf16 v[24:27], v[176:179], v[192:195], v[24:27]
	v_mfma_f32_16x16x32_bf16 v[16:19], v[168:171], v[200:203], v[16:19]
	v_mfma_f32_16x16x32_bf16 v[8:11], v[176:179], v[200:203], v[8:11]
	v_mfma_f32_16x16x32_bf16 v[4:7], v[168:171], v[212:215], v[4:7]
	v_mfma_f32_16x16x32_bf16 v[0:3], v[176:179], v[212:215], v[0:3]
	v_mfma_f32_16x16x32_bf16 v[48:51], v[172:175], v[188:191], v[48:51]
	v_mfma_f32_16x16x32_bf16 v[40:43], v[180:183], v[188:191], v[40:43]
	v_mfma_f32_16x16x32_bf16 v[32:35], v[172:175], v[196:199], v[32:35]
	v_mfma_f32_16x16x32_bf16 v[24:27], v[180:183], v[196:199], v[24:27]
	v_mfma_f32_16x16x32_bf16 v[16:19], v[172:175], v[204:207], v[16:19]
	v_mfma_f32_16x16x32_bf16 v[8:11], v[180:183], v[204:207], v[8:11]
	v_mfma_f32_16x16x32_bf16 v[4:7], v[172:175], v[216:219], v[4:7]
	v_mfma_f32_16x16x32_bf16 v[0:3], v[180:183], v[216:219], v[0:3]
	s_barrier
	s_add_i32 s76, 0, 0x18000
	s_add_i32 s77, 0, 0x1c000
	v_add_u32_e32 v164, s76, v147
	v_add_u32_e32 v180, s77, v147
	ds_read_b128 v[152:155], v164
	ds_read_b128 v[156:159], v164 offset:1024
	ds_read_b128 v[160:163], v164 offset:2048
	ds_read_b128 v[164:167], v164 offset:3072
	ds_read_b128 v[168:171], v180
	ds_read_b128 v[172:175], v180 offset:1024
	ds_read_b128 v[176:179], v180 offset:2048
	ds_read_b128 v[180:183], v180 offset:3072
	s_add_u32 s48, s48, 0x40000
	s_addc_u32 s49, s49, 0
	s_mov_b32 m0, s51
	v_lshl_add_u64 v[224:225], s[48:49], 0, v[134:135]
	ds_read_b128 v[184:187], v151 offset:32768
	ds_read_b128 v[188:191], v151 offset:33792
	ds_read_b128 v[192:195], v151 offset:34816
	ds_read_b128 v[196:199], v151 offset:35840
	ds_read_b128 v[200:203], v151 offset:36864
	ds_read_b128 v[204:207], v151 offset:37888
	ds_read_b128 v[212:215], v151 offset:38912
	ds_read_b128 v[216:219], v151 offset:39936
	global_load_lds_dwordx4 v[224:225], off
	v_lshl_add_u64 v[224:225], s[48:49], 0, v[130:131]
	s_mov_b32 m0, s52
	s_nop 0
	global_load_lds_dwordx4 v[224:225], off
	s_waitcnt vmcnt(8)
	s_waitcnt lgkmcnt(0)
	s_barrier
	s_waitcnt lgkmcnt(0)
	v_mfma_f32_16x16x32_bf16 v[124:127], v[152:155], v[184:187], v[124:127]
	v_mfma_f32_16x16x32_bf16 v[120:123], v[160:163], v[184:187], v[120:123]
	v_mfma_f32_16x16x32_bf16 v[116:119], v[152:155], v[192:195], v[116:119]
	v_mfma_f32_16x16x32_bf16 v[108:111], v[160:163], v[192:195], v[108:111]
	v_mfma_f32_16x16x32_bf16 v[100:103], v[152:155], v[200:203], v[100:103]
	v_mfma_f32_16x16x32_bf16 v[92:95], v[160:163], v[200:203], v[92:95]
	v_mfma_f32_16x16x32_bf16 v[84:87], v[152:155], v[212:215], v[84:87]
	v_mfma_f32_16x16x32_bf16 v[76:79], v[160:163], v[212:215], v[76:79]
	v_mfma_f32_16x16x32_bf16 v[124:127], v[156:159], v[188:191], v[124:127]
	v_mfma_f32_16x16x32_bf16 v[120:123], v[164:167], v[188:191], v[120:123]
	v_mfma_f32_16x16x32_bf16 v[116:119], v[156:159], v[196:199], v[116:119]
	v_mfma_f32_16x16x32_bf16 v[108:111], v[164:167], v[196:199], v[108:111]
	v_mfma_f32_16x16x32_bf16 v[100:103], v[156:159], v[204:207], v[100:103]
	v_mfma_f32_16x16x32_bf16 v[92:95], v[164:167], v[204:207], v[92:95]
	v_mfma_f32_16x16x32_bf16 v[84:87], v[156:159], v[216:219], v[84:87]
	v_mfma_f32_16x16x32_bf16 v[76:79], v[164:167], v[216:219], v[76:79]
	v_mfma_f32_16x16x32_bf16 v[112:115], v[168:171], v[184:187], v[112:115]
	v_mfma_f32_16x16x32_bf16 v[104:107], v[176:179], v[184:187], v[104:107]
	v_mfma_f32_16x16x32_bf16 v[96:99], v[168:171], v[192:195], v[96:99]
	v_mfma_f32_16x16x32_bf16 v[88:91], v[176:179], v[192:195], v[88:91]
	v_mfma_f32_16x16x32_bf16 v[80:83], v[168:171], v[200:203], v[80:83]
	v_mfma_f32_16x16x32_bf16 v[72:75], v[176:179], v[200:203], v[72:75]
	v_mfma_f32_16x16x32_bf16 v[68:71], v[168:171], v[212:215], v[68:71]
	v_mfma_f32_16x16x32_bf16 v[64:67], v[176:179], v[212:215], v[64:67]
	v_mfma_f32_16x16x32_bf16 v[112:115], v[172:175], v[188:191], v[112:115]
	v_mfma_f32_16x16x32_bf16 v[104:107], v[180:183], v[188:191], v[104:107]
	v_mfma_f32_16x16x32_bf16 v[96:99], v[172:175], v[196:199], v[96:99]
	v_mfma_f32_16x16x32_bf16 v[88:91], v[180:183], v[196:199], v[88:91]
	v_mfma_f32_16x16x32_bf16 v[80:83], v[172:175], v[204:207], v[80:83]
	v_mfma_f32_16x16x32_bf16 v[72:75], v[180:183], v[204:207], v[72:75]
	v_mfma_f32_16x16x32_bf16 v[68:71], v[172:175], v[216:219], v[68:71]
	v_mfma_f32_16x16x32_bf16 v[64:67], v[180:183], v[216:219], v[64:67]
	s_barrier
; #define PG8_STAGE(bufoff, gbase, voff) do { _Pragma("unroll") for (int _i = 0; _i < 2; ++_i) \
;         __builtin_amdgcn_global_load_lds((const unsigned*)((const char*)(gbase) + (voff)[_i]), (PG8_LAS unsigned*)(lds + (bufoff) + ldsw + _i * 8192), 16, 0, 0); } while (0)
; #define PG8_LDA(dst, b, h) do { _Pragma("unroll") for (int m = 0; m < 4; ++m) _Pragma("unroll") for (int k = 0; k < 2; ++k) dst[m][k] = *(const PG8_LAS bf16x8*)(lds + PG8_SA(b, h) + aoff + m * 2048 + k * 1024); } while (0)
; #define PG8_MMA(ai, bj, At, Bt) do { __builtin_amdgcn_s_setprio(1); _Pragma("unroll") for (int m = 0; m < 4; ++m) _Pragma("unroll") for (int n = 0; n < 2; ++n) _Pragma("unroll") for (int k = 0; k < 2; ++k) \
;         acc[ai][bj][m][n] = __builtin_amdgcn_mfma_f32_16x16x32_bf16(Bt[n][k], At[m][k], acc[ai][bj][m][n], 0, 0, 0); __builtin_amdgcn_s_setprio(0); } while (0)
; #define PG8_WAIT_V(n) asm volatile("s_waitcnt vmcnt(" #n ")" ::: "memory")
; #define PG8_WAIT_L(n) asm volatile("s_waitcnt lgkmcnt(" #n ")" ::: "memory")
; #define PG8_BAR __builtin_amdgcn_s_barrier()
; #define PG8_SCHED __builtin_amdgcn_sched_barrier(0)
; template <class Epi, class Sched, bool ALIGN_EPI = false, bool SP2 = false, bool AROWS128 = false>
; __device__ __forceinline__ void gemm_phase(PG8_LAS unsigned char* lds, const Gemm g, const Sched& S, const Epi& E) {
;     ...
;         for (int t = 0; t < nt; t += 2) {
;             const bool last = (t == nt - 2);
;             const char* a1 = cA + (size_t)(t + 1) * kstep;
;             const char* a2 = last ? nA : cA + (size_t)(t + 2) * kstep; const char* b2 = last ? nB : cB + (size_t)(t + 2) * kstep;
;     ...
;             PG8_LDA(At, 1, 1); PG8_STAGE(PG8_SB(1, 0), b3, voffB); PG8_STAGE(PG8_SB(1, 1), b3 + hstep, voffB); PG8_STAGE(PG8_SA(1, 0), a3, voffA);
;             PG8_WAIT_V(8); PG8_WAIT_L(0); PG8_BAR; PG8_MMA(1, 0, At, B0); PG8_MMA(1, 1, At, B1); PG8_BAR; PG8_SCHED;
	s_add_i32 s48, s76, s3
	v_lshl_add_u64 v[144:145], v[144:145], 0, s[16:17]
	s_mov_b32 m0, s48
	ds_read_b128 v[184:187], v151 offset:49152
	ds_read_b128 v[188:191], v151 offset:50176
	ds_read_b128 v[192:195], v151 offset:51200
	ds_read_b128 v[196:199], v151 offset:52224
	ds_read_b128 v[200:203], v151 offset:53248
	ds_read_b128 v[204:207], v151 offset:54272
	ds_read_b128 v[212:215], v151 offset:55296
	ds_read_b128 v[216:219], v151 offset:56320
	global_load_lds_dwordx4 v[144:145], off
	s_add_i32 m0, s48, 0x2000
	s_add_u32 s46, s46, 0x40080
	v_lshl_add_u64 v[144:145], v[208:209], 0, s[16:17]
	s_addc_u32 s47, s47, 0
	s_add_i32 s48, s77, s3
	global_load_lds_dwordx4 v[144:145], off
	v_lshl_add_u64 v[144:145], s[46:47], 0, v[132:133]
	s_mov_b32 m0, s48
	s_nop 0
	global_load_lds_dwordx4 v[144:145], off
	v_lshl_add_u64 v[144:145], s[46:47], 0, v[128:129]
	s_add_i32 m0, s48, 0x2000
	s_nop 0
	global_load_lds_dwordx4 v[144:145], off
	v_lshl_add_u64 v[144:145], v[220:221], 0, s[16:17]
	s_mov_b32 m0, s54
	s_nop 0
	global_load_lds_dwordx4 v[144:145], off
	v_lshl_add_u64 v[144:145], v[222:223], 0, s[16:17]
	s_mov_b32 m0, s55
	s_nop 0
	global_load_lds_dwordx4 v[144:145], off
	s_waitcnt vmcnt(8)
	s_waitcnt lgkmcnt(0)
	s_barrier
	s_waitcnt lgkmcnt(0)
	v_mfma_f32_16x16x32_bf16 v[60:63], v[152:155], v[184:187], v[60:63]
	v_mfma_f32_16x16x32_bf16 v[56:59], v[160:163], v[184:187], v[56:59]
	v_mfma_f32_16x16x32_bf16 v[52:55], v[152:155], v[192:195], v[52:55]
	v_mfma_f32_16x16x32_bf16 v[44:47], v[160:163], v[192:195], v[44:47]
	v_mfma_f32_16x16x32_bf16 v[36:39], v[152:155], v[200:203], v[36:39]
	v_mfma_f32_16x16x32_bf16 v[28:31], v[160:163], v[200:203], v[28:31]
	v_mfma_f32_16x16x32_bf16 v[20:23], v[152:155], v[212:215], v[20:23]
	v_mfma_f32_16x16x32_bf16 v[12:15], v[160:163], v[212:215], v[12:15]
	v_mfma_f32_16x16x32_bf16 v[60:63], v[156:159], v[188:191], v[60:63]
	v_mfma_f32_16x16x32_bf16 v[56:59], v[164:167], v[188:191], v[56:59]
	v_mfma_f32_16x16x32_bf16 v[52:55], v[156:159], v[196:199], v[52:55]
	v_mfma_f32_16x16x32_bf16 v[44:47], v[164:167], v[196:199], v[44:47]
	v_mfma_f32_16x16x32_bf16 v[36:39], v[156:159], v[204:207], v[36:39]
	v_mfma_f32_16x16x32_bf16 v[28:31], v[164:167], v[204:207], v[28:31]
	v_mfma_f32_16x16x32_bf16 v[20:23], v[156:159], v[216:219], v[20:23]
	v_mfma_f32_16x16x32_bf16 v[12:15], v[164:167], v[216:219], v[12:15]
	v_mfma_f32_16x16x32_bf16 v[48:51], v[168:171], v[184:187], v[48:51]
	v_mfma_f32_16x16x32_bf16 v[40:43], v[176:179], v[184:187], v[40:43]
	v_mfma_f32_16x16x32_bf16 v[32:35], v[168:171], v[192:195], v[32:35]
	v_mfma_f32_16x16x32_bf16 v[24:27], v[176:179], v[192:195], v[24:27]
	v_mfma_f32_16x16x32_bf16 v[16:19], v[168:171], v[200:203], v[16:19]
	v_mfma_f32_16x16x32_bf16 v[8:11], v[176:179], v[200:203], v[8:11]
	v_mfma_f32_16x16x32_bf16 v[4:7], v[168:171], v[212:215], v[4:7]
	v_mfma_f32_16x16x32_bf16 v[0:3], v[176:179], v[212:215], v[0:3]
	v_mfma_f32_16x16x32_bf16 v[48:51], v[172:175], v[188:191], v[48:51]
	v_mfma_f32_16x16x32_bf16 v[40:43], v[180:183], v[188:191], v[40:43]
	v_mfma_f32_16x16x32_bf16 v[32:35], v[172:175], v[196:199], v[32:35]
	v_mfma_f32_16x16x32_bf16 v[24:27], v[180:183], v[196:199], v[24:27]
	v_mfma_f32_16x16x32_bf16 v[16:19], v[172:175], v[204:207], v[16:19]
	v_mfma_f32_16x16x32_bf16 v[8:11], v[180:183], v[204:207], v[8:11]
	v_mfma_f32_16x16x32_bf16 v[4:7], v[172:175], v[216:219], v[4:7]
	v_mfma_f32_16x16x32_bf16 v[0:3], v[180:183], v[216:219], v[0:3]
	s_barrier
	s_add_i32 s73, s73, 2
	s_add_u32 s42, s42, 0x100
	s_addc_u32 s43, s43, 0
	s_add_u32 s67, s67, 0x100
	s_addc_u32 s72, s72, 0
	s_cmp_gt_u32 s73, 13
	s_cbranch_scc0 .LBB0_886
	s_and_b64 vcc, exec, s[18:19]
	s_cbranch_vccz .LBB0_889
	s_barrier

; #define PG8_STAGE(bufoff, gbase, voff) do { _Pragma("unroll") for (int _i = 0; _i < 2; ++_i) \
;         __builtin_amdgcn_global_load_lds((const unsigned*)((const char*)(gbase) + (voff)[_i]), (PG8_LAS unsigned*)(lds + (bufoff) + ldsw + _i * 8192), 16, 0, 0); } while (0)
; #define PG8_LDA(dst, b, h) do { _Pragma("unroll") for (int m = 0; m < 4; ++m) _Pragma("unroll") for (int k = 0; k < 2; ++k) dst[m][k] = *(const PG8_LAS bf16x8*)(lds + PG8_SA(b, h) + aoff + m * 2048 + k * 1024); } while (0)
; #define PG8_LDB(dst, b, h) do { _Pragma("unroll") for (int n = 0; n < 2; ++n) _Pragma("unroll") for (int k = 0; k < 2; ++k) dst[n][k] = *(const PG8_LAS bf16x8*)(lds + PG8_SB(b, h) + boff + n * 2048 + k * 1024); } while (0)
; #define PG8_WAIT_V(n) asm volatile("s_waitcnt vmcnt(" #n ")" ::: "memory")
; #define PG8_WAIT_L(n) asm volatile("s_waitcnt lgkmcnt(" #n ")" ::: "memory")
; #define PG8_BAR __builtin_amdgcn_s_barrier()
; #define PG8_SCHED __builtin_amdgcn_sched_barrier(0)
; template <class Epi, class Sched, bool ALIGN_EPI = false, bool SP2 = false, bool AROWS128 = false>
; __device__ __forceinline__ void gemm_phase(PG8_LAS unsigned char* lds, const Gemm g, const Sched& S, const Epi& E) {
;     ...
;         const bool has_next = S.next(ui + 1, nxt);
;         const char* nA = has_next ? (const char*)g.A + (size_t)nxt.pm * tstep : cA; const char* nB = has_next ? (const char*)g.Bt + (size_t)nxt.pn * tstep : cB;
;         for (int t = 0; t < nt; t += 2) {
;             const bool last = (t == nt - 2);
;             const char* a1 = cA + (size_t)(t + 1) * kstep;
;             const char* a2 = last ? nA : cA + (size_t)(t + 2) * kstep; const char* b2 = last ? nB : cB + (size_t)(t + 2) * kstep;
;             const char* a3 = a2 + kstep; const char* b3 = b2 + kstep;
;             if (last && has_next) S.a_ready(nxt);
;             if constexpr (SP2) {
;             PG8_LDB(B0, 0, 0); PG8_LDB(B1, 0, 1); PG8_SCHED; PG8_LDA(At, 0, 0); PG8_STAGE(PG8_SA(1, 1), a1 + hstepA, voffA);
;             PG8_WAIT_V(8); PG8_WAIT_L(0); PG8_BAR; PG8_MMA(0, 0, At, B0); PG8_MMA(0, 1, At, B1); PG8_BAR; PG8_SCHED;
;             PG8_LDA(At, 0, 1); PG8_STAGE(PG8_SB(0, 0), b2, voffB); PG8_STAGE(PG8_SB(0, 1), b2 + hstep, voffB); PG8_STAGE(PG8_SA(0, 0), a2, voffA);
;             PG8_WAIT_V(8); PG8_WAIT_L(0); PG8_BAR; PG8_MMA(1, 0, At, B0); PG8_MMA(1, 1, At, B1); PG8_BAR; PG8_SCHED;
.LBB0_902:
	s_add_u32 s47, s40, s46
	s_addc_u32 s52, s41, 0
	s_add_u32 s50, s47, 0x100
	s_addc_u32 s51, s52, 0
	s_and_b64 s[48:49], s[44:45], exec
	s_cselect_b32 s49, s27, s51
	s_cselect_b32 s48, s79, s50
	s_add_u32 s46, s38, s46
	s_addc_u32 s50, s39, 0
	s_add_u32 s46, s46, 0x100
	s_addc_u32 s50, s50, 0
	s_and_b64 s[44:45], s[44:45], exec
	s_cselect_b32 s51, s25, s50
	s_cselect_b32 s50, s80, s46
	s_add_u32 s54, s47, 0x10080
	ds_read_b128 v[148:151], v145
	ds_read_b128 v[152:155], v145 offset:1024
	ds_read_b128 v[156:159], v145 offset:2048
	ds_read_b128 v[160:163], v145 offset:3072
	ds_read_b128 v[164:167], v146
	ds_read_b128 v[168:171], v146 offset:1024
	ds_read_b128 v[172:175], v146 offset:2048
	ds_read_b128 v[176:179], v146 offset:3072
	s_addc_u32 s55, s52, 0
	s_add_i32 s88, s66, s3
	s_add_i32 m0, s37, 0xc000
	s_add_i32 s91, s37, 0xe000
	s_add_i32 s85, s88, 0x2000
	s_add_u32 s52, s50, 0x10000
	s_addc_u32 s53, s51, 0
	s_add_i32 s87, s67, s3
	s_add_i32 s86, s87, 0x2000
	s_add_i32 s84, 0, 0x18000
	s_add_i32 s83, 0, 0x1c000
	s_add_u32 s46, s48, 0x10000
	s_addc_u32 s47, s49, 0
	s_add_i32 s82, s84, s3
	s_add_i32 s81, s82, 0x2000
	s_add_u32 s44, s50, 0x10080
	s_addc_u32 s45, s51, 0
	s_add_i32 s90, s83, s3
	s_add_i32 s89, s90, 0x2000
	v_lshl_add_u64 v[140:141], s[54:55], 0, v[134:135]
	ds_read_b128 v[180:183], v147
	ds_read_b128 v[184:187], v147 offset:1024
	ds_read_b128 v[188:191], v147 offset:2048
	ds_read_b128 v[192:195], v147 offset:3072
	ds_read_b128 v[196:199], v147 offset:4096
	ds_read_b128 v[200:203], v147 offset:5120
	ds_read_b128 v[204:207], v147 offset:6144
	ds_read_b128 v[212:215], v147 offset:7168
	global_load_lds_dwordx4 v[140:141], off
	v_lshl_add_u64 v[140:141], s[54:55], 0, v[130:131]
	s_mov_b32 m0, s91
	s_nop 0
	global_load_lds_dwordx4 v[140:141], off
	s_waitcnt vmcnt(8)
	s_waitcnt lgkmcnt(0)
	s_barrier
	s_waitcnt lgkmcnt(0)
	v_mfma_f32_16x16x32_bf16 v[124:127], v[148:151], v[180:183], v[124:127]
	v_mfma_f32_16x16x32_bf16 v[120:123], v[156:159], v[180:183], v[120:123]
	v_mfma_f32_16x16x32_bf16 v[116:119], v[148:151], v[188:191], v[116:119]
	v_mfma_f32_16x16x32_bf16 v[108:111], v[156:159], v[188:191], v[108:111]
	v_mfma_f32_16x16x32_bf16 v[100:103], v[148:151], v[196:199], v[100:103]
	v_mfma_f32_16x16x32_bf16 v[92:95], v[156:159], v[196:199], v[92:95]
	v_mfma_f32_16x16x32_bf16 v[84:87], v[148:151], v[204:207], v[84:87]
	v_mfma_f32_16x16x32_bf16 v[76:79], v[156:159], v[204:207], v[76:79]
	v_mfma_f32_16x16x32_bf16 v[124:127], v[152:155], v[184:187], v[124:127]
	v_mfma_f32_16x16x32_bf16 v[120:123], v[160:163], v[184:187], v[120:123]
	v_mfma_f32_16x16x32_bf16 v[116:119], v[152:155], v[192:195], v[116:119]
	v_mfma_f32_16x16x32_bf16 v[108:111], v[160:163], v[192:195], v[108:111]
	v_mfma_f32_16x16x32_bf16 v[100:103], v[152:155], v[200:203], v[100:103]
	v_mfma_f32_16x16x32_bf16 v[92:95], v[160:163], v[200:203], v[92:95]
	v_mfma_f32_16x16x32_bf16 v[84:87], v[152:155], v[212:215], v[84:87]
	v_mfma_f32_16x16x32_bf16 v[76:79], v[160:163], v[212:215], v[76:79]
	v_mfma_f32_16x16x32_bf16 v[112:115], v[164:167], v[180:183], v[112:115]
	v_mfma_f32_16x16x32_bf16 v[104:107], v[172:175], v[180:183], v[104:107]
	v_mfma_f32_16x16x32_bf16 v[96:99], v[164:167], v[188:191], v[96:99]
	v_mfma_f32_16x16x32_bf16 v[88:91], v[172:175], v[188:191], v[88:91]
	v_mfma_f32_16x16x32_bf16 v[80:83], v[164:167], v[196:199], v[80:83]
	v_mfma_f32_16x16x32_bf16 v[72:75], v[172:175], v[196:199], v[72:75]
	v_mfma_f32_16x16x32_bf16 v[68:71], v[164:167], v[204:207], v[68:71]
	v_mfma_f32_16x16x32_bf16 v[64:67], v[172:175], v[204:207], v[64:67]
	v_mfma_f32_16x16x32_bf16 v[112:115], v[168:171], v[184:187], v[112:115]
	v_mfma_f32_16x16x32_bf16 v[104:107], v[176:179], v[184:187], v[104:107]
	v_mfma_f32_16x16x32_bf16 v[96:99], v[168:171], v[192:195], v[96:99]
	v_mfma_f32_16x16x32_bf16 v[88:91], v[176:179], v[192:195], v[88:91]
	v_mfma_f32_16x16x32_bf16 v[80:83], v[168:171], v[200:203], v[80:83]
	v_mfma_f32_16x16x32_bf16 v[72:75], v[176:179], v[200:203], v[72:75]
	v_mfma_f32_16x16x32_bf16 v[68:71], v[168:171], v[212:215], v[68:71]
	v_mfma_f32_16x16x32_bf16 v[64:67], v[176:179], v[212:215], v[64:67]
	s_barrier
	s_mov_b32 m0, s88
	v_lshl_add_u64 v[140:141], s[50:51], 0, v[132:133]
	ds_read_b128 v[180:183], v147 offset:16384
	ds_read_b128 v[184:187], v147 offset:17408
	ds_read_b128 v[188:191], v147 offset:18432
	ds_read_b128 v[192:195], v147 offset:19456
	ds_read_b128 v[196:199], v147 offset:20480
	ds_read_b128 v[200:203], v147 offset:21504
	ds_read_b128 v[204:207], v147 offset:22528
	ds_read_b128 v[212:215], v147 offset:23552
	global_load_lds_dwordx4 v[140:141], off
	v_lshl_add_u64 v[208:209], s[50:51], 0, v[128:129]
	s_mov_b32 m0, s85
	v_lshl_add_u64 v[216:217], s[52:53], 0, v[132:133]
	global_load_lds_dwordx4 v[208:209], off
	s_mov_b32 m0, s87
	v_lshl_add_u64 v[218:219], s[48:49], 0, v[130:131]
	global_load_lds_dwordx4 v[216:217], off
	v_lshl_add_u64 v[216:217], s[52:53], 0, v[128:129]
	s_mov_b32 m0, s86
	s_nop 0
	global_load_lds_dwordx4 v[216:217], off
	v_lshl_add_u64 v[216:217], s[48:49], 0, v[134:135]
	s_mov_b32 m0, s37
	s_nop 0
	global_load_lds_dwordx4 v[216:217], off
	s_mov_b32 m0, s58
	s_nop 0
	global_load_lds_dwordx4 v[218:219], off
	s_waitcnt vmcnt(8)
	s_waitcnt lgkmcnt(0)
	s_barrier
; #define PG8_STAGE(bufoff, gbase, voff) do { _Pragma("unroll") for (int _i = 0; _i < 2; ++_i) \
;         __builtin_amdgcn_global_load_lds((const unsigned*)((const char*)(gbase) + (voff)[_i]), (PG8_LAS unsigned*)(lds + (bufoff) + ldsw + _i * 8192), 16, 0, 0); } while (0)
; #define PG8_LDA(dst, b, h) do { _Pragma("unroll") for (int m = 0; m < 4; ++m) _Pragma("unroll") for (int k = 0; k < 2; ++k) dst[m][k] = *(const PG8_LAS bf16x8*)(lds + PG8_SA(b, h) + aoff + m * 2048 + k * 1024); } while (0)
; #define PG8_LDB(dst, b, h) do { _Pragma("unroll") for (int n = 0; n < 2; ++n) _Pragma("unroll") for (int k = 0; k < 2; ++k) dst[n][k] = *(const PG8_LAS bf16x8*)(lds + PG8_SB(b, h) + boff + n * 2048 + k * 1024); } while (0)
; #define PG8_MMA(ai, bj, At, Bt) do { __builtin_amdgcn_s_setprio(1); _Pragma("unroll") for (int m = 0; m < 4; ++m) _Pragma("unroll") for (int n = 0; n < 2; ++n) _Pragma("unroll") for (int k = 0; k < 2; ++k) \
;         acc[ai][bj][m][n] = __builtin_amdgcn_mfma_f32_16x16x32_bf16(Bt[n][k], At[m][k], acc[ai][bj][m][n], 0, 0, 0); __builtin_amdgcn_s_setprio(0); } while (0)
; #define PG8_WAIT_V(n) asm volatile("s_waitcnt vmcnt(" #n ")" ::: "memory")
; #define PG8_WAIT_L(n) asm volatile("s_waitcnt lgkmcnt(" #n ")" ::: "memory")
; #define PG8_BAR __builtin_amdgcn_s_barrier()
; #define PG8_SCHED __builtin_amdgcn_sched_barrier(0)
; template <class Epi, class Sched, bool ALIGN_EPI = false, bool SP2 = false, bool AROWS128 = false>
; __device__ __forceinline__ void gemm_phase(PG8_LAS unsigned char* lds, const Gemm g, const Sched& S, const Epi& E) {
;     ...
;             PG8_WAIT_V(8); PG8_WAIT_L(0); PG8_BAR; PG8_MMA(1, 0, At, B0); PG8_MMA(1, 1, At, B1); PG8_BAR; PG8_SCHED;
;             PG8_LDB(B0, 1, 0); PG8_LDB(B1, 1, 1); PG8_SCHED; PG8_LDA(At, 1, 0); PG8_STAGE(PG8_SA(0, 1), a2 + hstepA, voffA);
;             PG8_WAIT_V(8); PG8_WAIT_L(0); PG8_BAR; PG8_MMA(0, 0, At, B0); PG8_MMA(0, 1, At, B1); PG8_BAR; PG8_SCHED;
	s_waitcnt lgkmcnt(0)
	v_mfma_f32_16x16x32_bf16 v[60:63], v[148:151], v[180:183], v[60:63]
	v_mfma_f32_16x16x32_bf16 v[56:59], v[156:159], v[180:183], v[56:59]
	v_mfma_f32_16x16x32_bf16 v[52:55], v[148:151], v[188:191], v[52:55]
	v_mfma_f32_16x16x32_bf16 v[44:47], v[156:159], v[188:191], v[44:47]
	v_mfma_f32_16x16x32_bf16 v[36:39], v[148:151], v[196:199], v[36:39]
	v_mfma_f32_16x16x32_bf16 v[28:31], v[156:159], v[196:199], v[28:31]
	v_mfma_f32_16x16x32_bf16 v[20:23], v[148:151], v[204:207], v[20:23]
	v_mfma_f32_16x16x32_bf16 v[12:15], v[156:159], v[204:207], v[12:15]
	v_mfma_f32_16x16x32_bf16 v[60:63], v[152:155], v[184:187], v[60:63]
	v_mfma_f32_16x16x32_bf16 v[56:59], v[160:163], v[184:187], v[56:59]
	v_mfma_f32_16x16x32_bf16 v[52:55], v[152:155], v[192:195], v[52:55]
	v_mfma_f32_16x16x32_bf16 v[44:47], v[160:163], v[192:195], v[44:47]
	v_mfma_f32_16x16x32_bf16 v[36:39], v[152:155], v[200:203], v[36:39]
	v_mfma_f32_16x16x32_bf16 v[28:31], v[160:163], v[200:203], v[28:31]
	v_mfma_f32_16x16x32_bf16 v[20:23], v[152:155], v[212:215], v[20:23]
	v_mfma_f32_16x16x32_bf16 v[12:15], v[160:163], v[212:215], v[12:15]
	v_mfma_f32_16x16x32_bf16 v[48:51], v[164:167], v[180:183], v[48:51]
	v_mfma_f32_16x16x32_bf16 v[40:43], v[172:175], v[180:183], v[40:43]
	v_mfma_f32_16x16x32_bf16 v[32:35], v[164:167], v[188:191], v[32:35]
	v_mfma_f32_16x16x32_bf16 v[24:27], v[172:175], v[188:191], v[24:27]
	v_mfma_f32_16x16x32_bf16 v[16:19], v[164:167], v[196:199], v[16:19]
	v_mfma_f32_16x16x32_bf16 v[8:11], v[172:175], v[196:199], v[8:11]
	v_mfma_f32_16x16x32_bf16 v[4:7], v[164:167], v[204:207], v[4:7]
	v_mfma_f32_16x16x32_bf16 v[0:3], v[172:175], v[204:207], v[0:3]
	v_mfma_f32_16x16x32_bf16 v[48:51], v[168:171], v[184:187], v[48:51]
	v_mfma_f32_16x16x32_bf16 v[40:43], v[176:179], v[184:187], v[40:43]
	v_mfma_f32_16x16x32_bf16 v[32:35], v[168:171], v[192:195], v[32:35]
	v_mfma_f32_16x16x32_bf16 v[24:27], v[176:179], v[192:195], v[24:27]
	v_mfma_f32_16x16x32_bf16 v[16:19], v[168:171], v[200:203], v[16:19]
	v_mfma_f32_16x16x32_bf16 v[8:11], v[176:179], v[200:203], v[8:11]
	v_mfma_f32_16x16x32_bf16 v[4:7], v[168:171], v[212:215], v[4:7]
	v_mfma_f32_16x16x32_bf16 v[0:3], v[176:179], v[212:215], v[0:3]
	s_barrier
	v_add_u32_e32 v160, s84, v143
	v_add_u32_e32 v176, s83, v143
	ds_read_b128 v[148:151], v160
	ds_read_b128 v[152:155], v160 offset:1024
	ds_read_b128 v[156:159], v160 offset:2048
	ds_read_b128 v[160:163], v160 offset:3072
	ds_read_b128 v[164:167], v176
	ds_read_b128 v[168:171], v176 offset:1024
	ds_read_b128 v[172:175], v176 offset:2048
	ds_read_b128 v[176:179], v176 offset:3072
	s_mov_b32 m0, s59
	v_lshl_add_u64 v[220:221], s[46:47], 0, v[134:135]
	ds_read_b128 v[180:183], v147 offset:32768
	ds_read_b128 v[184:187], v147 offset:33792
	ds_read_b128 v[188:191], v147 offset:34816
	ds_read_b128 v[192:195], v147 offset:35840
	ds_read_b128 v[196:199], v147 offset:36864
	ds_read_b128 v[200:203], v147 offset:37888
	ds_read_b128 v[204:207], v147 offset:38912
	ds_read_b128 v[212:215], v147 offset:39936
	global_load_lds_dwordx4 v[220:221], off
	v_lshl_add_u64 v[220:221], s[46:47], 0, v[130:131]
	s_mov_b32 m0, s60
	s_nop 0
	global_load_lds_dwordx4 v[220:221], off
	s_waitcnt vmcnt(8)
	s_waitcnt lgkmcnt(0)
	s_barrier
	s_waitcnt lgkmcnt(0)
	v_mfma_f32_16x16x32_bf16 v[124:127], v[148:151], v[180:183], v[124:127]
	v_mfma_f32_16x16x32_bf16 v[120:123], v[156:159], v[180:183], v[120:123]
	v_mfma_f32_16x16x32_bf16 v[116:119], v[148:151], v[188:191], v[116:119]
	v_mfma_f32_16x16x32_bf16 v[108:111], v[156:159], v[188:191], v[108:111]
	v_mfma_f32_16x16x32_bf16 v[100:103], v[148:151], v[196:199], v[100:103]
	v_mfma_f32_16x16x32_bf16 v[92:95], v[156:159], v[196:199], v[92:95]
	v_mfma_f32_16x16x32_bf16 v[84:87], v[148:151], v[204:207], v[84:87]
	v_mfma_f32_16x16x32_bf16 v[76:79], v[156:159], v[204:207], v[76:79]
	v_mfma_f32_16x16x32_bf16 v[124:127], v[152:155], v[184:187], v[124:127]
	v_mfma_f32_16x16x32_bf16 v[120:123], v[160:163], v[184:187], v[120:123]
	v_mfma_f32_16x16x32_bf16 v[116:119], v[152:155], v[192:195], v[116:119]
	v_mfma_f32_16x16x32_bf16 v[108:111], v[160:163], v[192:195], v[108:111]
	v_mfma_f32_16x16x32_bf16 v[100:103], v[152:155], v[200:203], v[100:103]
	v_mfma_f32_16x16x32_bf16 v[92:95], v[160:163], v[200:203], v[92:95]
	v_mfma_f32_16x16x32_bf16 v[84:87], v[152:155], v[212:215], v[84:87]
	v_mfma_f32_16x16x32_bf16 v[76:79], v[160:163], v[212:215], v[76:79]
	v_mfma_f32_16x16x32_bf16 v[112:115], v[164:167], v[180:183], v[112:115]
	v_mfma_f32_16x16x32_bf16 v[104:107], v[172:175], v[180:183], v[104:107]
	v_mfma_f32_16x16x32_bf16 v[96:99], v[164:167], v[188:191], v[96:99]
	v_mfma_f32_16x16x32_bf16 v[88:91], v[172:175], v[188:191], v[88:91]
	v_mfma_f32_16x16x32_bf16 v[80:83], v[164:167], v[196:199], v[80:83]
	v_mfma_f32_16x16x32_bf16 v[72:75], v[172:175], v[196:199], v[72:75]
	v_mfma_f32_16x16x32_bf16 v[68:71], v[164:167], v[204:207], v[68:71]
	v_mfma_f32_16x16x32_bf16 v[64:67], v[172:175], v[204:207], v[64:67]
	v_mfma_f32_16x16x32_bf16 v[112:115], v[168:171], v[184:187], v[112:115]
	v_mfma_f32_16x16x32_bf16 v[104:107], v[176:179], v[184:187], v[104:107]
	v_mfma_f32_16x16x32_bf16 v[96:99], v[168:171], v[192:195], v[96:99]
	v_mfma_f32_16x16x32_bf16 v[88:91], v[176:179], v[192:195], v[88:91]
	v_mfma_f32_16x16x32_bf16 v[80:83], v[168:171], v[200:203], v[80:83]
	v_mfma_f32_16x16x32_bf16 v[72:75], v[176:179], v[200:203], v[72:75]
	v_mfma_f32_16x16x32_bf16 v[68:71], v[168:171], v[212:215], v[68:71]
	v_mfma_f32_16x16x32_bf16 v[64:67], v[176:179], v[212:215], v[64:67]
	s_barrier
; #define PG8_STAGE(bufoff, gbase, voff) do { _Pragma("unroll") for (int _i = 0; _i < 2; ++_i) \
;         __builtin_amdgcn_global_load_lds((const unsigned*)((const char*)(gbase) + (voff)[_i]), (PG8_LAS unsigned*)(lds + (bufoff) + ldsw + _i * 8192), 16, 0, 0); } while (0)
; #define PG8_LDA(dst, b, h) do { _Pragma("unroll") for (int m = 0; m < 4; ++m) _Pragma("unroll") for (int k = 0; k < 2; ++k) dst[m][k] = *(const PG8_LAS bf16x8*)(lds + PG8_SA(b, h) + aoff + m * 2048 + k * 1024); } while (0)
; #define PG8_MMA(ai, bj, At, Bt) do { __builtin_amdgcn_s_setprio(1); _Pragma("unroll") for (int m = 0; m < 4; ++m) _Pragma("unroll") for (int n = 0; n < 2; ++n) _Pragma("unroll") for (int k = 0; k < 2; ++k) \
;         acc[ai][bj][m][n] = __builtin_amdgcn_mfma_f32_16x16x32_bf16(Bt[n][k], At[m][k], acc[ai][bj][m][n], 0, 0, 0); __builtin_amdgcn_s_setprio(0); } while (0)
; #define PG8_WAIT_V(n) asm volatile("s_waitcnt vmcnt(" #n ")" ::: "memory")
; #define PG8_WAIT_L(n) asm volatile("s_waitcnt lgkmcnt(" #n ")" ::: "memory")
; #define PG8_BAR __builtin_amdgcn_s_barrier()
; #define PG8_SCHED __builtin_amdgcn_sched_barrier(0)
; template <class Epi, class Sched, bool ALIGN_EPI = false, bool SP2 = false, bool AROWS128 = false>
; __device__ __forceinline__ void gemm_phase(PG8_LAS unsigned char* lds, const Gemm g, const Sched& S, const Epi& E) {
;     ...
;             PG8_LDA(At, 1, 1); PG8_STAGE(PG8_SB(1, 0), b3, voffB); PG8_STAGE(PG8_SB(1, 1), b3 + hstep, voffB); PG8_STAGE(PG8_SA(1, 0), a3, voffA);
;             PG8_WAIT_V(8); PG8_WAIT_L(0); PG8_BAR; PG8_MMA(1, 0, At, B0); PG8_MMA(1, 1, At, B1); PG8_BAR; PG8_SCHED;
	s_mov_b32 m0, s82
	v_lshl_add_u64 v[140:141], v[140:141], 0, s[10:11]
	ds_read_b128 v[180:183], v147 offset:49152
	ds_read_b128 v[184:187], v147 offset:50176
	ds_read_b128 v[188:191], v147 offset:51200
	ds_read_b128 v[192:195], v147 offset:52224
	ds_read_b128 v[196:199], v147 offset:53248
	ds_read_b128 v[200:203], v147 offset:54272
	ds_read_b128 v[204:207], v147 offset:55296
	ds_read_b128 v[212:215], v147 offset:56320
	global_load_lds_dwordx4 v[140:141], off
	v_lshl_add_u64 v[140:141], v[208:209], 0, s[10:11]
	s_mov_b32 m0, s81
	s_nop 0
	global_load_lds_dwordx4 v[140:141], off
	v_lshl_add_u64 v[140:141], s[44:45], 0, v[132:133]
	s_mov_b32 m0, s90
	s_nop 0
	global_load_lds_dwordx4 v[140:141], off
	v_lshl_add_u64 v[140:141], s[44:45], 0, v[128:129]
	s_mov_b32 m0, s89
	s_nop 0
	global_load_lds_dwordx4 v[140:141], off
	v_lshl_add_u64 v[140:141], v[216:217], 0, s[10:11]
	s_mov_b32 m0, s62
	s_nop 0
	global_load_lds_dwordx4 v[140:141], off
	v_lshl_add_u64 v[140:141], v[218:219], 0, s[10:11]
	s_mov_b32 m0, s63
	s_nop 0
	global_load_lds_dwordx4 v[140:141], off
	s_waitcnt vmcnt(8)
	s_waitcnt lgkmcnt(0)
	s_barrier
	s_waitcnt lgkmcnt(0)
	v_mfma_f32_16x16x32_bf16 v[60:63], v[148:151], v[180:183], v[60:63]
	v_mfma_f32_16x16x32_bf16 v[56:59], v[156:159], v[180:183], v[56:59]
	v_mfma_f32_16x16x32_bf16 v[52:55], v[148:151], v[188:191], v[52:55]
	v_mfma_f32_16x16x32_bf16 v[44:47], v[156:159], v[188:191], v[44:47]
	v_mfma_f32_16x16x32_bf16 v[36:39], v[148:151], v[196:199], v[36:39]
	v_mfma_f32_16x16x32_bf16 v[28:31], v[156:159], v[196:199], v[28:31]
	v_mfma_f32_16x16x32_bf16 v[20:23], v[148:151], v[204:207], v[20:23]
	v_mfma_f32_16x16x32_bf16 v[12:15], v[156:159], v[204:207], v[12:15]
	v_mfma_f32_16x16x32_bf16 v[60:63], v[152:155], v[184:187], v[60:63]
	v_mfma_f32_16x16x32_bf16 v[56:59], v[160:163], v[184:187], v[56:59]
	v_mfma_f32_16x16x32_bf16 v[52:55], v[152:155], v[192:195], v[52:55]
	v_mfma_f32_16x16x32_bf16 v[44:47], v[160:163], v[192:195], v[44:47]
	v_mfma_f32_16x16x32_bf16 v[36:39], v[152:155], v[200:203], v[36:39]
	v_mfma_f32_16x16x32_bf16 v[28:31], v[160:163], v[200:203], v[28:31]
	v_mfma_f32_16x16x32_bf16 v[20:23], v[152:155], v[212:215], v[20:23]
	v_mfma_f32_16x16x32_bf16 v[12:15], v[160:163], v[212:215], v[12:15]
	v_mfma_f32_16x16x32_bf16 v[48:51], v[164:167], v[180:183], v[48:51]
	v_mfma_f32_16x16x32_bf16 v[40:43], v[172:175], v[180:183], v[40:43]
	v_mfma_f32_16x16x32_bf16 v[32:35], v[164:167], v[188:191], v[32:35]
	v_mfma_f32_16x16x32_bf16 v[24:27], v[172:175], v[188:191], v[24:27]
	v_mfma_f32_16x16x32_bf16 v[16:19], v[164:167], v[196:199], v[16:19]
	v_mfma_f32_16x16x32_bf16 v[8:11], v[172:175], v[196:199], v[8:11]
	v_mfma_f32_16x16x32_bf16 v[4:7], v[164:167], v[204:207], v[4:7]
	v_mfma_f32_16x16x32_bf16 v[0:3], v[172:175], v[204:207], v[0:3]
	v_mfma_f32_16x16x32_bf16 v[48:51], v[168:171], v[184:187], v[48:51]
	v_mfma_f32_16x16x32_bf16 v[40:43], v[176:179], v[184:187], v[40:43]
	v_mfma_f32_16x16x32_bf16 v[32:35], v[168:171], v[192:195], v[32:35]
	v_mfma_f32_16x16x32_bf16 v[24:27], v[176:179], v[192:195], v[24:27]
	v_mfma_f32_16x16x32_bf16 v[16:19], v[168:171], v[200:203], v[16:19]
	v_mfma_f32_16x16x32_bf16 v[8:11], v[176:179], v[200:203], v[8:11]
	v_mfma_f32_16x16x32_bf16 v[4:7], v[168:171], v[212:215], v[4:7]
	v_mfma_f32_16x16x32_bf16 v[0:3], v[176:179], v[212:215], v[0:3]
	s_barrier
	s_movk_i32 s46, 0x100
	s_andn2_b64 vcc, exec, s[42:43]
	s_mov_b64 s[44:45], -1
	s_mov_b64 s[42:43], 0
	s_cbranch_vccz .LBB0_902
	s_and_b64 vcc, exec, s[12:13]
	s_cbranch_vccz .LBB0_905
	s_barrier
